# GEMM K-loops: 8 of 16 LDS-DMA loads per iteration use saddr form (SGPR base + 32-bit VGPR offset), dropping their 64-bit VALU adds
# speedup vs baseline: 1.0013x; 1.0013x over previous
.LBB0_132:
	v_add_u32_e32 v153, s43, v161
	ds_read_b128 v[156:159], v153
	ds_read_b128 v[164:167], v153 offset:1024
	ds_read_b128 v[168:171], v153 offset:2048
	ds_read_b128 v[172:175], v153 offset:3072
	v_add_u32_e32 v153, s44, v161
	ds_read_b128 v[176:179], v153
	ds_read_b128 v[180:183], v153 offset:1024
	ds_read_b128 v[184:187], v153 offset:2048
	ds_read_b128 v[188:191], v153 offset:3072
	s_add_u32 s34, s28, 0xfff80080
	s_addc_u32 s35, s29, -1
	s_and_b64 s[30:31], s[30:31], exec
	s_cselect_b32 s35, s23, s35
	s_cselect_b32 s34, s48, s34
	s_cselect_b32 s31, s21, s53
	s_cselect_b32 s30, s49, s51
	s_add_i32 m0, s19, 0xc000
	ds_read_b128 v[192:195], v163
	ds_read_b128 v[196:199], v163 offset:1024
	ds_read_b128 v[200:203], v163 offset:2048
	ds_read_b128 v[204:207], v163 offset:3072
	ds_read_b128 v[208:211], v163 offset:4096
	ds_read_b128 v[212:215], v163 offset:5120
	ds_read_b128 v[216:219], v163 offset:6144
	ds_read_b128 v[222:225], v163 offset:7168
	global_load_lds_dwordx4 v136, s[28:29]
	s_add_i32 m0, s19, 0xe000
	s_nop 0
	global_load_lds_dwordx4 v138, s[28:29]
	s_waitcnt vmcnt(8)
	s_waitcnt lgkmcnt(0)
	s_setprio 1
	s_waitcnt lgkmcnt(0)
	v_mfma_f32_16x16x32_bf16 v[124:127], v[156:159], v[192:195], v[124:127]
	v_mfma_f32_16x16x32_bf16 v[120:123], v[168:171], v[192:195], v[120:123]
	v_mfma_f32_16x16x32_bf16 v[124:127], v[164:167], v[196:199], v[124:127]
	v_mfma_f32_16x16x32_bf16 v[120:123], v[172:175], v[196:199], v[120:123]
	s_barrier
	v_mfma_f32_16x16x32_bf16 v[108:111], v[156:159], v[200:203], v[108:111]
	v_mfma_f32_16x16x32_bf16 v[104:107], v[168:171], v[200:203], v[104:107]
	v_mfma_f32_16x16x32_bf16 v[92:95], v[156:159], v[208:211], v[92:95]
	v_mfma_f32_16x16x32_bf16 v[88:91], v[168:171], v[208:211], v[88:91]
	v_mfma_f32_16x16x32_bf16 v[76:79], v[156:159], v[216:219], v[76:79]
	v_mfma_f32_16x16x32_bf16 v[72:75], v[168:171], v[216:219], v[72:75]
	v_mfma_f32_16x16x32_bf16 v[116:119], v[176:179], v[192:195], v[116:119]
	v_mfma_f32_16x16x32_bf16 v[112:115], v[184:187], v[192:195], v[112:115]
	v_mfma_f32_16x16x32_bf16 v[100:103], v[176:179], v[200:203], v[100:103]
	v_mfma_f32_16x16x32_bf16 v[96:99], v[184:187], v[200:203], v[96:99]
	v_mfma_f32_16x16x32_bf16 v[84:87], v[176:179], v[208:211], v[84:87]
	v_mfma_f32_16x16x32_bf16 v[80:83], v[184:187], v[208:211], v[80:83]
	v_mfma_f32_16x16x32_bf16 v[68:71], v[176:179], v[216:219], v[68:71]
	v_mfma_f32_16x16x32_bf16 v[64:67], v[184:187], v[216:219], v[64:67]
	v_mfma_f32_16x16x32_bf16 v[108:111], v[164:167], v[204:207], v[108:111]
	v_mfma_f32_16x16x32_bf16 v[104:107], v[172:175], v[204:207], v[104:107]
	v_mfma_f32_16x16x32_bf16 v[92:95], v[164:167], v[212:215], v[92:95]
	v_mfma_f32_16x16x32_bf16 v[88:91], v[172:175], v[212:215], v[88:91]
	v_mfma_f32_16x16x32_bf16 v[76:79], v[164:167], v[222:225], v[76:79]
	v_mfma_f32_16x16x32_bf16 v[72:75], v[172:175], v[222:225], v[72:75]
	v_mfma_f32_16x16x32_bf16 v[116:119], v[180:183], v[196:199], v[116:119]
	v_mfma_f32_16x16x32_bf16 v[112:115], v[188:191], v[196:199], v[112:115]
	v_mfma_f32_16x16x32_bf16 v[100:103], v[180:183], v[204:207], v[100:103]
	v_mfma_f32_16x16x32_bf16 v[96:99], v[188:191], v[204:207], v[96:99]
	v_mfma_f32_16x16x32_bf16 v[84:87], v[180:183], v[212:215], v[84:87]
	v_mfma_f32_16x16x32_bf16 v[80:83], v[188:191], v[212:215], v[80:83]
	v_mfma_f32_16x16x32_bf16 v[68:71], v[180:183], v[222:225], v[68:71]
	v_mfma_f32_16x16x32_bf16 v[64:67], v[188:191], v[222:225], v[64:67]
	s_setprio 0
	s_barrier
	s_add_i32 s56, s43, s2
	v_lshl_add_u64 v[226:227], s[30:31], 0, v[132:133]
	s_mov_b32 m0, s56
	ds_read_b128 v[192:195], v163 offset:16384
	ds_read_b128 v[196:199], v163 offset:17408
	ds_read_b128 v[200:203], v163 offset:18432
	ds_read_b128 v[204:207], v163 offset:19456
	ds_read_b128 v[208:211], v163 offset:20480
	ds_read_b128 v[212:215], v163 offset:21504
	ds_read_b128 v[216:219], v163 offset:22528
	ds_read_b128 v[222:225], v163 offset:23552
	global_load_lds_dwordx4 v[226:227], off
	s_add_i32 m0, s56, 0x2000
	s_add_u32 s56, s30, 0x80000
	v_lshl_add_u64 v[228:229], s[30:31], 0, v[128:129]
	s_addc_u32 s57, s31, 0
	s_add_i32 s58, s44, s2
	global_load_lds_dwordx4 v[228:229], off
	s_mov_b32 m0, s58
	v_lshl_add_u64 v[232:233], s[34:35], 0, v[130:131]
	global_load_lds_dwordx4 v132, s[56:57]
	s_add_i32 m0, s58, 0x2000
	s_nop 0
	global_load_lds_dwordx4 v128, s[56:57]
	v_lshl_add_u64 v[230:231], s[34:35], 0, v[134:135]
	s_mov_b32 m0, s19
	s_nop 0
	global_load_lds_dwordx4 v[230:231], off
	s_mov_b32 m0, s33
	s_nop 0
	global_load_lds_dwordx4 v[232:233], off
	s_waitcnt vmcnt(8)
	s_waitcnt lgkmcnt(0)
	s_setprio 1
	s_waitcnt lgkmcnt(0)
	v_mfma_f32_16x16x32_bf16 v[60:63], v[156:159], v[192:195], v[60:63]
	v_mfma_f32_16x16x32_bf16 v[56:59], v[168:171], v[192:195], v[56:59]
	v_mfma_f32_16x16x32_bf16 v[60:63], v[164:167], v[196:199], v[60:63]
	v_mfma_f32_16x16x32_bf16 v[56:59], v[172:175], v[196:199], v[56:59]
	s_barrier
	v_mfma_f32_16x16x32_bf16 v[44:47], v[156:159], v[200:203], v[44:47]
	v_mfma_f32_16x16x32_bf16 v[40:43], v[168:171], v[200:203], v[40:43]
	v_mfma_f32_16x16x32_bf16 v[28:31], v[156:159], v[208:211], v[28:31]
	v_mfma_f32_16x16x32_bf16 v[24:27], v[168:171], v[208:211], v[24:27]
	v_mfma_f32_16x16x32_bf16 v[12:15], v[156:159], v[216:219], v[12:15]
	v_mfma_f32_16x16x32_bf16 v[8:11], v[168:171], v[216:219], v[8:11]
	v_mfma_f32_16x16x32_bf16 v[52:55], v[176:179], v[192:195], v[52:55]
	v_mfma_f32_16x16x32_bf16 v[48:51], v[184:187], v[192:195], v[48:51]
	v_mfma_f32_16x16x32_bf16 v[36:39], v[176:179], v[200:203], v[36:39]
	v_mfma_f32_16x16x32_bf16 v[32:35], v[184:187], v[200:203], v[32:35]
	v_mfma_f32_16x16x32_bf16 v[20:23], v[176:179], v[208:211], v[20:23]
	v_mfma_f32_16x16x32_bf16 v[16:19], v[184:187], v[208:211], v[16:19]
	v_mfma_f32_16x16x32_bf16 v[4:7], v[176:179], v[216:219], v[4:7]
	v_mfma_f32_16x16x32_bf16 v[0:3], v[184:187], v[216:219], v[0:3]
	v_mfma_f32_16x16x32_bf16 v[44:47], v[164:167], v[204:207], v[44:47]
	v_mfma_f32_16x16x32_bf16 v[40:43], v[172:175], v[204:207], v[40:43]
	v_mfma_f32_16x16x32_bf16 v[28:31], v[164:167], v[212:215], v[28:31]
	v_mfma_f32_16x16x32_bf16 v[24:27], v[172:175], v[212:215], v[24:27]
	v_mfma_f32_16x16x32_bf16 v[12:15], v[164:167], v[222:225], v[12:15]
	v_mfma_f32_16x16x32_bf16 v[8:11], v[172:175], v[222:225], v[8:11]
	v_mfma_f32_16x16x32_bf16 v[52:55], v[180:183], v[196:199], v[52:55]
	v_mfma_f32_16x16x32_bf16 v[48:51], v[188:191], v[196:199], v[48:51]
	v_mfma_f32_16x16x32_bf16 v[36:39], v[180:183], v[204:207], v[36:39]
	v_mfma_f32_16x16x32_bf16 v[32:35], v[188:191], v[204:207], v[32:35]
	v_mfma_f32_16x16x32_bf16 v[20:23], v[180:183], v[212:215], v[20:23]
	v_mfma_f32_16x16x32_bf16 v[16:19], v[188:191], v[212:215], v[16:19]
	v_mfma_f32_16x16x32_bf16 v[4:7], v[180:183], v[222:225], v[4:7]
	v_mfma_f32_16x16x32_bf16 v[0:3], v[188:191], v[222:225], v[0:3]
	s_setprio 0
	s_barrier
	s_add_i32 s56, 0, 0x18000
	v_add_u32_e32 v153, s56, v161
	s_add_i32 s57, 0, 0x1c000
	ds_read_b128 v[156:159], v153
	ds_read_b128 v[164:167], v153 offset:1024
	ds_read_b128 v[168:171], v153 offset:2048
	ds_read_b128 v[172:175], v153 offset:3072
	v_add_u32_e32 v153, s57, v161
	ds_read_b128 v[176:179], v153
	ds_read_b128 v[180:183], v153 offset:1024
	ds_read_b128 v[184:187], v153 offset:2048
	ds_read_b128 v[188:191], v153 offset:3072
	s_add_u32 s34, s34, 0x80000
	s_addc_u32 s35, s35, 0
	s_mov_b32 m0, s36
	ds_read_b128 v[192:195], v163 offset:32768
	ds_read_b128 v[196:199], v163 offset:33792
	ds_read_b128 v[200:203], v163 offset:34816
	ds_read_b128 v[204:207], v163 offset:35840
	ds_read_b128 v[208:211], v163 offset:36864
	ds_read_b128 v[212:215], v163 offset:37888
	ds_read_b128 v[216:219], v163 offset:38912
	ds_read_b128 v[222:225], v163 offset:39936
	global_load_lds_dwordx4 v134, s[34:35]
	s_mov_b32 m0, s37
	s_nop 0
	global_load_lds_dwordx4 v130, s[34:35]
	s_waitcnt vmcnt(8)
	s_waitcnt lgkmcnt(0)
	s_setprio 1
	s_waitcnt lgkmcnt(0)
	v_mfma_f32_16x16x32_bf16 v[124:127], v[156:159], v[192:195], v[124:127]
	v_mfma_f32_16x16x32_bf16 v[120:123], v[168:171], v[192:195], v[120:123]
	v_mfma_f32_16x16x32_bf16 v[124:127], v[164:167], v[196:199], v[124:127]
	v_mfma_f32_16x16x32_bf16 v[120:123], v[172:175], v[196:199], v[120:123]
	s_barrier
	v_mfma_f32_16x16x32_bf16 v[108:111], v[156:159], v[200:203], v[108:111]
	v_mfma_f32_16x16x32_bf16 v[104:107], v[168:171], v[200:203], v[104:107]
	v_mfma_f32_16x16x32_bf16 v[92:95], v[156:159], v[208:211], v[92:95]
	v_mfma_f32_16x16x32_bf16 v[88:91], v[168:171], v[208:211], v[88:91]
	v_mfma_f32_16x16x32_bf16 v[76:79], v[156:159], v[216:219], v[76:79]
	v_mfma_f32_16x16x32_bf16 v[72:75], v[168:171], v[216:219], v[72:75]
	v_mfma_f32_16x16x32_bf16 v[116:119], v[176:179], v[192:195], v[116:119]
	v_mfma_f32_16x16x32_bf16 v[112:115], v[184:187], v[192:195], v[112:115]
	v_mfma_f32_16x16x32_bf16 v[100:103], v[176:179], v[200:203], v[100:103]
	v_mfma_f32_16x16x32_bf16 v[96:99], v[184:187], v[200:203], v[96:99]
	v_mfma_f32_16x16x32_bf16 v[84:87], v[176:179], v[208:211], v[84:87]
	v_mfma_f32_16x16x32_bf16 v[80:83], v[184:187], v[208:211], v[80:83]
	v_mfma_f32_16x16x32_bf16 v[68:71], v[176:179], v[216:219], v[68:71]
	v_mfma_f32_16x16x32_bf16 v[64:67], v[184:187], v[216:219], v[64:67]
	v_mfma_f32_16x16x32_bf16 v[108:111], v[164:167], v[204:207], v[108:111]
	v_mfma_f32_16x16x32_bf16 v[104:107], v[172:175], v[204:207], v[104:107]
	v_mfma_f32_16x16x32_bf16 v[92:95], v[164:167], v[212:215], v[92:95]
	v_mfma_f32_16x16x32_bf16 v[88:91], v[172:175], v[212:215], v[88:91]
	v_mfma_f32_16x16x32_bf16 v[76:79], v[164:167], v[222:225], v[76:79]
	v_mfma_f32_16x16x32_bf16 v[72:75], v[172:175], v[222:225], v[72:75]
	v_mfma_f32_16x16x32_bf16 v[116:119], v[180:183], v[196:199], v[116:119]
	v_mfma_f32_16x16x32_bf16 v[112:115], v[188:191], v[196:199], v[112:115]
	v_mfma_f32_16x16x32_bf16 v[100:103], v[180:183], v[204:207], v[100:103]
	v_mfma_f32_16x16x32_bf16 v[96:99], v[188:191], v[204:207], v[96:99]
	v_mfma_f32_16x16x32_bf16 v[84:87], v[180:183], v[212:215], v[84:87]
	v_mfma_f32_16x16x32_bf16 v[80:83], v[188:191], v[212:215], v[80:83]
	v_mfma_f32_16x16x32_bf16 v[68:71], v[180:183], v[222:225], v[68:71]
	v_mfma_f32_16x16x32_bf16 v[64:67], v[188:191], v[222:225], v[64:67]
	s_setprio 0
	s_barrier
	s_add_i32 s34, s56, s2
	v_lshl_add_u64 v[226:227], v[226:227], 0, s[8:9]
	s_mov_b32 m0, s34
	ds_read_b128 v[192:195], v163 offset:49152
	ds_read_b128 v[196:199], v163 offset:50176
	ds_read_b128 v[200:203], v163 offset:51200
	ds_read_b128 v[204:207], v163 offset:52224
	ds_read_b128 v[208:211], v163 offset:53248
	ds_read_b128 v[212:215], v163 offset:54272
	ds_read_b128 v[216:219], v163 offset:55296
	ds_read_b128 v[222:225], v163 offset:56320
	global_load_lds_dwordx4 v[226:227], off
	s_add_i32 m0, s34, 0x2000
	s_add_u32 s30, s30, 0x80080
	v_lshl_add_u64 v[226:227], v[228:229], 0, s[8:9]
	s_addc_u32 s31, s31, 0
	s_add_i32 s34, s57, s2
	global_load_lds_dwordx4 v[226:227], off
	s_mov_b32 m0, s34
	s_nop 0
	global_load_lds_dwordx4 v132, s[30:31]
	s_add_i32 m0, s34, 0x2000
	s_nop 0
	global_load_lds_dwordx4 v128, s[30:31]
	v_lshl_add_u64 v[226:227], v[230:231], 0, s[8:9]
	s_mov_b32 m0, s39
	s_nop 0
	global_load_lds_dwordx4 v[226:227], off
	v_lshl_add_u64 v[226:227], v[232:233], 0, s[8:9]
	s_mov_b32 m0, s40
	s_nop 0
	global_load_lds_dwordx4 v[226:227], off
	s_waitcnt vmcnt(8)
	s_waitcnt lgkmcnt(0)
	s_setprio 1
	s_waitcnt lgkmcnt(0)
	v_mfma_f32_16x16x32_bf16 v[60:63], v[156:159], v[192:195], v[60:63]
	v_mfma_f32_16x16x32_bf16 v[56:59], v[168:171], v[192:195], v[56:59]
	v_mfma_f32_16x16x32_bf16 v[60:63], v[164:167], v[196:199], v[60:63]
	v_mfma_f32_16x16x32_bf16 v[56:59], v[172:175], v[196:199], v[56:59]
	s_barrier
	v_mfma_f32_16x16x32_bf16 v[44:47], v[156:159], v[200:203], v[44:47]
	v_mfma_f32_16x16x32_bf16 v[40:43], v[168:171], v[200:203], v[40:43]
	v_mfma_f32_16x16x32_bf16 v[28:31], v[156:159], v[208:211], v[28:31]
	v_mfma_f32_16x16x32_bf16 v[24:27], v[168:171], v[208:211], v[24:27]
	v_mfma_f32_16x16x32_bf16 v[12:15], v[156:159], v[216:219], v[12:15]
	v_mfma_f32_16x16x32_bf16 v[8:11], v[168:171], v[216:219], v[8:11]
	v_mfma_f32_16x16x32_bf16 v[52:55], v[176:179], v[192:195], v[52:55]
	v_mfma_f32_16x16x32_bf16 v[48:51], v[184:187], v[192:195], v[48:51]
	v_mfma_f32_16x16x32_bf16 v[36:39], v[176:179], v[200:203], v[36:39]
	v_mfma_f32_16x16x32_bf16 v[32:35], v[184:187], v[200:203], v[32:35]
	v_mfma_f32_16x16x32_bf16 v[20:23], v[176:179], v[208:211], v[20:23]
	v_mfma_f32_16x16x32_bf16 v[16:19], v[184:187], v[208:211], v[16:19]
	v_mfma_f32_16x16x32_bf16 v[4:7], v[176:179], v[216:219], v[4:7]
	v_mfma_f32_16x16x32_bf16 v[0:3], v[184:187], v[216:219], v[0:3]
	v_mfma_f32_16x16x32_bf16 v[44:47], v[164:167], v[204:207], v[44:47]
	v_mfma_f32_16x16x32_bf16 v[40:43], v[172:175], v[204:207], v[40:43]
	v_mfma_f32_16x16x32_bf16 v[28:31], v[164:167], v[212:215], v[28:31]
	v_mfma_f32_16x16x32_bf16 v[24:27], v[172:175], v[212:215], v[24:27]
	v_mfma_f32_16x16x32_bf16 v[12:15], v[164:167], v[222:225], v[12:15]
	v_mfma_f32_16x16x32_bf16 v[8:11], v[172:175], v[222:225], v[8:11]
	v_mfma_f32_16x16x32_bf16 v[52:55], v[180:183], v[196:199], v[52:55]
	v_mfma_f32_16x16x32_bf16 v[48:51], v[188:191], v[196:199], v[48:51]
	v_mfma_f32_16x16x32_bf16 v[36:39], v[180:183], v[204:207], v[36:39]
	v_mfma_f32_16x16x32_bf16 v[32:35], v[188:191], v[204:207], v[32:35]
	v_mfma_f32_16x16x32_bf16 v[20:23], v[180:183], v[212:215], v[20:23]
	v_mfma_f32_16x16x32_bf16 v[16:19], v[188:191], v[212:215], v[16:19]
	v_mfma_f32_16x16x32_bf16 v[4:7], v[180:183], v[222:225], v[4:7]
	v_mfma_f32_16x16x32_bf16 v[0:3], v[188:191], v[222:225], v[0:3]
	s_setprio 0
	s_barrier
	s_add_i32 s55, s55, 2
	s_add_u32 s28, s28, 0x100
	s_addc_u32 s29, s29, 0
	s_add_u32 s51, s51, 0x100
	s_addc_u32 s53, s53, 0
	s_cmp_gt_u32 s55, 29
	s_cbranch_scc1 .LBB0_135

.LBB0_237:
	ds_read_b128 v[144:147], v151
	ds_read_b128 v[156:159], v151 offset:1024
	ds_read_b128 v[160:163], v151 offset:2048
	ds_read_b128 v[164:167], v151 offset:3072
	ds_read_b128 v[168:171], v152
	ds_read_b128 v[172:175], v152 offset:1024
	ds_read_b128 v[176:179], v152 offset:2048
	ds_read_b128 v[180:183], v152 offset:3072
	s_add_u32 s24, s22, 0x100
	s_addc_u32 s25, s23, 0
	s_cmpk_eq_i32 s51, 0x54
	s_cselect_b32 s29, s1, s25
	s_cselect_b32 s28, s0, s24
	s_cselect_b32 s27, s21, s49
	s_cselect_b32 s26, s20, s48
	v_lshl_add_u64 v[216:217], s[22:23], 0, v[136:137]
	s_add_i32 m0, s31, 0xc000
	ds_read_b128 v[184:187], v153
	ds_read_b128 v[188:191], v153 offset:1024
	ds_read_b128 v[192:195], v153 offset:2048
	ds_read_b128 v[196:199], v153 offset:3072
	ds_read_b128 v[200:203], v153 offset:4096
	ds_read_b128 v[204:207], v153 offset:5120
	ds_read_b128 v[208:211], v153 offset:6144
	ds_read_b128 v[212:215], v153 offset:7168
	global_load_lds_dwordx4 v[216:217], off
	v_lshl_add_u64 v[216:217], s[22:23], 0, v[138:139]
	s_add_i32 m0, s31, 0xe000
	s_nop 0
	global_load_lds_dwordx4 v[216:217], off
	s_waitcnt vmcnt(8)
	s_waitcnt lgkmcnt(0)
	s_setprio 1
	s_waitcnt lgkmcnt(0)
	v_mfma_f32_16x16x32_bf16 v[124:127], v[144:147], v[184:187], v[124:127]
	v_mfma_f32_16x16x32_bf16 v[120:123], v[160:163], v[184:187], v[120:123]
	v_mfma_f32_16x16x32_bf16 v[124:127], v[156:159], v[188:191], v[124:127]
	v_mfma_f32_16x16x32_bf16 v[120:123], v[164:167], v[188:191], v[120:123]
	s_barrier
	v_mfma_f32_16x16x32_bf16 v[108:111], v[144:147], v[192:195], v[108:111]
	v_mfma_f32_16x16x32_bf16 v[104:107], v[160:163], v[192:195], v[104:107]
	v_mfma_f32_16x16x32_bf16 v[92:95], v[144:147], v[200:203], v[92:95]
	v_mfma_f32_16x16x32_bf16 v[88:91], v[160:163], v[200:203], v[88:91]
	v_mfma_f32_16x16x32_bf16 v[76:79], v[144:147], v[208:211], v[76:79]
	v_mfma_f32_16x16x32_bf16 v[72:75], v[160:163], v[208:211], v[72:75]
	v_mfma_f32_16x16x32_bf16 v[116:119], v[168:171], v[184:187], v[116:119]
	v_mfma_f32_16x16x32_bf16 v[112:115], v[176:179], v[184:187], v[112:115]
	v_mfma_f32_16x16x32_bf16 v[100:103], v[168:171], v[192:195], v[100:103]
	v_mfma_f32_16x16x32_bf16 v[96:99], v[176:179], v[192:195], v[96:99]
	v_mfma_f32_16x16x32_bf16 v[84:87], v[168:171], v[200:203], v[84:87]
	v_mfma_f32_16x16x32_bf16 v[80:83], v[176:179], v[200:203], v[80:83]
	v_mfma_f32_16x16x32_bf16 v[68:71], v[168:171], v[208:211], v[68:71]
	v_mfma_f32_16x16x32_bf16 v[64:67], v[176:179], v[208:211], v[64:67]
	v_mfma_f32_16x16x32_bf16 v[108:111], v[156:159], v[196:199], v[108:111]
	v_mfma_f32_16x16x32_bf16 v[104:107], v[164:167], v[196:199], v[104:107]
	v_mfma_f32_16x16x32_bf16 v[92:95], v[156:159], v[204:207], v[92:95]
	v_mfma_f32_16x16x32_bf16 v[88:91], v[164:167], v[204:207], v[88:91]
	v_mfma_f32_16x16x32_bf16 v[76:79], v[156:159], v[212:215], v[76:79]
	v_mfma_f32_16x16x32_bf16 v[72:75], v[164:167], v[212:215], v[72:75]
	v_mfma_f32_16x16x32_bf16 v[116:119], v[172:175], v[188:191], v[116:119]
	v_mfma_f32_16x16x32_bf16 v[112:115], v[180:183], v[188:191], v[112:115]
	v_mfma_f32_16x16x32_bf16 v[100:103], v[172:175], v[196:199], v[100:103]
	v_mfma_f32_16x16x32_bf16 v[96:99], v[180:183], v[196:199], v[96:99]
	v_mfma_f32_16x16x32_bf16 v[84:87], v[172:175], v[204:207], v[84:87]
	v_mfma_f32_16x16x32_bf16 v[80:83], v[180:183], v[204:207], v[80:83]
	v_mfma_f32_16x16x32_bf16 v[68:71], v[172:175], v[212:215], v[68:71]
	v_mfma_f32_16x16x32_bf16 v[64:67], v[180:183], v[212:215], v[64:67]
	s_setprio 0
	s_barrier
	s_add_i32 s22, s42, s30
	v_lshl_add_u64 v[216:217], s[26:27], 0, v[130:131]
	s_mov_b32 m0, s22
	ds_read_b128 v[184:187], v153 offset:16384
	ds_read_b128 v[188:191], v153 offset:17408
	ds_read_b128 v[192:195], v153 offset:18432
	ds_read_b128 v[196:199], v153 offset:19456
	ds_read_b128 v[200:203], v153 offset:20480
	ds_read_b128 v[204:207], v153 offset:21504
	ds_read_b128 v[208:211], v153 offset:22528
	ds_read_b128 v[212:215], v153 offset:23552
	global_load_lds_dwordx4 v[216:217], off
	s_add_i32 m0, s22, 0x2000
	s_add_u32 s22, s26, 0x160000
	v_lshl_add_u64 v[218:219], s[26:27], 0, v[134:135]
	s_addc_u32 s23, s27, 0
	s_add_i32 s53, s43, s30
	global_load_lds_dwordx4 v[218:219], off
	s_mov_b32 m0, s53
	v_lshl_add_u64 v[224:225], s[28:29], 0, v[132:133]
	global_load_lds_dwordx4 v130, s[22:23]
	s_add_i32 m0, s53, 0x2000
	s_nop 0
	global_load_lds_dwordx4 v134, s[22:23]
	v_lshl_add_u64 v[222:223], s[28:29], 0, v[128:129]
	s_mov_b32 m0, s31
	s_nop 0
	global_load_lds_dwordx4 v[222:223], off
	s_mov_b32 m0, s33
	s_nop 0
	global_load_lds_dwordx4 v[224:225], off
	s_waitcnt vmcnt(8)
	s_waitcnt lgkmcnt(0)
	s_setprio 1
	s_waitcnt lgkmcnt(0)
	v_mfma_f32_16x16x32_bf16 v[60:63], v[144:147], v[184:187], v[60:63]
	v_mfma_f32_16x16x32_bf16 v[56:59], v[160:163], v[184:187], v[56:59]
	v_mfma_f32_16x16x32_bf16 v[60:63], v[156:159], v[188:191], v[60:63]
	v_mfma_f32_16x16x32_bf16 v[56:59], v[164:167], v[188:191], v[56:59]
	s_barrier
	v_mfma_f32_16x16x32_bf16 v[44:47], v[144:147], v[192:195], v[44:47]
	v_mfma_f32_16x16x32_bf16 v[40:43], v[160:163], v[192:195], v[40:43]
	v_mfma_f32_16x16x32_bf16 v[28:31], v[144:147], v[200:203], v[28:31]
	v_mfma_f32_16x16x32_bf16 v[24:27], v[160:163], v[200:203], v[24:27]
	v_mfma_f32_16x16x32_bf16 v[12:15], v[144:147], v[208:211], v[12:15]
	v_mfma_f32_16x16x32_bf16 v[8:11], v[160:163], v[208:211], v[8:11]
	v_mfma_f32_16x16x32_bf16 v[52:55], v[168:171], v[184:187], v[52:55]
	v_mfma_f32_16x16x32_bf16 v[48:51], v[176:179], v[184:187], v[48:51]
	v_mfma_f32_16x16x32_bf16 v[36:39], v[168:171], v[192:195], v[36:39]
	v_mfma_f32_16x16x32_bf16 v[32:35], v[176:179], v[192:195], v[32:35]
	v_mfma_f32_16x16x32_bf16 v[20:23], v[168:171], v[200:203], v[20:23]
	v_mfma_f32_16x16x32_bf16 v[16:19], v[176:179], v[200:203], v[16:19]
	v_mfma_f32_16x16x32_bf16 v[4:7], v[168:171], v[208:211], v[4:7]
	v_mfma_f32_16x16x32_bf16 v[0:3], v[176:179], v[208:211], v[0:3]
	v_mfma_f32_16x16x32_bf16 v[44:47], v[156:159], v[196:199], v[44:47]
	v_mfma_f32_16x16x32_bf16 v[40:43], v[164:167], v[196:199], v[40:43]
	v_mfma_f32_16x16x32_bf16 v[28:31], v[156:159], v[204:207], v[28:31]
	v_mfma_f32_16x16x32_bf16 v[24:27], v[164:167], v[204:207], v[24:27]
	v_mfma_f32_16x16x32_bf16 v[12:15], v[156:159], v[212:215], v[12:15]
	v_mfma_f32_16x16x32_bf16 v[8:11], v[164:167], v[212:215], v[8:11]
	v_mfma_f32_16x16x32_bf16 v[52:55], v[172:175], v[188:191], v[52:55]
	v_mfma_f32_16x16x32_bf16 v[48:51], v[180:183], v[188:191], v[48:51]
	v_mfma_f32_16x16x32_bf16 v[36:39], v[172:175], v[196:199], v[36:39]
	v_mfma_f32_16x16x32_bf16 v[32:35], v[180:183], v[196:199], v[32:35]
	v_mfma_f32_16x16x32_bf16 v[20:23], v[172:175], v[204:207], v[20:23]
	v_mfma_f32_16x16x32_bf16 v[16:19], v[180:183], v[204:207], v[16:19]
	v_mfma_f32_16x16x32_bf16 v[4:7], v[172:175], v[212:215], v[4:7]
	v_mfma_f32_16x16x32_bf16 v[0:3], v[180:183], v[212:215], v[0:3]
	s_setprio 0
	s_barrier
	s_add_i32 s53, 0, 0x18000
	v_add_u32_e32 v155, s53, v149
	s_add_i32 s55, 0, 0x1c000
	ds_read_b128 v[144:147], v155
	ds_read_b128 v[156:159], v155 offset:1024
	ds_read_b128 v[160:163], v155 offset:2048
	ds_read_b128 v[164:167], v155 offset:3072
	v_add_u32_e32 v155, s55, v149
	ds_read_b128 v[168:171], v155
	ds_read_b128 v[172:175], v155 offset:1024
	ds_read_b128 v[176:179], v155 offset:2048
	ds_read_b128 v[180:183], v155 offset:3072
	s_add_u32 s22, s28, 0x160000
	s_addc_u32 s23, s29, 0
	s_mov_b32 m0, s34
	ds_read_b128 v[184:187], v153 offset:32768
	ds_read_b128 v[188:191], v153 offset:33792
	ds_read_b128 v[192:195], v153 offset:34816
	ds_read_b128 v[196:199], v153 offset:35840
	ds_read_b128 v[200:203], v153 offset:36864
	ds_read_b128 v[204:207], v153 offset:37888
	ds_read_b128 v[208:211], v153 offset:38912
	ds_read_b128 v[212:215], v153 offset:39936
	global_load_lds_dwordx4 v128, s[22:23]
	s_mov_b32 m0, s35
	s_nop 0
	global_load_lds_dwordx4 v132, s[22:23]
	s_waitcnt vmcnt(8)
	s_waitcnt lgkmcnt(0)
	s_setprio 1
	s_waitcnt lgkmcnt(0)
	v_mfma_f32_16x16x32_bf16 v[124:127], v[144:147], v[184:187], v[124:127]
	v_mfma_f32_16x16x32_bf16 v[120:123], v[160:163], v[184:187], v[120:123]
	v_mfma_f32_16x16x32_bf16 v[124:127], v[156:159], v[188:191], v[124:127]
	v_mfma_f32_16x16x32_bf16 v[120:123], v[164:167], v[188:191], v[120:123]
	s_barrier
	v_mfma_f32_16x16x32_bf16 v[108:111], v[144:147], v[192:195], v[108:111]
	v_mfma_f32_16x16x32_bf16 v[104:107], v[160:163], v[192:195], v[104:107]
	v_mfma_f32_16x16x32_bf16 v[92:95], v[144:147], v[200:203], v[92:95]
	v_mfma_f32_16x16x32_bf16 v[88:91], v[160:163], v[200:203], v[88:91]
	v_mfma_f32_16x16x32_bf16 v[76:79], v[144:147], v[208:211], v[76:79]
	v_mfma_f32_16x16x32_bf16 v[72:75], v[160:163], v[208:211], v[72:75]
	v_mfma_f32_16x16x32_bf16 v[116:119], v[168:171], v[184:187], v[116:119]
	v_mfma_f32_16x16x32_bf16 v[112:115], v[176:179], v[184:187], v[112:115]
	v_mfma_f32_16x16x32_bf16 v[100:103], v[168:171], v[192:195], v[100:103]
	v_mfma_f32_16x16x32_bf16 v[96:99], v[176:179], v[192:195], v[96:99]
	v_mfma_f32_16x16x32_bf16 v[84:87], v[168:171], v[200:203], v[84:87]
	v_mfma_f32_16x16x32_bf16 v[80:83], v[176:179], v[200:203], v[80:83]
	v_mfma_f32_16x16x32_bf16 v[68:71], v[168:171], v[208:211], v[68:71]
	v_mfma_f32_16x16x32_bf16 v[64:67], v[176:179], v[208:211], v[64:67]
	v_mfma_f32_16x16x32_bf16 v[108:111], v[156:159], v[196:199], v[108:111]
	v_mfma_f32_16x16x32_bf16 v[104:107], v[164:167], v[196:199], v[104:107]
	v_mfma_f32_16x16x32_bf16 v[92:95], v[156:159], v[204:207], v[92:95]
	v_mfma_f32_16x16x32_bf16 v[88:91], v[164:167], v[204:207], v[88:91]
	v_mfma_f32_16x16x32_bf16 v[76:79], v[156:159], v[212:215], v[76:79]
	v_mfma_f32_16x16x32_bf16 v[72:75], v[164:167], v[212:215], v[72:75]
	v_mfma_f32_16x16x32_bf16 v[116:119], v[172:175], v[188:191], v[116:119]
	v_mfma_f32_16x16x32_bf16 v[112:115], v[180:183], v[188:191], v[112:115]
	v_mfma_f32_16x16x32_bf16 v[100:103], v[172:175], v[196:199], v[100:103]
	v_mfma_f32_16x16x32_bf16 v[96:99], v[180:183], v[196:199], v[96:99]
	v_mfma_f32_16x16x32_bf16 v[84:87], v[172:175], v[204:207], v[84:87]
	v_mfma_f32_16x16x32_bf16 v[80:83], v[180:183], v[204:207], v[80:83]
	v_mfma_f32_16x16x32_bf16 v[68:71], v[172:175], v[212:215], v[68:71]
	v_mfma_f32_16x16x32_bf16 v[64:67], v[180:183], v[212:215], v[64:67]
	s_setprio 0
	s_barrier
	s_add_i32 s22, s53, s30
	v_lshl_add_u64 v[216:217], v[216:217], 0, s[12:13]
	s_mov_b32 m0, s22
	ds_read_b128 v[184:187], v153 offset:49152
	ds_read_b128 v[188:191], v153 offset:50176
	ds_read_b128 v[192:195], v153 offset:51200
	ds_read_b128 v[196:199], v153 offset:52224
	ds_read_b128 v[200:203], v153 offset:53248
	ds_read_b128 v[204:207], v153 offset:54272
	ds_read_b128 v[208:211], v153 offset:55296
	ds_read_b128 v[212:215], v153 offset:56320
	global_load_lds_dwordx4 v[216:217], off
	s_add_i32 m0, s22, 0x2000
	s_add_u32 s22, s26, 0x160080
	v_lshl_add_u64 v[216:217], v[218:219], 0, s[12:13]
	s_addc_u32 s23, s27, 0
	s_add_i32 s26, s55, s30
	global_load_lds_dwordx4 v[216:217], off
	s_mov_b32 m0, s26
	s_nop 0
	global_load_lds_dwordx4 v130, s[22:23]
	s_add_i32 m0, s26, 0x2000
	s_nop 0
	global_load_lds_dwordx4 v134, s[22:23]
	v_lshl_add_u64 v[216:217], v[222:223], 0, s[12:13]
	s_mov_b32 m0, s37
	s_nop 0
	global_load_lds_dwordx4 v[216:217], off
	v_lshl_add_u64 v[216:217], v[224:225], 0, s[12:13]
	s_mov_b32 m0, s38
	s_nop 0
	global_load_lds_dwordx4 v[216:217], off
	s_waitcnt vmcnt(8)
	s_waitcnt lgkmcnt(0)
	s_setprio 1
	s_waitcnt lgkmcnt(0)
	v_mfma_f32_16x16x32_bf16 v[60:63], v[144:147], v[184:187], v[60:63]
	v_mfma_f32_16x16x32_bf16 v[56:59], v[160:163], v[184:187], v[56:59]
	v_mfma_f32_16x16x32_bf16 v[60:63], v[156:159], v[188:191], v[60:63]
	v_mfma_f32_16x16x32_bf16 v[56:59], v[164:167], v[188:191], v[56:59]
	s_barrier
	v_mfma_f32_16x16x32_bf16 v[44:47], v[144:147], v[192:195], v[44:47]
	v_mfma_f32_16x16x32_bf16 v[40:43], v[160:163], v[192:195], v[40:43]
	v_mfma_f32_16x16x32_bf16 v[28:31], v[144:147], v[200:203], v[28:31]
	v_mfma_f32_16x16x32_bf16 v[24:27], v[160:163], v[200:203], v[24:27]
	v_mfma_f32_16x16x32_bf16 v[12:15], v[144:147], v[208:211], v[12:15]
	v_mfma_f32_16x16x32_bf16 v[8:11], v[160:163], v[208:211], v[8:11]
	v_mfma_f32_16x16x32_bf16 v[52:55], v[168:171], v[184:187], v[52:55]
	v_mfma_f32_16x16x32_bf16 v[48:51], v[176:179], v[184:187], v[48:51]
	v_mfma_f32_16x16x32_bf16 v[36:39], v[168:171], v[192:195], v[36:39]
	v_mfma_f32_16x16x32_bf16 v[32:35], v[176:179], v[192:195], v[32:35]
	v_mfma_f32_16x16x32_bf16 v[20:23], v[168:171], v[200:203], v[20:23]
	v_mfma_f32_16x16x32_bf16 v[16:19], v[176:179], v[200:203], v[16:19]
	v_mfma_f32_16x16x32_bf16 v[4:7], v[168:171], v[208:211], v[4:7]
	v_mfma_f32_16x16x32_bf16 v[0:3], v[176:179], v[208:211], v[0:3]
	v_mfma_f32_16x16x32_bf16 v[44:47], v[156:159], v[196:199], v[44:47]
	v_mfma_f32_16x16x32_bf16 v[40:43], v[164:167], v[196:199], v[40:43]
	v_mfma_f32_16x16x32_bf16 v[28:31], v[156:159], v[204:207], v[28:31]
	v_mfma_f32_16x16x32_bf16 v[24:27], v[164:167], v[204:207], v[24:27]
	v_mfma_f32_16x16x32_bf16 v[12:15], v[156:159], v[212:215], v[12:15]
	v_mfma_f32_16x16x32_bf16 v[8:11], v[164:167], v[212:215], v[8:11]
	v_mfma_f32_16x16x32_bf16 v[52:55], v[172:175], v[188:191], v[52:55]
	v_mfma_f32_16x16x32_bf16 v[48:51], v[180:183], v[188:191], v[48:51]
	v_mfma_f32_16x16x32_bf16 v[36:39], v[172:175], v[196:199], v[36:39]
	v_mfma_f32_16x16x32_bf16 v[32:35], v[180:183], v[196:199], v[32:35]
	v_mfma_f32_16x16x32_bf16 v[20:23], v[172:175], v[204:207], v[20:23]
	v_mfma_f32_16x16x32_bf16 v[16:19], v[180:183], v[204:207], v[16:19]
	v_mfma_f32_16x16x32_bf16 v[4:7], v[172:175], v[212:215], v[4:7]
	v_mfma_f32_16x16x32_bf16 v[0:3], v[180:183], v[212:215], v[0:3]
	s_setprio 0
	s_barrier
	s_add_i32 s51, s51, 2
	s_add_u32 s48, s48, 0x100
	s_addc_u32 s49, s49, 0
	s_cmpk_gt_u32 s51, 0x55
	s_mov_b64 s[22:23], s[24:25]
	s_cbranch_scc0 .LBB0_237
	s_and_b64 vcc, exec, s[18:19]
	s_cbranch_vccz .LBB0_240
	s_barrier

.LBB0_331:
	v_add_u32_e32 v161, s43, v149
	ds_read_b128 v[162:165], v161
	ds_read_b128 v[166:169], v161 offset:1024
	ds_read_b128 v[170:173], v161 offset:2048
	ds_read_b128 v[174:177], v161 offset:3072
	v_add_u32_e32 v161, s44, v149
	ds_read_b128 v[178:181], v161
	ds_read_b128 v[182:185], v161 offset:1024
	ds_read_b128 v[186:189], v161 offset:2048
	ds_read_b128 v[190:193], v161 offset:3072
	s_add_u32 s34, s8, 0xfff80080
	s_addc_u32 s35, s9, -1
	s_and_b64 s[30:31], s[30:31], exec
	s_cselect_b32 s35, s23, s35
	s_cselect_b32 s34, s46, s34
	s_cselect_b32 s31, s21, s49
	s_cselect_b32 s30, s47, s48
	s_add_i32 m0, s3, 0xc000
	ds_read_b128 v[194:197], v151
	ds_read_b128 v[198:201], v151 offset:1024
	ds_read_b128 v[202:205], v151 offset:2048
	ds_read_b128 v[206:209], v151 offset:3072
	ds_read_b128 v[210:213], v151 offset:4096
	ds_read_b128 v[214:217], v151 offset:5120
	ds_read_b128 v[222:225], v151 offset:6144
	ds_read_b128 v[226:229], v151 offset:7168
	global_load_lds_dwordx4 v136, s[8:9]
	s_add_i32 m0, s3, 0xe000
	s_nop 0
	global_load_lds_dwordx4 v138, s[8:9]
	s_waitcnt vmcnt(8)
	s_waitcnt lgkmcnt(0)
	s_setprio 1
	s_waitcnt lgkmcnt(0)
	v_mfma_f32_16x16x32_bf16 v[124:127], v[162:165], v[194:197], v[124:127]
	v_mfma_f32_16x16x32_bf16 v[120:123], v[170:173], v[194:197], v[120:123]
	v_mfma_f32_16x16x32_bf16 v[124:127], v[166:169], v[198:201], v[124:127]
	v_mfma_f32_16x16x32_bf16 v[120:123], v[174:177], v[198:201], v[120:123]
	s_barrier
	v_mfma_f32_16x16x32_bf16 v[108:111], v[162:165], v[202:205], v[108:111]
	v_mfma_f32_16x16x32_bf16 v[104:107], v[170:173], v[202:205], v[104:107]
	v_mfma_f32_16x16x32_bf16 v[92:95], v[162:165], v[210:213], v[92:95]
	v_mfma_f32_16x16x32_bf16 v[88:91], v[170:173], v[210:213], v[88:91]
	v_mfma_f32_16x16x32_bf16 v[76:79], v[162:165], v[222:225], v[76:79]
	v_mfma_f32_16x16x32_bf16 v[72:75], v[170:173], v[222:225], v[72:75]
	v_mfma_f32_16x16x32_bf16 v[116:119], v[178:181], v[194:197], v[116:119]
	v_mfma_f32_16x16x32_bf16 v[112:115], v[186:189], v[194:197], v[112:115]
	v_mfma_f32_16x16x32_bf16 v[100:103], v[178:181], v[202:205], v[100:103]
	v_mfma_f32_16x16x32_bf16 v[96:99], v[186:189], v[202:205], v[96:99]
	v_mfma_f32_16x16x32_bf16 v[84:87], v[178:181], v[210:213], v[84:87]
	v_mfma_f32_16x16x32_bf16 v[80:83], v[186:189], v[210:213], v[80:83]
	v_mfma_f32_16x16x32_bf16 v[68:71], v[178:181], v[222:225], v[68:71]
	v_mfma_f32_16x16x32_bf16 v[64:67], v[186:189], v[222:225], v[64:67]
	v_mfma_f32_16x16x32_bf16 v[108:111], v[166:169], v[206:209], v[108:111]
	v_mfma_f32_16x16x32_bf16 v[104:107], v[174:177], v[206:209], v[104:107]
	v_mfma_f32_16x16x32_bf16 v[92:95], v[166:169], v[214:217], v[92:95]
	v_mfma_f32_16x16x32_bf16 v[88:91], v[174:177], v[214:217], v[88:91]
	v_mfma_f32_16x16x32_bf16 v[76:79], v[166:169], v[226:229], v[76:79]
	v_mfma_f32_16x16x32_bf16 v[72:75], v[174:177], v[226:229], v[72:75]
	v_mfma_f32_16x16x32_bf16 v[116:119], v[182:185], v[198:201], v[116:119]
	v_mfma_f32_16x16x32_bf16 v[112:115], v[190:193], v[198:201], v[112:115]
	v_mfma_f32_16x16x32_bf16 v[100:103], v[182:185], v[206:209], v[100:103]
	v_mfma_f32_16x16x32_bf16 v[96:99], v[190:193], v[206:209], v[96:99]
	v_mfma_f32_16x16x32_bf16 v[84:87], v[182:185], v[214:217], v[84:87]
	v_mfma_f32_16x16x32_bf16 v[80:83], v[190:193], v[214:217], v[80:83]
	v_mfma_f32_16x16x32_bf16 v[68:71], v[182:185], v[226:229], v[68:71]
	v_mfma_f32_16x16x32_bf16 v[64:67], v[190:193], v[226:229], v[64:67]
	s_setprio 0
	s_barrier
	s_add_i32 s53, s43, s2
	v_lshl_add_u64 v[218:219], s[30:31], 0, v[130:131]
	s_mov_b32 m0, s53
	ds_read_b128 v[194:197], v151 offset:16384
	ds_read_b128 v[198:201], v151 offset:17408
	ds_read_b128 v[202:205], v151 offset:18432
	ds_read_b128 v[206:209], v151 offset:19456
	ds_read_b128 v[210:213], v151 offset:20480
	ds_read_b128 v[214:217], v151 offset:21504
	ds_read_b128 v[222:225], v151 offset:22528
	ds_read_b128 v[226:229], v151 offset:23552
	global_load_lds_dwordx4 v[218:219], off
	s_add_i32 m0, s53, 0x2000
	s_add_u32 s56, s30, 0x80000
	v_lshl_add_u64 v[230:231], s[30:31], 0, v[134:135]
	s_addc_u32 s57, s31, 0
	s_add_i32 s53, s44, s2
	global_load_lds_dwordx4 v[230:231], off
	s_mov_b32 m0, s53
	v_lshl_add_u64 v[234:235], s[34:35], 0, v[132:133]
	global_load_lds_dwordx4 v130, s[56:57]
	s_add_i32 m0, s53, 0x2000
	s_nop 0
	global_load_lds_dwordx4 v134, s[56:57]
	v_lshl_add_u64 v[232:233], s[34:35], 0, v[128:129]
	s_mov_b32 m0, s3
	s_nop 0
	global_load_lds_dwordx4 v[232:233], off
	s_mov_b32 m0, s29
	s_nop 0
	global_load_lds_dwordx4 v[234:235], off
	s_waitcnt vmcnt(8)
	s_waitcnt lgkmcnt(0)
	s_setprio 1
	s_waitcnt lgkmcnt(0)
	v_mfma_f32_16x16x32_bf16 v[60:63], v[162:165], v[194:197], v[60:63]
	v_mfma_f32_16x16x32_bf16 v[56:59], v[170:173], v[194:197], v[56:59]
	v_mfma_f32_16x16x32_bf16 v[60:63], v[166:169], v[198:201], v[60:63]
	v_mfma_f32_16x16x32_bf16 v[56:59], v[174:177], v[198:201], v[56:59]
	s_barrier
	v_mfma_f32_16x16x32_bf16 v[44:47], v[162:165], v[202:205], v[44:47]
	v_mfma_f32_16x16x32_bf16 v[40:43], v[170:173], v[202:205], v[40:43]
	v_mfma_f32_16x16x32_bf16 v[28:31], v[162:165], v[210:213], v[28:31]
	v_mfma_f32_16x16x32_bf16 v[24:27], v[170:173], v[210:213], v[24:27]
	v_mfma_f32_16x16x32_bf16 v[12:15], v[162:165], v[222:225], v[12:15]
	v_mfma_f32_16x16x32_bf16 v[8:11], v[170:173], v[222:225], v[8:11]
	v_mfma_f32_16x16x32_bf16 v[52:55], v[178:181], v[194:197], v[52:55]
	v_mfma_f32_16x16x32_bf16 v[48:51], v[186:189], v[194:197], v[48:51]
	v_mfma_f32_16x16x32_bf16 v[36:39], v[178:181], v[202:205], v[36:39]
	v_mfma_f32_16x16x32_bf16 v[32:35], v[186:189], v[202:205], v[32:35]
	v_mfma_f32_16x16x32_bf16 v[20:23], v[178:181], v[210:213], v[20:23]
	v_mfma_f32_16x16x32_bf16 v[16:19], v[186:189], v[210:213], v[16:19]
	v_mfma_f32_16x16x32_bf16 v[4:7], v[178:181], v[222:225], v[4:7]
	v_mfma_f32_16x16x32_bf16 v[0:3], v[186:189], v[222:225], v[0:3]
	v_mfma_f32_16x16x32_bf16 v[44:47], v[166:169], v[206:209], v[44:47]
	v_mfma_f32_16x16x32_bf16 v[40:43], v[174:177], v[206:209], v[40:43]
	v_mfma_f32_16x16x32_bf16 v[28:31], v[166:169], v[214:217], v[28:31]
	v_mfma_f32_16x16x32_bf16 v[24:27], v[174:177], v[214:217], v[24:27]
	v_mfma_f32_16x16x32_bf16 v[12:15], v[166:169], v[226:229], v[12:15]
	v_mfma_f32_16x16x32_bf16 v[8:11], v[174:177], v[226:229], v[8:11]
	v_mfma_f32_16x16x32_bf16 v[52:55], v[182:185], v[198:201], v[52:55]
	v_mfma_f32_16x16x32_bf16 v[48:51], v[190:193], v[198:201], v[48:51]
	v_mfma_f32_16x16x32_bf16 v[36:39], v[182:185], v[206:209], v[36:39]
	v_mfma_f32_16x16x32_bf16 v[32:35], v[190:193], v[206:209], v[32:35]
	v_mfma_f32_16x16x32_bf16 v[20:23], v[182:185], v[214:217], v[20:23]
	v_mfma_f32_16x16x32_bf16 v[16:19], v[190:193], v[214:217], v[16:19]
	v_mfma_f32_16x16x32_bf16 v[4:7], v[182:185], v[226:229], v[4:7]
	v_mfma_f32_16x16x32_bf16 v[0:3], v[190:193], v[226:229], v[0:3]
	s_setprio 0
	s_barrier
	s_add_i32 s53, 0, 0x18000
	v_add_u32_e32 v161, s53, v149
	s_add_i32 s55, 0, 0x1c000
	ds_read_b128 v[162:165], v161
	ds_read_b128 v[166:169], v161 offset:1024
	ds_read_b128 v[170:173], v161 offset:2048
	ds_read_b128 v[174:177], v161 offset:3072
	v_add_u32_e32 v161, s55, v149
	ds_read_b128 v[178:181], v161
	ds_read_b128 v[182:185], v161 offset:1024
	ds_read_b128 v[186:189], v161 offset:2048
	ds_read_b128 v[190:193], v161 offset:3072
	s_add_u32 s34, s34, 0x80000
	s_addc_u32 s35, s35, 0
	s_mov_b32 m0, s33
	ds_read_b128 v[194:197], v151 offset:32768
	ds_read_b128 v[198:201], v151 offset:33792
	ds_read_b128 v[202:205], v151 offset:34816
	ds_read_b128 v[206:209], v151 offset:35840
	ds_read_b128 v[210:213], v151 offset:36864
	ds_read_b128 v[214:217], v151 offset:37888
	ds_read_b128 v[222:225], v151 offset:38912
	ds_read_b128 v[226:229], v151 offset:39936
	global_load_lds_dwordx4 v128, s[34:35]
	s_mov_b32 m0, s36
	s_nop 0
	global_load_lds_dwordx4 v132, s[34:35]
	s_waitcnt vmcnt(8)
	s_waitcnt lgkmcnt(0)
	s_setprio 1
	s_waitcnt lgkmcnt(0)
	v_mfma_f32_16x16x32_bf16 v[124:127], v[162:165], v[194:197], v[124:127]
	v_mfma_f32_16x16x32_bf16 v[120:123], v[170:173], v[194:197], v[120:123]
	v_mfma_f32_16x16x32_bf16 v[124:127], v[166:169], v[198:201], v[124:127]
	v_mfma_f32_16x16x32_bf16 v[120:123], v[174:177], v[198:201], v[120:123]
	s_barrier
	v_mfma_f32_16x16x32_bf16 v[108:111], v[162:165], v[202:205], v[108:111]
	v_mfma_f32_16x16x32_bf16 v[104:107], v[170:173], v[202:205], v[104:107]
	v_mfma_f32_16x16x32_bf16 v[92:95], v[162:165], v[210:213], v[92:95]
	v_mfma_f32_16x16x32_bf16 v[88:91], v[170:173], v[210:213], v[88:91]
	v_mfma_f32_16x16x32_bf16 v[76:79], v[162:165], v[222:225], v[76:79]
	v_mfma_f32_16x16x32_bf16 v[72:75], v[170:173], v[222:225], v[72:75]
	v_mfma_f32_16x16x32_bf16 v[116:119], v[178:181], v[194:197], v[116:119]
	v_mfma_f32_16x16x32_bf16 v[112:115], v[186:189], v[194:197], v[112:115]
	v_mfma_f32_16x16x32_bf16 v[100:103], v[178:181], v[202:205], v[100:103]
	v_mfma_f32_16x16x32_bf16 v[96:99], v[186:189], v[202:205], v[96:99]
	v_mfma_f32_16x16x32_bf16 v[84:87], v[178:181], v[210:213], v[84:87]
	v_mfma_f32_16x16x32_bf16 v[80:83], v[186:189], v[210:213], v[80:83]
	v_mfma_f32_16x16x32_bf16 v[68:71], v[178:181], v[222:225], v[68:71]
	v_mfma_f32_16x16x32_bf16 v[64:67], v[186:189], v[222:225], v[64:67]
	v_mfma_f32_16x16x32_bf16 v[108:111], v[166:169], v[206:209], v[108:111]
	v_mfma_f32_16x16x32_bf16 v[104:107], v[174:177], v[206:209], v[104:107]
	v_mfma_f32_16x16x32_bf16 v[92:95], v[166:169], v[214:217], v[92:95]
	v_mfma_f32_16x16x32_bf16 v[88:91], v[174:177], v[214:217], v[88:91]
	v_mfma_f32_16x16x32_bf16 v[76:79], v[166:169], v[226:229], v[76:79]
	v_mfma_f32_16x16x32_bf16 v[72:75], v[174:177], v[226:229], v[72:75]
	v_mfma_f32_16x16x32_bf16 v[116:119], v[182:185], v[198:201], v[116:119]
	v_mfma_f32_16x16x32_bf16 v[112:115], v[190:193], v[198:201], v[112:115]
	v_mfma_f32_16x16x32_bf16 v[100:103], v[182:185], v[206:209], v[100:103]
	v_mfma_f32_16x16x32_bf16 v[96:99], v[190:193], v[206:209], v[96:99]
	v_mfma_f32_16x16x32_bf16 v[84:87], v[182:185], v[214:217], v[84:87]
	v_mfma_f32_16x16x32_bf16 v[80:83], v[190:193], v[214:217], v[80:83]
	v_mfma_f32_16x16x32_bf16 v[68:71], v[182:185], v[226:229], v[68:71]
	v_mfma_f32_16x16x32_bf16 v[64:67], v[190:193], v[226:229], v[64:67]
	s_setprio 0
	s_barrier
	s_add_i32 s34, s53, s2
	v_lshl_add_u64 v[218:219], v[218:219], 0, s[12:13]
	s_mov_b32 m0, s34
	ds_read_b128 v[194:197], v151 offset:49152
	ds_read_b128 v[198:201], v151 offset:50176
	ds_read_b128 v[202:205], v151 offset:51200
	ds_read_b128 v[206:209], v151 offset:52224
	ds_read_b128 v[210:213], v151 offset:53248
	ds_read_b128 v[214:217], v151 offset:54272
	ds_read_b128 v[222:225], v151 offset:55296
	ds_read_b128 v[226:229], v151 offset:56320
	global_load_lds_dwordx4 v[218:219], off
	s_add_i32 m0, s34, 0x2000
	s_add_u32 s30, s30, 0x80080
	v_lshl_add_u64 v[218:219], v[230:231], 0, s[12:13]
	s_addc_u32 s31, s31, 0
	s_add_i32 s34, s55, s2
	global_load_lds_dwordx4 v[218:219], off
	s_mov_b32 m0, s34
	s_nop 0
	global_load_lds_dwordx4 v130, s[30:31]
	s_add_i32 m0, s34, 0x2000
	s_nop 0
	global_load_lds_dwordx4 v134, s[30:31]
	v_lshl_add_u64 v[218:219], v[232:233], 0, s[12:13]
	s_mov_b32 m0, s38
	s_nop 0
	global_load_lds_dwordx4 v[218:219], off
	v_lshl_add_u64 v[218:219], v[234:235], 0, s[12:13]
	s_mov_b32 m0, s39
	s_nop 0
	global_load_lds_dwordx4 v[218:219], off
	s_waitcnt vmcnt(8)
	s_waitcnt lgkmcnt(0)
	s_setprio 1
	s_waitcnt lgkmcnt(0)
	v_mfma_f32_16x16x32_bf16 v[60:63], v[162:165], v[194:197], v[60:63]
	v_mfma_f32_16x16x32_bf16 v[56:59], v[170:173], v[194:197], v[56:59]
	v_mfma_f32_16x16x32_bf16 v[60:63], v[166:169], v[198:201], v[60:63]
	v_mfma_f32_16x16x32_bf16 v[56:59], v[174:177], v[198:201], v[56:59]
	s_barrier
	v_mfma_f32_16x16x32_bf16 v[44:47], v[162:165], v[202:205], v[44:47]
	v_mfma_f32_16x16x32_bf16 v[40:43], v[170:173], v[202:205], v[40:43]
	v_mfma_f32_16x16x32_bf16 v[28:31], v[162:165], v[210:213], v[28:31]
	v_mfma_f32_16x16x32_bf16 v[24:27], v[170:173], v[210:213], v[24:27]
	v_mfma_f32_16x16x32_bf16 v[12:15], v[162:165], v[222:225], v[12:15]
	v_mfma_f32_16x16x32_bf16 v[8:11], v[170:173], v[222:225], v[8:11]
	v_mfma_f32_16x16x32_bf16 v[52:55], v[178:181], v[194:197], v[52:55]
	v_mfma_f32_16x16x32_bf16 v[48:51], v[186:189], v[194:197], v[48:51]
	v_mfma_f32_16x16x32_bf16 v[36:39], v[178:181], v[202:205], v[36:39]
	v_mfma_f32_16x16x32_bf16 v[32:35], v[186:189], v[202:205], v[32:35]
	v_mfma_f32_16x16x32_bf16 v[20:23], v[178:181], v[210:213], v[20:23]
	v_mfma_f32_16x16x32_bf16 v[16:19], v[186:189], v[210:213], v[16:19]
	v_mfma_f32_16x16x32_bf16 v[4:7], v[178:181], v[222:225], v[4:7]
	v_mfma_f32_16x16x32_bf16 v[0:3], v[186:189], v[222:225], v[0:3]
	v_mfma_f32_16x16x32_bf16 v[44:47], v[166:169], v[206:209], v[44:47]
	v_mfma_f32_16x16x32_bf16 v[40:43], v[174:177], v[206:209], v[40:43]
	v_mfma_f32_16x16x32_bf16 v[28:31], v[166:169], v[214:217], v[28:31]
	v_mfma_f32_16x16x32_bf16 v[24:27], v[174:177], v[214:217], v[24:27]
	v_mfma_f32_16x16x32_bf16 v[12:15], v[166:169], v[226:229], v[12:15]
	v_mfma_f32_16x16x32_bf16 v[8:11], v[174:177], v[226:229], v[8:11]
	v_mfma_f32_16x16x32_bf16 v[52:55], v[182:185], v[198:201], v[52:55]
	v_mfma_f32_16x16x32_bf16 v[48:51], v[190:193], v[198:201], v[48:51]
	v_mfma_f32_16x16x32_bf16 v[36:39], v[182:185], v[206:209], v[36:39]
	v_mfma_f32_16x16x32_bf16 v[32:35], v[190:193], v[206:209], v[32:35]
	v_mfma_f32_16x16x32_bf16 v[20:23], v[182:185], v[214:217], v[20:23]
	v_mfma_f32_16x16x32_bf16 v[16:19], v[190:193], v[214:217], v[16:19]
	v_mfma_f32_16x16x32_bf16 v[4:7], v[182:185], v[226:229], v[4:7]
	v_mfma_f32_16x16x32_bf16 v[0:3], v[190:193], v[226:229], v[0:3]
	s_setprio 0
	s_barrier
	s_add_i32 s51, s51, 2
	s_add_u32 s8, s8, 0x100
	s_addc_u32 s9, s9, 0
	s_add_u32 s48, s48, 0x100
	s_addc_u32 s49, s49, 0
	s_cmp_gt_u32 s51, 29
	s_cbranch_scc1 .LBB0_334

.LBB0_1094:
	ds_read_b128 v[144:147], v151
	ds_read_b128 v[156:159], v151 offset:1024
	ds_read_b128 v[160:163], v151 offset:2048
	ds_read_b128 v[164:167], v151 offset:3072
	ds_read_b128 v[168:171], v152
	ds_read_b128 v[172:175], v152 offset:1024
	ds_read_b128 v[176:179], v152 offset:2048
	ds_read_b128 v[180:183], v152 offset:3072
	s_add_u32 s28, s26, 0xfff80080
	s_addc_u32 s29, s27, -1
	s_cmp_eq_u32 s48, 28
	s_cselect_b32 s31, s17, s29
	s_cselect_b32 s30, s23, s28
	s_cselect_b32 s29, s15, s47
	s_cselect_b32 s28, s45, s46
	s_add_i32 m0, s25, 0xc000
	ds_read_b128 v[184:187], v153
	ds_read_b128 v[188:191], v153 offset:1024
	ds_read_b128 v[192:195], v153 offset:2048
	ds_read_b128 v[196:199], v153 offset:3072
	ds_read_b128 v[200:203], v153 offset:4096
	ds_read_b128 v[204:207], v153 offset:5120
	ds_read_b128 v[208:211], v153 offset:6144
	ds_read_b128 v[212:215], v153 offset:7168
	global_load_lds_dwordx4 v136, s[26:27]
	s_add_i32 m0, s25, 0xe000
	s_nop 0
	global_load_lds_dwordx4 v138, s[26:27]
	s_waitcnt vmcnt(8)
	s_waitcnt lgkmcnt(0)
	s_setprio 1
	s_waitcnt lgkmcnt(0)
	v_mfma_f32_16x16x32_bf16 v[124:127], v[144:147], v[184:187], v[124:127]
	v_mfma_f32_16x16x32_bf16 v[120:123], v[160:163], v[184:187], v[120:123]
	v_mfma_f32_16x16x32_bf16 v[124:127], v[156:159], v[188:191], v[124:127]
	v_mfma_f32_16x16x32_bf16 v[120:123], v[164:167], v[188:191], v[120:123]
	s_barrier
	v_mfma_f32_16x16x32_bf16 v[108:111], v[144:147], v[192:195], v[108:111]
	v_mfma_f32_16x16x32_bf16 v[104:107], v[160:163], v[192:195], v[104:107]
	v_mfma_f32_16x16x32_bf16 v[92:95], v[144:147], v[200:203], v[92:95]
	v_mfma_f32_16x16x32_bf16 v[88:91], v[160:163], v[200:203], v[88:91]
	v_mfma_f32_16x16x32_bf16 v[76:79], v[144:147], v[208:211], v[76:79]
	v_mfma_f32_16x16x32_bf16 v[72:75], v[160:163], v[208:211], v[72:75]
	v_mfma_f32_16x16x32_bf16 v[116:119], v[168:171], v[184:187], v[116:119]
	v_mfma_f32_16x16x32_bf16 v[112:115], v[176:179], v[184:187], v[112:115]
	v_mfma_f32_16x16x32_bf16 v[100:103], v[168:171], v[192:195], v[100:103]
	v_mfma_f32_16x16x32_bf16 v[96:99], v[176:179], v[192:195], v[96:99]
	v_mfma_f32_16x16x32_bf16 v[84:87], v[168:171], v[200:203], v[84:87]
	v_mfma_f32_16x16x32_bf16 v[80:83], v[176:179], v[200:203], v[80:83]
	v_mfma_f32_16x16x32_bf16 v[68:71], v[168:171], v[208:211], v[68:71]
	v_mfma_f32_16x16x32_bf16 v[64:67], v[176:179], v[208:211], v[64:67]
	v_mfma_f32_16x16x32_bf16 v[108:111], v[156:159], v[196:199], v[108:111]
	v_mfma_f32_16x16x32_bf16 v[104:107], v[164:167], v[196:199], v[104:107]
	v_mfma_f32_16x16x32_bf16 v[92:95], v[156:159], v[204:207], v[92:95]
	v_mfma_f32_16x16x32_bf16 v[88:91], v[164:167], v[204:207], v[88:91]
	v_mfma_f32_16x16x32_bf16 v[76:79], v[156:159], v[212:215], v[76:79]
	v_mfma_f32_16x16x32_bf16 v[72:75], v[164:167], v[212:215], v[72:75]
	v_mfma_f32_16x16x32_bf16 v[116:119], v[172:175], v[188:191], v[116:119]
	v_mfma_f32_16x16x32_bf16 v[112:115], v[180:183], v[188:191], v[112:115]
	v_mfma_f32_16x16x32_bf16 v[100:103], v[172:175], v[196:199], v[100:103]
	v_mfma_f32_16x16x32_bf16 v[96:99], v[180:183], v[196:199], v[96:99]
	v_mfma_f32_16x16x32_bf16 v[84:87], v[172:175], v[204:207], v[84:87]
	v_mfma_f32_16x16x32_bf16 v[80:83], v[180:183], v[204:207], v[80:83]
	v_mfma_f32_16x16x32_bf16 v[68:71], v[172:175], v[212:215], v[68:71]
	v_mfma_f32_16x16x32_bf16 v[64:67], v[180:183], v[212:215], v[64:67]
	s_setprio 0
	s_barrier
	s_add_i32 s49, s95, s2
	v_lshl_add_u64 v[216:217], s[28:29], 0, v[130:131]
	s_mov_b32 m0, s49
	ds_read_b128 v[184:187], v153 offset:16384
	ds_read_b128 v[188:191], v153 offset:17408
	ds_read_b128 v[192:195], v153 offset:18432
	ds_read_b128 v[196:199], v153 offset:19456
	ds_read_b128 v[200:203], v153 offset:20480
	ds_read_b128 v[204:207], v153 offset:21504
	ds_read_b128 v[208:211], v153 offset:22528
	ds_read_b128 v[212:215], v153 offset:23552
	global_load_lds_dwordx4 v[216:217], off
	s_add_i32 m0, s49, 0x2000
	s_add_u32 s50, s28, 0x80000
	v_lshl_add_u64 v[218:219], s[28:29], 0, v[134:135]
	s_addc_u32 s51, s29, 0
	s_add_i32 s49, s33, s2
	global_load_lds_dwordx4 v[218:219], off
	s_mov_b32 m0, s49
	v_lshl_add_u64 v[224:225], s[30:31], 0, v[132:133]
	global_load_lds_dwordx4 v130, s[50:51]
	s_add_i32 m0, s49, 0x2000
	s_nop 0
	global_load_lds_dwordx4 v134, s[50:51]
	v_lshl_add_u64 v[222:223], s[30:31], 0, v[128:129]
	s_mov_b32 m0, s25
	s_nop 0
	global_load_lds_dwordx4 v[222:223], off
	s_mov_b32 m0, s36
	s_nop 0
	global_load_lds_dwordx4 v[224:225], off
	s_waitcnt vmcnt(8)
	s_waitcnt lgkmcnt(0)
	s_setprio 1
	s_waitcnt lgkmcnt(0)
	v_mfma_f32_16x16x32_bf16 v[60:63], v[144:147], v[184:187], v[60:63]
	v_mfma_f32_16x16x32_bf16 v[56:59], v[160:163], v[184:187], v[56:59]
	v_mfma_f32_16x16x32_bf16 v[60:63], v[156:159], v[188:191], v[60:63]
	v_mfma_f32_16x16x32_bf16 v[56:59], v[164:167], v[188:191], v[56:59]
	s_barrier
	v_mfma_f32_16x16x32_bf16 v[44:47], v[144:147], v[192:195], v[44:47]
	v_mfma_f32_16x16x32_bf16 v[40:43], v[160:163], v[192:195], v[40:43]
	v_mfma_f32_16x16x32_bf16 v[28:31], v[144:147], v[200:203], v[28:31]
	v_mfma_f32_16x16x32_bf16 v[24:27], v[160:163], v[200:203], v[24:27]
	v_mfma_f32_16x16x32_bf16 v[12:15], v[144:147], v[208:211], v[12:15]
	v_mfma_f32_16x16x32_bf16 v[8:11], v[160:163], v[208:211], v[8:11]
	v_mfma_f32_16x16x32_bf16 v[52:55], v[168:171], v[184:187], v[52:55]
	v_mfma_f32_16x16x32_bf16 v[48:51], v[176:179], v[184:187], v[48:51]
	v_mfma_f32_16x16x32_bf16 v[36:39], v[168:171], v[192:195], v[36:39]
	v_mfma_f32_16x16x32_bf16 v[32:35], v[176:179], v[192:195], v[32:35]
	v_mfma_f32_16x16x32_bf16 v[20:23], v[168:171], v[200:203], v[20:23]
	v_mfma_f32_16x16x32_bf16 v[16:19], v[176:179], v[200:203], v[16:19]
	v_mfma_f32_16x16x32_bf16 v[4:7], v[168:171], v[208:211], v[4:7]
	v_mfma_f32_16x16x32_bf16 v[0:3], v[176:179], v[208:211], v[0:3]
	v_mfma_f32_16x16x32_bf16 v[44:47], v[156:159], v[196:199], v[44:47]
	v_mfma_f32_16x16x32_bf16 v[40:43], v[164:167], v[196:199], v[40:43]
	v_mfma_f32_16x16x32_bf16 v[28:31], v[156:159], v[204:207], v[28:31]
	v_mfma_f32_16x16x32_bf16 v[24:27], v[164:167], v[204:207], v[24:27]
	v_mfma_f32_16x16x32_bf16 v[12:15], v[156:159], v[212:215], v[12:15]
	v_mfma_f32_16x16x32_bf16 v[8:11], v[164:167], v[212:215], v[8:11]
	v_mfma_f32_16x16x32_bf16 v[52:55], v[172:175], v[188:191], v[52:55]
	v_mfma_f32_16x16x32_bf16 v[48:51], v[180:183], v[188:191], v[48:51]
	v_mfma_f32_16x16x32_bf16 v[36:39], v[172:175], v[196:199], v[36:39]
	v_mfma_f32_16x16x32_bf16 v[32:35], v[180:183], v[196:199], v[32:35]
	v_mfma_f32_16x16x32_bf16 v[20:23], v[172:175], v[204:207], v[20:23]
	v_mfma_f32_16x16x32_bf16 v[16:19], v[180:183], v[204:207], v[16:19]
	v_mfma_f32_16x16x32_bf16 v[4:7], v[172:175], v[212:215], v[4:7]
	v_mfma_f32_16x16x32_bf16 v[0:3], v[180:183], v[212:215], v[0:3]
	s_setprio 0
	s_barrier
	v_add_u32_e32 v155, s3, v149
	ds_read_b128 v[144:147], v155
	ds_read_b128 v[156:159], v155 offset:1024
	ds_read_b128 v[160:163], v155 offset:2048
	ds_read_b128 v[164:167], v155 offset:3072
	v_add_u32_e32 v155, s58, v149
	ds_read_b128 v[168:171], v155
	ds_read_b128 v[172:175], v155 offset:1024
	ds_read_b128 v[176:179], v155 offset:2048
	ds_read_b128 v[180:183], v155 offset:3072
	s_add_u32 s30, s30, 0x80000
	s_addc_u32 s31, s31, 0
	s_mov_b32 m0, s37
	ds_read_b128 v[184:187], v153 offset:32768
	ds_read_b128 v[188:191], v153 offset:33792
	ds_read_b128 v[192:195], v153 offset:34816
	ds_read_b128 v[196:199], v153 offset:35840
	ds_read_b128 v[200:203], v153 offset:36864
	ds_read_b128 v[204:207], v153 offset:37888
	ds_read_b128 v[208:211], v153 offset:38912
	ds_read_b128 v[212:215], v153 offset:39936
	global_load_lds_dwordx4 v128, s[30:31]
	s_mov_b32 m0, s38
	s_nop 0
	global_load_lds_dwordx4 v132, s[30:31]
	s_waitcnt vmcnt(8)
	s_waitcnt lgkmcnt(0)
	s_setprio 1
	s_waitcnt lgkmcnt(0)
	v_mfma_f32_16x16x32_bf16 v[124:127], v[144:147], v[184:187], v[124:127]
	v_mfma_f32_16x16x32_bf16 v[120:123], v[160:163], v[184:187], v[120:123]
	v_mfma_f32_16x16x32_bf16 v[124:127], v[156:159], v[188:191], v[124:127]
	v_mfma_f32_16x16x32_bf16 v[120:123], v[164:167], v[188:191], v[120:123]
	s_barrier
	v_mfma_f32_16x16x32_bf16 v[108:111], v[144:147], v[192:195], v[108:111]
	v_mfma_f32_16x16x32_bf16 v[104:107], v[160:163], v[192:195], v[104:107]
	v_mfma_f32_16x16x32_bf16 v[92:95], v[144:147], v[200:203], v[92:95]
	v_mfma_f32_16x16x32_bf16 v[88:91], v[160:163], v[200:203], v[88:91]
	v_mfma_f32_16x16x32_bf16 v[76:79], v[144:147], v[208:211], v[76:79]
	v_mfma_f32_16x16x32_bf16 v[72:75], v[160:163], v[208:211], v[72:75]
	v_mfma_f32_16x16x32_bf16 v[116:119], v[168:171], v[184:187], v[116:119]
	v_mfma_f32_16x16x32_bf16 v[112:115], v[176:179], v[184:187], v[112:115]
	v_mfma_f32_16x16x32_bf16 v[100:103], v[168:171], v[192:195], v[100:103]
	v_mfma_f32_16x16x32_bf16 v[96:99], v[176:179], v[192:195], v[96:99]
	v_mfma_f32_16x16x32_bf16 v[84:87], v[168:171], v[200:203], v[84:87]
	v_mfma_f32_16x16x32_bf16 v[80:83], v[176:179], v[200:203], v[80:83]
	v_mfma_f32_16x16x32_bf16 v[68:71], v[168:171], v[208:211], v[68:71]
	v_mfma_f32_16x16x32_bf16 v[64:67], v[176:179], v[208:211], v[64:67]
	v_mfma_f32_16x16x32_bf16 v[108:111], v[156:159], v[196:199], v[108:111]
	v_mfma_f32_16x16x32_bf16 v[104:107], v[164:167], v[196:199], v[104:107]
	v_mfma_f32_16x16x32_bf16 v[92:95], v[156:159], v[204:207], v[92:95]
	v_mfma_f32_16x16x32_bf16 v[88:91], v[164:167], v[204:207], v[88:91]
	v_mfma_f32_16x16x32_bf16 v[76:79], v[156:159], v[212:215], v[76:79]
	v_mfma_f32_16x16x32_bf16 v[72:75], v[164:167], v[212:215], v[72:75]
	v_mfma_f32_16x16x32_bf16 v[116:119], v[172:175], v[188:191], v[116:119]
	v_mfma_f32_16x16x32_bf16 v[112:115], v[180:183], v[188:191], v[112:115]
	v_mfma_f32_16x16x32_bf16 v[100:103], v[172:175], v[196:199], v[100:103]
	v_mfma_f32_16x16x32_bf16 v[96:99], v[180:183], v[196:199], v[96:99]
	v_mfma_f32_16x16x32_bf16 v[84:87], v[172:175], v[204:207], v[84:87]
	v_mfma_f32_16x16x32_bf16 v[80:83], v[180:183], v[204:207], v[80:83]
	v_mfma_f32_16x16x32_bf16 v[68:71], v[172:175], v[212:215], v[68:71]
	v_mfma_f32_16x16x32_bf16 v[64:67], v[180:183], v[212:215], v[64:67]
	s_setprio 0
	s_barrier
	s_add_i32 s30, s3, s2
	v_lshl_add_u64 v[216:217], v[216:217], 0, s[10:11]
	s_mov_b32 m0, s30
	ds_read_b128 v[184:187], v153 offset:49152
	ds_read_b128 v[188:191], v153 offset:50176
	ds_read_b128 v[192:195], v153 offset:51200
	ds_read_b128 v[196:199], v153 offset:52224
	ds_read_b128 v[200:203], v153 offset:53248
	ds_read_b128 v[204:207], v153 offset:54272
	ds_read_b128 v[208:211], v153 offset:55296
	ds_read_b128 v[212:215], v153 offset:56320
	global_load_lds_dwordx4 v[216:217], off
	s_add_i32 m0, s30, 0x2000
	s_add_u32 s28, s28, 0x80080
	v_lshl_add_u64 v[216:217], v[218:219], 0, s[10:11]
	s_addc_u32 s29, s29, 0
	s_add_i32 s30, s58, s2
	global_load_lds_dwordx4 v[216:217], off
	s_mov_b32 m0, s30
	s_nop 0
	global_load_lds_dwordx4 v130, s[28:29]
	s_add_i32 m0, s30, 0x2000
	s_nop 0
	global_load_lds_dwordx4 v134, s[28:29]
	v_lshl_add_u64 v[216:217], v[222:223], 0, s[10:11]
	s_mov_b32 m0, s40
	s_nop 0
	global_load_lds_dwordx4 v[216:217], off
	v_lshl_add_u64 v[216:217], v[224:225], 0, s[10:11]
	s_mov_b32 m0, s41
	s_nop 0
	global_load_lds_dwordx4 v[216:217], off
	s_waitcnt vmcnt(8)
	s_waitcnt lgkmcnt(0)
	s_setprio 1
	s_waitcnt lgkmcnt(0)
	v_mfma_f32_16x16x32_bf16 v[60:63], v[144:147], v[184:187], v[60:63]
	v_mfma_f32_16x16x32_bf16 v[56:59], v[160:163], v[184:187], v[56:59]
	v_mfma_f32_16x16x32_bf16 v[60:63], v[156:159], v[188:191], v[60:63]
	v_mfma_f32_16x16x32_bf16 v[56:59], v[164:167], v[188:191], v[56:59]
	s_barrier
	v_mfma_f32_16x16x32_bf16 v[44:47], v[144:147], v[192:195], v[44:47]
	v_mfma_f32_16x16x32_bf16 v[40:43], v[160:163], v[192:195], v[40:43]
	v_mfma_f32_16x16x32_bf16 v[28:31], v[144:147], v[200:203], v[28:31]
	v_mfma_f32_16x16x32_bf16 v[24:27], v[160:163], v[200:203], v[24:27]
	v_mfma_f32_16x16x32_bf16 v[12:15], v[144:147], v[208:211], v[12:15]
	v_mfma_f32_16x16x32_bf16 v[8:11], v[160:163], v[208:211], v[8:11]
	v_mfma_f32_16x16x32_bf16 v[52:55], v[168:171], v[184:187], v[52:55]
	v_mfma_f32_16x16x32_bf16 v[48:51], v[176:179], v[184:187], v[48:51]
	v_mfma_f32_16x16x32_bf16 v[36:39], v[168:171], v[192:195], v[36:39]
	v_mfma_f32_16x16x32_bf16 v[32:35], v[176:179], v[192:195], v[32:35]
	v_mfma_f32_16x16x32_bf16 v[20:23], v[168:171], v[200:203], v[20:23]
	v_mfma_f32_16x16x32_bf16 v[16:19], v[176:179], v[200:203], v[16:19]
	v_mfma_f32_16x16x32_bf16 v[4:7], v[168:171], v[208:211], v[4:7]
	v_mfma_f32_16x16x32_bf16 v[0:3], v[176:179], v[208:211], v[0:3]
	v_mfma_f32_16x16x32_bf16 v[44:47], v[156:159], v[196:199], v[44:47]
	v_mfma_f32_16x16x32_bf16 v[40:43], v[164:167], v[196:199], v[40:43]
	v_mfma_f32_16x16x32_bf16 v[28:31], v[156:159], v[204:207], v[28:31]
	v_mfma_f32_16x16x32_bf16 v[24:27], v[164:167], v[204:207], v[24:27]
	v_mfma_f32_16x16x32_bf16 v[12:15], v[156:159], v[212:215], v[12:15]
	v_mfma_f32_16x16x32_bf16 v[8:11], v[164:167], v[212:215], v[8:11]
	v_mfma_f32_16x16x32_bf16 v[52:55], v[172:175], v[188:191], v[52:55]
	v_mfma_f32_16x16x32_bf16 v[48:51], v[180:183], v[188:191], v[48:51]
	v_mfma_f32_16x16x32_bf16 v[36:39], v[172:175], v[196:199], v[36:39]
	v_mfma_f32_16x16x32_bf16 v[32:35], v[180:183], v[196:199], v[32:35]
	v_mfma_f32_16x16x32_bf16 v[20:23], v[172:175], v[204:207], v[20:23]
	v_mfma_f32_16x16x32_bf16 v[16:19], v[180:183], v[204:207], v[16:19]
	v_mfma_f32_16x16x32_bf16 v[4:7], v[172:175], v[212:215], v[4:7]
	v_mfma_f32_16x16x32_bf16 v[0:3], v[180:183], v[212:215], v[0:3]
	s_setprio 0
	s_barrier
	s_add_i32 s48, s48, 2
	s_add_u32 s26, s26, 0x100
	s_addc_u32 s27, s27, 0
	s_add_u32 s46, s46, 0x100
	s_addc_u32 s47, s47, 0
	s_cmp_gt_u32 s48, 29
	s_cbranch_scc0 .LBB0_1094
	s_and_b64 vcc, exec, s[12:13]
	s_cbranch_vccz .LBB0_1097
	s_barrier

.LBB0_1178:
	v_add_u32_e32 v153, s95, v161
	ds_read_b128 v[156:159], v153
	ds_read_b128 v[164:167], v153 offset:1024
	ds_read_b128 v[168:171], v153 offset:2048
	ds_read_b128 v[172:175], v153 offset:3072
	v_add_u32_e32 v153, s33, v161
	ds_read_b128 v[176:179], v153
	ds_read_b128 v[180:183], v153 offset:1024
	ds_read_b128 v[184:187], v153 offset:2048
	ds_read_b128 v[188:191], v153 offset:3072
	s_add_u32 s34, s28, 0xfff80080
	s_addc_u32 s35, s29, -1
	s_and_b64 s[30:31], s[30:31], exec
	s_cselect_b32 s35, s23, s35
	s_cselect_b32 s34, s47, s34
	s_cselect_b32 s31, s21, s50
	s_cselect_b32 s30, s48, s49
	s_add_i32 m0, s19, 0xc000
	ds_read_b128 v[192:195], v163
	ds_read_b128 v[196:199], v163 offset:1024
	ds_read_b128 v[200:203], v163 offset:2048
	ds_read_b128 v[204:207], v163 offset:3072
	ds_read_b128 v[208:211], v163 offset:4096
	ds_read_b128 v[212:215], v163 offset:5120
	ds_read_b128 v[216:219], v163 offset:6144
	ds_read_b128 v[222:225], v163 offset:7168
	global_load_lds_dwordx4 v136, s[28:29]
	s_add_i32 m0, s19, 0xe000
	s_nop 0
	global_load_lds_dwordx4 v138, s[28:29]
	s_waitcnt vmcnt(8)
	s_waitcnt lgkmcnt(0)
	s_setprio 1
	s_waitcnt lgkmcnt(0)
	v_mfma_f32_16x16x32_bf16 v[124:127], v[156:159], v[192:195], v[124:127]
	v_mfma_f32_16x16x32_bf16 v[120:123], v[168:171], v[192:195], v[120:123]
	v_mfma_f32_16x16x32_bf16 v[124:127], v[164:167], v[196:199], v[124:127]
	v_mfma_f32_16x16x32_bf16 v[120:123], v[172:175], v[196:199], v[120:123]
	s_barrier
	v_mfma_f32_16x16x32_bf16 v[108:111], v[156:159], v[200:203], v[108:111]
	v_mfma_f32_16x16x32_bf16 v[104:107], v[168:171], v[200:203], v[104:107]
	v_mfma_f32_16x16x32_bf16 v[92:95], v[156:159], v[208:211], v[92:95]
	v_mfma_f32_16x16x32_bf16 v[88:91], v[168:171], v[208:211], v[88:91]
	v_mfma_f32_16x16x32_bf16 v[76:79], v[156:159], v[216:219], v[76:79]
	v_mfma_f32_16x16x32_bf16 v[72:75], v[168:171], v[216:219], v[72:75]
	v_mfma_f32_16x16x32_bf16 v[116:119], v[176:179], v[192:195], v[116:119]
	v_mfma_f32_16x16x32_bf16 v[112:115], v[184:187], v[192:195], v[112:115]
	v_mfma_f32_16x16x32_bf16 v[100:103], v[176:179], v[200:203], v[100:103]
	v_mfma_f32_16x16x32_bf16 v[96:99], v[184:187], v[200:203], v[96:99]
	v_mfma_f32_16x16x32_bf16 v[84:87], v[176:179], v[208:211], v[84:87]
	v_mfma_f32_16x16x32_bf16 v[80:83], v[184:187], v[208:211], v[80:83]
	v_mfma_f32_16x16x32_bf16 v[68:71], v[176:179], v[216:219], v[68:71]
	v_mfma_f32_16x16x32_bf16 v[64:67], v[184:187], v[216:219], v[64:67]
	v_mfma_f32_16x16x32_bf16 v[108:111], v[164:167], v[204:207], v[108:111]
	v_mfma_f32_16x16x32_bf16 v[104:107], v[172:175], v[204:207], v[104:107]
	v_mfma_f32_16x16x32_bf16 v[92:95], v[164:167], v[212:215], v[92:95]
	v_mfma_f32_16x16x32_bf16 v[88:91], v[172:175], v[212:215], v[88:91]
	v_mfma_f32_16x16x32_bf16 v[76:79], v[164:167], v[222:225], v[76:79]
	v_mfma_f32_16x16x32_bf16 v[72:75], v[172:175], v[222:225], v[72:75]
	v_mfma_f32_16x16x32_bf16 v[116:119], v[180:183], v[196:199], v[116:119]
	v_mfma_f32_16x16x32_bf16 v[112:115], v[188:191], v[196:199], v[112:115]
	v_mfma_f32_16x16x32_bf16 v[100:103], v[180:183], v[204:207], v[100:103]
	v_mfma_f32_16x16x32_bf16 v[96:99], v[188:191], v[204:207], v[96:99]
	v_mfma_f32_16x16x32_bf16 v[84:87], v[180:183], v[212:215], v[84:87]
	v_mfma_f32_16x16x32_bf16 v[80:83], v[188:191], v[212:215], v[80:83]
	v_mfma_f32_16x16x32_bf16 v[68:71], v[180:183], v[222:225], v[68:71]
	v_mfma_f32_16x16x32_bf16 v[64:67], v[188:191], v[222:225], v[64:67]
	s_setprio 0
	s_barrier
	s_add_i32 s53, s95, s7
	v_lshl_add_u64 v[226:227], s[30:31], 0, v[132:133]
	s_mov_b32 m0, s53
	ds_read_b128 v[192:195], v163 offset:16384
	ds_read_b128 v[196:199], v163 offset:17408
	ds_read_b128 v[200:203], v163 offset:18432
	ds_read_b128 v[204:207], v163 offset:19456
	ds_read_b128 v[208:211], v163 offset:20480
	ds_read_b128 v[212:215], v163 offset:21504
	ds_read_b128 v[216:219], v163 offset:22528
	ds_read_b128 v[222:225], v163 offset:23552
	global_load_lds_dwordx4 v[226:227], off
	s_add_i32 m0, s53, 0x2000
	s_add_u32 s54, s30, 0x80000
	v_lshl_add_u64 v[228:229], s[30:31], 0, v[128:129]
	s_addc_u32 s55, s31, 0
	s_add_i32 s53, s33, s7
	global_load_lds_dwordx4 v[228:229], off
	s_mov_b32 m0, s53
	v_lshl_add_u64 v[232:233], s[34:35], 0, v[130:131]
	global_load_lds_dwordx4 v132, s[54:55]
	s_add_i32 m0, s53, 0x2000
	s_nop 0
	global_load_lds_dwordx4 v128, s[54:55]
	v_lshl_add_u64 v[230:231], s[34:35], 0, v[134:135]
	s_mov_b32 m0, s19
	s_nop 0
	global_load_lds_dwordx4 v[230:231], off
	s_mov_b32 m0, s36
	s_nop 0
	global_load_lds_dwordx4 v[232:233], off
	s_waitcnt vmcnt(8)
	s_waitcnt lgkmcnt(0)
	s_setprio 1
	s_waitcnt lgkmcnt(0)
	v_mfma_f32_16x16x32_bf16 v[60:63], v[156:159], v[192:195], v[60:63]
	v_mfma_f32_16x16x32_bf16 v[56:59], v[168:171], v[192:195], v[56:59]
	v_mfma_f32_16x16x32_bf16 v[60:63], v[164:167], v[196:199], v[60:63]
	v_mfma_f32_16x16x32_bf16 v[56:59], v[172:175], v[196:199], v[56:59]
	s_barrier
	v_mfma_f32_16x16x32_bf16 v[44:47], v[156:159], v[200:203], v[44:47]
	v_mfma_f32_16x16x32_bf16 v[40:43], v[168:171], v[200:203], v[40:43]
	v_mfma_f32_16x16x32_bf16 v[28:31], v[156:159], v[208:211], v[28:31]
	v_mfma_f32_16x16x32_bf16 v[24:27], v[168:171], v[208:211], v[24:27]
	v_mfma_f32_16x16x32_bf16 v[12:15], v[156:159], v[216:219], v[12:15]
	v_mfma_f32_16x16x32_bf16 v[8:11], v[168:171], v[216:219], v[8:11]
	v_mfma_f32_16x16x32_bf16 v[52:55], v[176:179], v[192:195], v[52:55]
	v_mfma_f32_16x16x32_bf16 v[48:51], v[184:187], v[192:195], v[48:51]
	v_mfma_f32_16x16x32_bf16 v[36:39], v[176:179], v[200:203], v[36:39]
	v_mfma_f32_16x16x32_bf16 v[32:35], v[184:187], v[200:203], v[32:35]
	v_mfma_f32_16x16x32_bf16 v[20:23], v[176:179], v[208:211], v[20:23]
	v_mfma_f32_16x16x32_bf16 v[16:19], v[184:187], v[208:211], v[16:19]
	v_mfma_f32_16x16x32_bf16 v[4:7], v[176:179], v[216:219], v[4:7]
	v_mfma_f32_16x16x32_bf16 v[0:3], v[184:187], v[216:219], v[0:3]
	v_mfma_f32_16x16x32_bf16 v[44:47], v[164:167], v[204:207], v[44:47]
	v_mfma_f32_16x16x32_bf16 v[40:43], v[172:175], v[204:207], v[40:43]
	v_mfma_f32_16x16x32_bf16 v[28:31], v[164:167], v[212:215], v[28:31]
	v_mfma_f32_16x16x32_bf16 v[24:27], v[172:175], v[212:215], v[24:27]
	v_mfma_f32_16x16x32_bf16 v[12:15], v[164:167], v[222:225], v[12:15]
	v_mfma_f32_16x16x32_bf16 v[8:11], v[172:175], v[222:225], v[8:11]
	v_mfma_f32_16x16x32_bf16 v[52:55], v[180:183], v[196:199], v[52:55]
	v_mfma_f32_16x16x32_bf16 v[48:51], v[188:191], v[196:199], v[48:51]
	v_mfma_f32_16x16x32_bf16 v[36:39], v[180:183], v[204:207], v[36:39]
	v_mfma_f32_16x16x32_bf16 v[32:35], v[188:191], v[204:207], v[32:35]
	v_mfma_f32_16x16x32_bf16 v[20:23], v[180:183], v[212:215], v[20:23]
	v_mfma_f32_16x16x32_bf16 v[16:19], v[188:191], v[212:215], v[16:19]
	v_mfma_f32_16x16x32_bf16 v[4:7], v[180:183], v[222:225], v[4:7]
	v_mfma_f32_16x16x32_bf16 v[0:3], v[188:191], v[222:225], v[0:3]
	s_setprio 0
	s_barrier
	v_add_u32_e32 v153, s3, v161
	ds_read_b128 v[156:159], v153
	ds_read_b128 v[164:167], v153 offset:1024
	ds_read_b128 v[168:171], v153 offset:2048
	ds_read_b128 v[172:175], v153 offset:3072
	v_add_u32_e32 v153, s58, v161
	ds_read_b128 v[176:179], v153
	ds_read_b128 v[180:183], v153 offset:1024
	ds_read_b128 v[184:187], v153 offset:2048
	ds_read_b128 v[188:191], v153 offset:3072
	s_add_u32 s34, s34, 0x80000
	s_addc_u32 s35, s35, 0
	s_mov_b32 m0, s37
	ds_read_b128 v[192:195], v163 offset:32768
	ds_read_b128 v[196:199], v163 offset:33792
	ds_read_b128 v[200:203], v163 offset:34816
	ds_read_b128 v[204:207], v163 offset:35840
	ds_read_b128 v[208:211], v163 offset:36864
	ds_read_b128 v[212:215], v163 offset:37888
	ds_read_b128 v[216:219], v163 offset:38912
	ds_read_b128 v[222:225], v163 offset:39936
	global_load_lds_dwordx4 v134, s[34:35]
	s_mov_b32 m0, s38
	s_nop 0
	global_load_lds_dwordx4 v130, s[34:35]
	s_waitcnt vmcnt(8)
	s_waitcnt lgkmcnt(0)
	s_setprio 1
	s_waitcnt lgkmcnt(0)
	v_mfma_f32_16x16x32_bf16 v[124:127], v[156:159], v[192:195], v[124:127]
	v_mfma_f32_16x16x32_bf16 v[120:123], v[168:171], v[192:195], v[120:123]
	v_mfma_f32_16x16x32_bf16 v[124:127], v[164:167], v[196:199], v[124:127]
	v_mfma_f32_16x16x32_bf16 v[120:123], v[172:175], v[196:199], v[120:123]
	s_barrier
	v_mfma_f32_16x16x32_bf16 v[108:111], v[156:159], v[200:203], v[108:111]
	v_mfma_f32_16x16x32_bf16 v[104:107], v[168:171], v[200:203], v[104:107]
	v_mfma_f32_16x16x32_bf16 v[92:95], v[156:159], v[208:211], v[92:95]
	v_mfma_f32_16x16x32_bf16 v[88:91], v[168:171], v[208:211], v[88:91]
	v_mfma_f32_16x16x32_bf16 v[76:79], v[156:159], v[216:219], v[76:79]
	v_mfma_f32_16x16x32_bf16 v[72:75], v[168:171], v[216:219], v[72:75]
	v_mfma_f32_16x16x32_bf16 v[116:119], v[176:179], v[192:195], v[116:119]
	v_mfma_f32_16x16x32_bf16 v[112:115], v[184:187], v[192:195], v[112:115]
	v_mfma_f32_16x16x32_bf16 v[100:103], v[176:179], v[200:203], v[100:103]
	v_mfma_f32_16x16x32_bf16 v[96:99], v[184:187], v[200:203], v[96:99]
	v_mfma_f32_16x16x32_bf16 v[84:87], v[176:179], v[208:211], v[84:87]
	v_mfma_f32_16x16x32_bf16 v[80:83], v[184:187], v[208:211], v[80:83]
	v_mfma_f32_16x16x32_bf16 v[68:71], v[176:179], v[216:219], v[68:71]
	v_mfma_f32_16x16x32_bf16 v[64:67], v[184:187], v[216:219], v[64:67]
	v_mfma_f32_16x16x32_bf16 v[108:111], v[164:167], v[204:207], v[108:111]
	v_mfma_f32_16x16x32_bf16 v[104:107], v[172:175], v[204:207], v[104:107]
	v_mfma_f32_16x16x32_bf16 v[92:95], v[164:167], v[212:215], v[92:95]
	v_mfma_f32_16x16x32_bf16 v[88:91], v[172:175], v[212:215], v[88:91]
	v_mfma_f32_16x16x32_bf16 v[76:79], v[164:167], v[222:225], v[76:79]
	v_mfma_f32_16x16x32_bf16 v[72:75], v[172:175], v[222:225], v[72:75]
	v_mfma_f32_16x16x32_bf16 v[116:119], v[180:183], v[196:199], v[116:119]
	v_mfma_f32_16x16x32_bf16 v[112:115], v[188:191], v[196:199], v[112:115]
	v_mfma_f32_16x16x32_bf16 v[100:103], v[180:183], v[204:207], v[100:103]
	v_mfma_f32_16x16x32_bf16 v[96:99], v[188:191], v[204:207], v[96:99]
	v_mfma_f32_16x16x32_bf16 v[84:87], v[180:183], v[212:215], v[84:87]
	v_mfma_f32_16x16x32_bf16 v[80:83], v[188:191], v[212:215], v[80:83]
	v_mfma_f32_16x16x32_bf16 v[68:71], v[180:183], v[222:225], v[68:71]
	v_mfma_f32_16x16x32_bf16 v[64:67], v[188:191], v[222:225], v[64:67]
	s_setprio 0
	s_barrier
	s_add_i32 s34, s3, s7
	v_lshl_add_u64 v[226:227], v[226:227], 0, s[10:11]
	s_mov_b32 m0, s34
	ds_read_b128 v[192:195], v163 offset:49152
	ds_read_b128 v[196:199], v163 offset:50176
	ds_read_b128 v[200:203], v163 offset:51200
	ds_read_b128 v[204:207], v163 offset:52224
	ds_read_b128 v[208:211], v163 offset:53248
	ds_read_b128 v[212:215], v163 offset:54272
	ds_read_b128 v[216:219], v163 offset:55296
	ds_read_b128 v[222:225], v163 offset:56320
	global_load_lds_dwordx4 v[226:227], off
	s_add_i32 m0, s34, 0x2000
	s_add_u32 s30, s30, 0x80080
	v_lshl_add_u64 v[226:227], v[228:229], 0, s[10:11]
	s_addc_u32 s31, s31, 0
	s_add_i32 s34, s58, s7
	global_load_lds_dwordx4 v[226:227], off
	s_mov_b32 m0, s34
	s_nop 0
	global_load_lds_dwordx4 v132, s[30:31]
	s_add_i32 m0, s34, 0x2000
	s_nop 0
	global_load_lds_dwordx4 v128, s[30:31]
	v_lshl_add_u64 v[226:227], v[230:231], 0, s[10:11]
	s_mov_b32 m0, s40
	s_nop 0
	global_load_lds_dwordx4 v[226:227], off
	v_lshl_add_u64 v[226:227], v[232:233], 0, s[10:11]
	s_mov_b32 m0, s41
	s_nop 0
	global_load_lds_dwordx4 v[226:227], off
	s_waitcnt vmcnt(8)
	s_waitcnt lgkmcnt(0)
	s_setprio 1
	s_waitcnt lgkmcnt(0)
	v_mfma_f32_16x16x32_bf16 v[60:63], v[156:159], v[192:195], v[60:63]
	v_mfma_f32_16x16x32_bf16 v[56:59], v[168:171], v[192:195], v[56:59]
	v_mfma_f32_16x16x32_bf16 v[60:63], v[164:167], v[196:199], v[60:63]
	v_mfma_f32_16x16x32_bf16 v[56:59], v[172:175], v[196:199], v[56:59]
	s_barrier
	v_mfma_f32_16x16x32_bf16 v[44:47], v[156:159], v[200:203], v[44:47]
	v_mfma_f32_16x16x32_bf16 v[40:43], v[168:171], v[200:203], v[40:43]
	v_mfma_f32_16x16x32_bf16 v[28:31], v[156:159], v[208:211], v[28:31]
	v_mfma_f32_16x16x32_bf16 v[24:27], v[168:171], v[208:211], v[24:27]
	v_mfma_f32_16x16x32_bf16 v[12:15], v[156:159], v[216:219], v[12:15]
	v_mfma_f32_16x16x32_bf16 v[8:11], v[168:171], v[216:219], v[8:11]
	v_mfma_f32_16x16x32_bf16 v[52:55], v[176:179], v[192:195], v[52:55]
	v_mfma_f32_16x16x32_bf16 v[48:51], v[184:187], v[192:195], v[48:51]
	v_mfma_f32_16x16x32_bf16 v[36:39], v[176:179], v[200:203], v[36:39]
	v_mfma_f32_16x16x32_bf16 v[32:35], v[184:187], v[200:203], v[32:35]
	v_mfma_f32_16x16x32_bf16 v[20:23], v[176:179], v[208:211], v[20:23]
	v_mfma_f32_16x16x32_bf16 v[16:19], v[184:187], v[208:211], v[16:19]
	v_mfma_f32_16x16x32_bf16 v[4:7], v[176:179], v[216:219], v[4:7]
	v_mfma_f32_16x16x32_bf16 v[0:3], v[184:187], v[216:219], v[0:3]
	v_mfma_f32_16x16x32_bf16 v[44:47], v[164:167], v[204:207], v[44:47]
	v_mfma_f32_16x16x32_bf16 v[40:43], v[172:175], v[204:207], v[40:43]
	v_mfma_f32_16x16x32_bf16 v[28:31], v[164:167], v[212:215], v[28:31]
	v_mfma_f32_16x16x32_bf16 v[24:27], v[172:175], v[212:215], v[24:27]
	v_mfma_f32_16x16x32_bf16 v[12:15], v[164:167], v[222:225], v[12:15]
	v_mfma_f32_16x16x32_bf16 v[8:11], v[172:175], v[222:225], v[8:11]
	v_mfma_f32_16x16x32_bf16 v[52:55], v[180:183], v[196:199], v[52:55]
	v_mfma_f32_16x16x32_bf16 v[48:51], v[188:191], v[196:199], v[48:51]
	v_mfma_f32_16x16x32_bf16 v[36:39], v[180:183], v[204:207], v[36:39]
	v_mfma_f32_16x16x32_bf16 v[32:35], v[188:191], v[204:207], v[32:35]
	v_mfma_f32_16x16x32_bf16 v[20:23], v[180:183], v[212:215], v[20:23]
	v_mfma_f32_16x16x32_bf16 v[16:19], v[188:191], v[212:215], v[16:19]
	v_mfma_f32_16x16x32_bf16 v[4:7], v[180:183], v[222:225], v[4:7]
	v_mfma_f32_16x16x32_bf16 v[0:3], v[188:191], v[222:225], v[0:3]
	s_setprio 0
	s_barrier
	s_add_i32 s51, s51, 2
	s_add_u32 s28, s28, 0x100
	s_addc_u32 s29, s29, 0
	s_add_u32 s49, s49, 0x100
	s_addc_u32 s50, s50, 0
	s_cmp_gt_u32 s51, 29
	s_cbranch_scc1 .LBB0_1181

.LBB0_1294:
	ds_read_b128 v[144:147], v151
	ds_read_b128 v[156:159], v151 offset:1024
	ds_read_b128 v[160:163], v151 offset:2048
	ds_read_b128 v[164:167], v151 offset:3072
	ds_read_b128 v[168:171], v152
	ds_read_b128 v[172:175], v152 offset:1024
	ds_read_b128 v[176:179], v152 offset:2048
	ds_read_b128 v[180:183], v152 offset:3072
	s_add_u32 s22, s20, 0x100
	s_addc_u32 s23, s21, 0
	s_cmpk_eq_i32 s46, 0x54
	s_cselect_b32 s27, s1, s23
	s_cselect_b32 s26, s0, s22
	s_cselect_b32 s25, s19, s45
	s_cselect_b32 s24, s18, s44
	v_lshl_add_u64 v[216:217], s[20:21], 0, v[136:137]
	s_add_i32 m0, s28, 0xc000
	ds_read_b128 v[184:187], v153
	ds_read_b128 v[188:191], v153 offset:1024
	ds_read_b128 v[192:195], v153 offset:2048
	ds_read_b128 v[196:199], v153 offset:3072
	ds_read_b128 v[200:203], v153 offset:4096
	ds_read_b128 v[204:207], v153 offset:5120
	ds_read_b128 v[208:211], v153 offset:6144
	ds_read_b128 v[212:215], v153 offset:7168
	global_load_lds_dwordx4 v[216:217], off
	v_lshl_add_u64 v[216:217], s[20:21], 0, v[138:139]
	s_add_i32 m0, s28, 0xe000
	s_nop 0
	global_load_lds_dwordx4 v[216:217], off
	s_waitcnt vmcnt(8)
	s_waitcnt lgkmcnt(0)
	s_setprio 1
	s_waitcnt lgkmcnt(0)
	v_mfma_f32_16x16x32_bf16 v[124:127], v[144:147], v[184:187], v[124:127]
	v_mfma_f32_16x16x32_bf16 v[120:123], v[160:163], v[184:187], v[120:123]
	v_mfma_f32_16x16x32_bf16 v[124:127], v[156:159], v[188:191], v[124:127]
	v_mfma_f32_16x16x32_bf16 v[120:123], v[164:167], v[188:191], v[120:123]
	s_barrier
	v_mfma_f32_16x16x32_bf16 v[108:111], v[144:147], v[192:195], v[108:111]
	v_mfma_f32_16x16x32_bf16 v[104:107], v[160:163], v[192:195], v[104:107]
	v_mfma_f32_16x16x32_bf16 v[92:95], v[144:147], v[200:203], v[92:95]
	v_mfma_f32_16x16x32_bf16 v[88:91], v[160:163], v[200:203], v[88:91]
	v_mfma_f32_16x16x32_bf16 v[76:79], v[144:147], v[208:211], v[76:79]
	v_mfma_f32_16x16x32_bf16 v[72:75], v[160:163], v[208:211], v[72:75]
	v_mfma_f32_16x16x32_bf16 v[116:119], v[168:171], v[184:187], v[116:119]
	v_mfma_f32_16x16x32_bf16 v[112:115], v[176:179], v[184:187], v[112:115]
	v_mfma_f32_16x16x32_bf16 v[100:103], v[168:171], v[192:195], v[100:103]
	v_mfma_f32_16x16x32_bf16 v[96:99], v[176:179], v[192:195], v[96:99]
	v_mfma_f32_16x16x32_bf16 v[84:87], v[168:171], v[200:203], v[84:87]
	v_mfma_f32_16x16x32_bf16 v[80:83], v[176:179], v[200:203], v[80:83]
	v_mfma_f32_16x16x32_bf16 v[68:71], v[168:171], v[208:211], v[68:71]
	v_mfma_f32_16x16x32_bf16 v[64:67], v[176:179], v[208:211], v[64:67]
	v_mfma_f32_16x16x32_bf16 v[108:111], v[156:159], v[196:199], v[108:111]
	v_mfma_f32_16x16x32_bf16 v[104:107], v[164:167], v[196:199], v[104:107]
	v_mfma_f32_16x16x32_bf16 v[92:95], v[156:159], v[204:207], v[92:95]
	v_mfma_f32_16x16x32_bf16 v[88:91], v[164:167], v[204:207], v[88:91]
	v_mfma_f32_16x16x32_bf16 v[76:79], v[156:159], v[212:215], v[76:79]
	v_mfma_f32_16x16x32_bf16 v[72:75], v[164:167], v[212:215], v[72:75]
	v_mfma_f32_16x16x32_bf16 v[116:119], v[172:175], v[188:191], v[116:119]
	v_mfma_f32_16x16x32_bf16 v[112:115], v[180:183], v[188:191], v[112:115]
	v_mfma_f32_16x16x32_bf16 v[100:103], v[172:175], v[196:199], v[100:103]
	v_mfma_f32_16x16x32_bf16 v[96:99], v[180:183], v[196:199], v[96:99]
	v_mfma_f32_16x16x32_bf16 v[84:87], v[172:175], v[204:207], v[84:87]
	v_mfma_f32_16x16x32_bf16 v[80:83], v[180:183], v[204:207], v[80:83]
	v_mfma_f32_16x16x32_bf16 v[68:71], v[172:175], v[212:215], v[68:71]
	v_mfma_f32_16x16x32_bf16 v[64:67], v[180:183], v[212:215], v[64:67]
	s_setprio 0
	s_barrier
	s_add_i32 s20, s95, s7
	v_lshl_add_u64 v[216:217], s[24:25], 0, v[130:131]
	s_mov_b32 m0, s20
	ds_read_b128 v[184:187], v153 offset:16384
	ds_read_b128 v[188:191], v153 offset:17408
	ds_read_b128 v[192:195], v153 offset:18432
	ds_read_b128 v[196:199], v153 offset:19456
	ds_read_b128 v[200:203], v153 offset:20480
	ds_read_b128 v[204:207], v153 offset:21504
	ds_read_b128 v[208:211], v153 offset:22528
	ds_read_b128 v[212:215], v153 offset:23552
	global_load_lds_dwordx4 v[216:217], off
	s_add_i32 m0, s20, 0x2000
	s_add_u32 s20, s24, 0x160000
	v_lshl_add_u64 v[218:219], s[24:25], 0, v[134:135]
	s_addc_u32 s21, s25, 0
	s_add_i32 s47, s33, s7
	global_load_lds_dwordx4 v[218:219], off
	s_mov_b32 m0, s47
	v_lshl_add_u64 v[224:225], s[26:27], 0, v[132:133]
	global_load_lds_dwordx4 v130, s[20:21]
	s_add_i32 m0, s47, 0x2000
	s_nop 0
	global_load_lds_dwordx4 v134, s[20:21]
	v_lshl_add_u64 v[222:223], s[26:27], 0, v[128:129]
	s_mov_b32 m0, s28
	s_nop 0
	global_load_lds_dwordx4 v[222:223], off
	s_mov_b32 m0, s29
	s_nop 0
	global_load_lds_dwordx4 v[224:225], off
	s_waitcnt vmcnt(8)
	s_waitcnt lgkmcnt(0)
	s_setprio 1
	s_waitcnt lgkmcnt(0)
	v_mfma_f32_16x16x32_bf16 v[60:63], v[144:147], v[184:187], v[60:63]
	v_mfma_f32_16x16x32_bf16 v[56:59], v[160:163], v[184:187], v[56:59]
	v_mfma_f32_16x16x32_bf16 v[60:63], v[156:159], v[188:191], v[60:63]
	v_mfma_f32_16x16x32_bf16 v[56:59], v[164:167], v[188:191], v[56:59]
	s_barrier
	v_mfma_f32_16x16x32_bf16 v[44:47], v[144:147], v[192:195], v[44:47]
	v_mfma_f32_16x16x32_bf16 v[40:43], v[160:163], v[192:195], v[40:43]
	v_mfma_f32_16x16x32_bf16 v[28:31], v[144:147], v[200:203], v[28:31]
	v_mfma_f32_16x16x32_bf16 v[24:27], v[160:163], v[200:203], v[24:27]
	v_mfma_f32_16x16x32_bf16 v[12:15], v[144:147], v[208:211], v[12:15]
	v_mfma_f32_16x16x32_bf16 v[8:11], v[160:163], v[208:211], v[8:11]
	v_mfma_f32_16x16x32_bf16 v[52:55], v[168:171], v[184:187], v[52:55]
	v_mfma_f32_16x16x32_bf16 v[48:51], v[176:179], v[184:187], v[48:51]
	v_mfma_f32_16x16x32_bf16 v[36:39], v[168:171], v[192:195], v[36:39]
	v_mfma_f32_16x16x32_bf16 v[32:35], v[176:179], v[192:195], v[32:35]
	v_mfma_f32_16x16x32_bf16 v[20:23], v[168:171], v[200:203], v[20:23]
	v_mfma_f32_16x16x32_bf16 v[16:19], v[176:179], v[200:203], v[16:19]
	v_mfma_f32_16x16x32_bf16 v[4:7], v[168:171], v[208:211], v[4:7]
	v_mfma_f32_16x16x32_bf16 v[0:3], v[176:179], v[208:211], v[0:3]
	v_mfma_f32_16x16x32_bf16 v[44:47], v[156:159], v[196:199], v[44:47]
	v_mfma_f32_16x16x32_bf16 v[40:43], v[164:167], v[196:199], v[40:43]
	v_mfma_f32_16x16x32_bf16 v[28:31], v[156:159], v[204:207], v[28:31]
	v_mfma_f32_16x16x32_bf16 v[24:27], v[164:167], v[204:207], v[24:27]
	v_mfma_f32_16x16x32_bf16 v[12:15], v[156:159], v[212:215], v[12:15]
	v_mfma_f32_16x16x32_bf16 v[8:11], v[164:167], v[212:215], v[8:11]
	v_mfma_f32_16x16x32_bf16 v[52:55], v[172:175], v[188:191], v[52:55]
	v_mfma_f32_16x16x32_bf16 v[48:51], v[180:183], v[188:191], v[48:51]
	v_mfma_f32_16x16x32_bf16 v[36:39], v[172:175], v[196:199], v[36:39]
	v_mfma_f32_16x16x32_bf16 v[32:35], v[180:183], v[196:199], v[32:35]
	v_mfma_f32_16x16x32_bf16 v[20:23], v[172:175], v[204:207], v[20:23]
	v_mfma_f32_16x16x32_bf16 v[16:19], v[180:183], v[204:207], v[16:19]
	v_mfma_f32_16x16x32_bf16 v[4:7], v[172:175], v[212:215], v[4:7]
	v_mfma_f32_16x16x32_bf16 v[0:3], v[180:183], v[212:215], v[0:3]
	s_setprio 0
	s_barrier
	v_add_u32_e32 v155, s3, v149
	ds_read_b128 v[144:147], v155
	ds_read_b128 v[156:159], v155 offset:1024
	ds_read_b128 v[160:163], v155 offset:2048
	ds_read_b128 v[164:167], v155 offset:3072
	v_add_u32_e32 v155, s58, v149
	ds_read_b128 v[168:171], v155
	ds_read_b128 v[172:175], v155 offset:1024
	ds_read_b128 v[176:179], v155 offset:2048
	ds_read_b128 v[180:183], v155 offset:3072
	s_add_u32 s20, s26, 0x160000
	s_addc_u32 s21, s27, 0
	s_mov_b32 m0, s30
	ds_read_b128 v[184:187], v153 offset:32768
	ds_read_b128 v[188:191], v153 offset:33792
	ds_read_b128 v[192:195], v153 offset:34816
	ds_read_b128 v[196:199], v153 offset:35840
	ds_read_b128 v[200:203], v153 offset:36864
	ds_read_b128 v[204:207], v153 offset:37888
	ds_read_b128 v[208:211], v153 offset:38912
	ds_read_b128 v[212:215], v153 offset:39936
	global_load_lds_dwordx4 v128, s[20:21]
	s_mov_b32 m0, s31
	s_nop 0
	global_load_lds_dwordx4 v132, s[20:21]
	s_waitcnt vmcnt(8)
	s_waitcnt lgkmcnt(0)
	s_setprio 1
	s_waitcnt lgkmcnt(0)
	v_mfma_f32_16x16x32_bf16 v[124:127], v[144:147], v[184:187], v[124:127]
	v_mfma_f32_16x16x32_bf16 v[120:123], v[160:163], v[184:187], v[120:123]
	v_mfma_f32_16x16x32_bf16 v[124:127], v[156:159], v[188:191], v[124:127]
	v_mfma_f32_16x16x32_bf16 v[120:123], v[164:167], v[188:191], v[120:123]
	s_barrier
	v_mfma_f32_16x16x32_bf16 v[108:111], v[144:147], v[192:195], v[108:111]
	v_mfma_f32_16x16x32_bf16 v[104:107], v[160:163], v[192:195], v[104:107]
	v_mfma_f32_16x16x32_bf16 v[92:95], v[144:147], v[200:203], v[92:95]
	v_mfma_f32_16x16x32_bf16 v[88:91], v[160:163], v[200:203], v[88:91]
	v_mfma_f32_16x16x32_bf16 v[76:79], v[144:147], v[208:211], v[76:79]
	v_mfma_f32_16x16x32_bf16 v[72:75], v[160:163], v[208:211], v[72:75]
	v_mfma_f32_16x16x32_bf16 v[116:119], v[168:171], v[184:187], v[116:119]
	v_mfma_f32_16x16x32_bf16 v[112:115], v[176:179], v[184:187], v[112:115]
	v_mfma_f32_16x16x32_bf16 v[100:103], v[168:171], v[192:195], v[100:103]
	v_mfma_f32_16x16x32_bf16 v[96:99], v[176:179], v[192:195], v[96:99]
	v_mfma_f32_16x16x32_bf16 v[84:87], v[168:171], v[200:203], v[84:87]
	v_mfma_f32_16x16x32_bf16 v[80:83], v[176:179], v[200:203], v[80:83]
	v_mfma_f32_16x16x32_bf16 v[68:71], v[168:171], v[208:211], v[68:71]
	v_mfma_f32_16x16x32_bf16 v[64:67], v[176:179], v[208:211], v[64:67]
	v_mfma_f32_16x16x32_bf16 v[108:111], v[156:159], v[196:199], v[108:111]
	v_mfma_f32_16x16x32_bf16 v[104:107], v[164:167], v[196:199], v[104:107]
	v_mfma_f32_16x16x32_bf16 v[92:95], v[156:159], v[204:207], v[92:95]
	v_mfma_f32_16x16x32_bf16 v[88:91], v[164:167], v[204:207], v[88:91]
	v_mfma_f32_16x16x32_bf16 v[76:79], v[156:159], v[212:215], v[76:79]
	v_mfma_f32_16x16x32_bf16 v[72:75], v[164:167], v[212:215], v[72:75]
	v_mfma_f32_16x16x32_bf16 v[116:119], v[172:175], v[188:191], v[116:119]
	v_mfma_f32_16x16x32_bf16 v[112:115], v[180:183], v[188:191], v[112:115]
	v_mfma_f32_16x16x32_bf16 v[100:103], v[172:175], v[196:199], v[100:103]
	v_mfma_f32_16x16x32_bf16 v[96:99], v[180:183], v[196:199], v[96:99]
	v_mfma_f32_16x16x32_bf16 v[84:87], v[172:175], v[204:207], v[84:87]
	v_mfma_f32_16x16x32_bf16 v[80:83], v[180:183], v[204:207], v[80:83]
	v_mfma_f32_16x16x32_bf16 v[68:71], v[172:175], v[212:215], v[68:71]
	v_mfma_f32_16x16x32_bf16 v[64:67], v[180:183], v[212:215], v[64:67]
	s_setprio 0
	s_barrier
	s_add_i32 s20, s3, s7
	v_lshl_add_u64 v[216:217], v[216:217], 0, s[14:15]
	s_mov_b32 m0, s20
	ds_read_b128 v[184:187], v153 offset:49152
	ds_read_b128 v[188:191], v153 offset:50176
	ds_read_b128 v[192:195], v153 offset:51200
	ds_read_b128 v[196:199], v153 offset:52224
	ds_read_b128 v[200:203], v153 offset:53248
	ds_read_b128 v[204:207], v153 offset:54272
	ds_read_b128 v[208:211], v153 offset:55296
	ds_read_b128 v[212:215], v153 offset:56320
	global_load_lds_dwordx4 v[216:217], off
	s_add_i32 m0, s20, 0x2000
	s_add_u32 s20, s24, 0x160080
	v_lshl_add_u64 v[216:217], v[218:219], 0, s[14:15]
	s_addc_u32 s21, s25, 0
	s_add_i32 s24, s58, s7
	global_load_lds_dwordx4 v[216:217], off
	s_mov_b32 m0, s24
	s_nop 0
	global_load_lds_dwordx4 v130, s[20:21]
	s_add_i32 m0, s24, 0x2000
	s_nop 0
	global_load_lds_dwordx4 v134, s[20:21]
	v_lshl_add_u64 v[216:217], v[222:223], 0, s[14:15]
	s_mov_b32 m0, s35
	s_nop 0
	global_load_lds_dwordx4 v[216:217], off
	v_lshl_add_u64 v[216:217], v[224:225], 0, s[14:15]
	s_mov_b32 m0, s36
	s_nop 0
	global_load_lds_dwordx4 v[216:217], off
	s_waitcnt vmcnt(8)
	s_waitcnt lgkmcnt(0)
	s_setprio 1
	s_waitcnt lgkmcnt(0)
	v_mfma_f32_16x16x32_bf16 v[60:63], v[144:147], v[184:187], v[60:63]
	v_mfma_f32_16x16x32_bf16 v[56:59], v[160:163], v[184:187], v[56:59]
	v_mfma_f32_16x16x32_bf16 v[60:63], v[156:159], v[188:191], v[60:63]
	v_mfma_f32_16x16x32_bf16 v[56:59], v[164:167], v[188:191], v[56:59]
	s_barrier
	v_mfma_f32_16x16x32_bf16 v[44:47], v[144:147], v[192:195], v[44:47]
	v_mfma_f32_16x16x32_bf16 v[40:43], v[160:163], v[192:195], v[40:43]
	v_mfma_f32_16x16x32_bf16 v[28:31], v[144:147], v[200:203], v[28:31]
	v_mfma_f32_16x16x32_bf16 v[24:27], v[160:163], v[200:203], v[24:27]
	v_mfma_f32_16x16x32_bf16 v[12:15], v[144:147], v[208:211], v[12:15]
	v_mfma_f32_16x16x32_bf16 v[8:11], v[160:163], v[208:211], v[8:11]
	v_mfma_f32_16x16x32_bf16 v[52:55], v[168:171], v[184:187], v[52:55]
	v_mfma_f32_16x16x32_bf16 v[48:51], v[176:179], v[184:187], v[48:51]
	v_mfma_f32_16x16x32_bf16 v[36:39], v[168:171], v[192:195], v[36:39]
	v_mfma_f32_16x16x32_bf16 v[32:35], v[176:179], v[192:195], v[32:35]
	v_mfma_f32_16x16x32_bf16 v[20:23], v[168:171], v[200:203], v[20:23]
	v_mfma_f32_16x16x32_bf16 v[16:19], v[176:179], v[200:203], v[16:19]
	v_mfma_f32_16x16x32_bf16 v[4:7], v[168:171], v[208:211], v[4:7]
	v_mfma_f32_16x16x32_bf16 v[0:3], v[176:179], v[208:211], v[0:3]
	v_mfma_f32_16x16x32_bf16 v[44:47], v[156:159], v[196:199], v[44:47]
	v_mfma_f32_16x16x32_bf16 v[40:43], v[164:167], v[196:199], v[40:43]
	v_mfma_f32_16x16x32_bf16 v[28:31], v[156:159], v[204:207], v[28:31]
	v_mfma_f32_16x16x32_bf16 v[24:27], v[164:167], v[204:207], v[24:27]
	v_mfma_f32_16x16x32_bf16 v[12:15], v[156:159], v[212:215], v[12:15]
	v_mfma_f32_16x16x32_bf16 v[8:11], v[164:167], v[212:215], v[8:11]
	v_mfma_f32_16x16x32_bf16 v[52:55], v[172:175], v[188:191], v[52:55]
	v_mfma_f32_16x16x32_bf16 v[48:51], v[180:183], v[188:191], v[48:51]
	v_mfma_f32_16x16x32_bf16 v[36:39], v[172:175], v[196:199], v[36:39]
	v_mfma_f32_16x16x32_bf16 v[32:35], v[180:183], v[196:199], v[32:35]
	v_mfma_f32_16x16x32_bf16 v[20:23], v[172:175], v[204:207], v[20:23]
	v_mfma_f32_16x16x32_bf16 v[16:19], v[180:183], v[204:207], v[16:19]
	v_mfma_f32_16x16x32_bf16 v[4:7], v[172:175], v[212:215], v[4:7]
	v_mfma_f32_16x16x32_bf16 v[0:3], v[180:183], v[212:215], v[0:3]
	s_setprio 0
	s_barrier
	s_add_i32 s46, s46, 2
	s_add_u32 s44, s44, 0x100
	s_addc_u32 s45, s45, 0
	s_cmpk_gt_u32 s46, 0x55
	s_mov_b64 s[20:21], s[22:23]
	s_cbranch_scc0 .LBB0_1294
	s_and_b64 vcc, exec, s[16:17]
	s_cbranch_vccz .LBB0_1297
	s_barrier

.LBB0_1386:
	v_add_u32_e32 v156, s95, v159
	ds_read_b128 v[162:165], v156
	ds_read_b128 v[166:169], v156 offset:1024
	ds_read_b128 v[170:173], v156 offset:2048
	ds_read_b128 v[174:177], v156 offset:3072
	v_add_u32_e32 v156, s33, v159
	ds_read_b128 v[178:181], v156
	ds_read_b128 v[182:185], v156 offset:1024
	ds_read_b128 v[186:189], v156 offset:2048
	ds_read_b128 v[190:193], v156 offset:3072
	s_add_u32 s38, s34, 0xfff80080
	s_addc_u32 s39, s35, -1
	s_and_b64 s[36:37], s[36:37], exec
	s_cselect_b32 s39, s27, s39
	s_cselect_b32 s38, s53, s38
	s_cselect_b32 s37, s25, s56
	s_cselect_b32 s36, s54, s55
	s_add_i32 m0, s7, 0xc000
	ds_read_b128 v[194:197], v161
	ds_read_b128 v[198:201], v161 offset:1024
	ds_read_b128 v[202:205], v161 offset:2048
	ds_read_b128 v[206:209], v161 offset:3072
	ds_read_b128 v[210:213], v161 offset:4096
	ds_read_b128 v[214:217], v161 offset:5120
	ds_read_b128 v[222:225], v161 offset:6144
	ds_read_b128 v[226:229], v161 offset:7168
	global_load_lds_dwordx4 v136, s[34:35]
	s_add_i32 m0, s7, 0xe000
	s_nop 0
	global_load_lds_dwordx4 v138, s[34:35]
	s_waitcnt vmcnt(8)
	s_waitcnt lgkmcnt(0)
	s_setprio 1
	s_waitcnt lgkmcnt(0)
	v_mfma_f32_16x16x32_bf16 v[124:127], v[162:165], v[194:197], v[124:127]
	v_mfma_f32_16x16x32_bf16 v[120:123], v[170:173], v[194:197], v[120:123]
	v_mfma_f32_16x16x32_bf16 v[124:127], v[166:169], v[198:201], v[124:127]
	v_mfma_f32_16x16x32_bf16 v[120:123], v[174:177], v[198:201], v[120:123]
	s_barrier
	v_mfma_f32_16x16x32_bf16 v[116:119], v[162:165], v[202:205], v[116:119]
	v_mfma_f32_16x16x32_bf16 v[104:107], v[170:173], v[202:205], v[104:107]
	v_mfma_f32_16x16x32_bf16 v[92:95], v[162:165], v[210:213], v[92:95]
	v_mfma_f32_16x16x32_bf16 v[88:91], v[170:173], v[210:213], v[88:91]
	v_mfma_f32_16x16x32_bf16 v[84:87], v[162:165], v[222:225], v[84:87]
	v_mfma_f32_16x16x32_bf16 v[72:75], v[170:173], v[222:225], v[72:75]
	v_mfma_f32_16x16x32_bf16 v[112:115], v[178:181], v[194:197], v[112:115]
	v_mfma_f32_16x16x32_bf16 v[108:111], v[186:189], v[194:197], v[108:111]
	v_mfma_f32_16x16x32_bf16 v[100:103], v[178:181], v[202:205], v[100:103]
	v_mfma_f32_16x16x32_bf16 v[96:99], v[186:189], v[202:205], v[96:99]
	v_mfma_f32_16x16x32_bf16 v[80:83], v[178:181], v[210:213], v[80:83]
	v_mfma_f32_16x16x32_bf16 v[76:79], v[186:189], v[210:213], v[76:79]
	v_mfma_f32_16x16x32_bf16 v[68:71], v[178:181], v[222:225], v[68:71]
	v_mfma_f32_16x16x32_bf16 v[64:67], v[186:189], v[222:225], v[64:67]
	v_mfma_f32_16x16x32_bf16 v[116:119], v[166:169], v[206:209], v[116:119]
	v_mfma_f32_16x16x32_bf16 v[104:107], v[174:177], v[206:209], v[104:107]
	v_mfma_f32_16x16x32_bf16 v[92:95], v[166:169], v[214:217], v[92:95]
	v_mfma_f32_16x16x32_bf16 v[88:91], v[174:177], v[214:217], v[88:91]
	v_mfma_f32_16x16x32_bf16 v[84:87], v[166:169], v[226:229], v[84:87]
	v_mfma_f32_16x16x32_bf16 v[72:75], v[174:177], v[226:229], v[72:75]
	v_mfma_f32_16x16x32_bf16 v[112:115], v[182:185], v[198:201], v[112:115]
	v_mfma_f32_16x16x32_bf16 v[108:111], v[190:193], v[198:201], v[108:111]
	v_mfma_f32_16x16x32_bf16 v[100:103], v[182:185], v[206:209], v[100:103]
	v_mfma_f32_16x16x32_bf16 v[96:99], v[190:193], v[206:209], v[96:99]
	v_mfma_f32_16x16x32_bf16 v[80:83], v[182:185], v[214:217], v[80:83]
	v_mfma_f32_16x16x32_bf16 v[76:79], v[190:193], v[214:217], v[76:79]
	v_mfma_f32_16x16x32_bf16 v[68:71], v[182:185], v[226:229], v[68:71]
	v_mfma_f32_16x16x32_bf16 v[64:67], v[190:193], v[226:229], v[64:67]
	s_setprio 0
	s_barrier
	s_add_i32 s59, s95, s6
	v_lshl_add_u64 v[156:157], s[36:37], 0, v[130:131]
	s_mov_b32 m0, s59
	ds_read_b128 v[194:197], v161 offset:16384
	ds_read_b128 v[198:201], v161 offset:17408
	ds_read_b128 v[202:205], v161 offset:18432
	ds_read_b128 v[206:209], v161 offset:19456
	ds_read_b128 v[210:213], v161 offset:20480
	ds_read_b128 v[214:217], v161 offset:21504
	ds_read_b128 v[222:225], v161 offset:22528
	ds_read_b128 v[226:229], v161 offset:23552
	global_load_lds_dwordx4 v[156:157], off
	s_add_i32 m0, s59, 0x2000
	s_add_u32 s62, s36, 0x80000
	v_lshl_add_u64 v[218:219], s[36:37], 0, v[134:135]
	s_addc_u32 s63, s37, 0
	s_add_i32 s59, s33, s6
	global_load_lds_dwordx4 v[218:219], off
	s_mov_b32 m0, s59
	v_lshl_add_u64 v[232:233], s[38:39], 0, v[132:133]
	global_load_lds_dwordx4 v130, s[62:63]
	s_add_i32 m0, s59, 0x2000
	s_nop 0
	global_load_lds_dwordx4 v134, s[62:63]
	v_lshl_add_u64 v[230:231], s[38:39], 0, v[128:129]
	s_mov_b32 m0, s7
	s_nop 0
	global_load_lds_dwordx4 v[230:231], off
	s_mov_b32 m0, s17
	s_nop 0
	global_load_lds_dwordx4 v[232:233], off
	s_waitcnt vmcnt(8)
	s_waitcnt lgkmcnt(0)
	s_setprio 1
	s_waitcnt lgkmcnt(0)
	v_mfma_f32_16x16x32_bf16 v[60:63], v[162:165], v[194:197], v[60:63]
	v_mfma_f32_16x16x32_bf16 v[56:59], v[170:173], v[194:197], v[56:59]
	v_mfma_f32_16x16x32_bf16 v[60:63], v[166:169], v[198:201], v[60:63]
	v_mfma_f32_16x16x32_bf16 v[56:59], v[174:177], v[198:201], v[56:59]
	s_barrier
	v_mfma_f32_16x16x32_bf16 v[52:55], v[162:165], v[202:205], v[52:55]
	v_mfma_f32_16x16x32_bf16 v[44:47], v[170:173], v[202:205], v[44:47]
	v_mfma_f32_16x16x32_bf16 v[32:35], v[162:165], v[210:213], v[32:35]
	v_mfma_f32_16x16x32_bf16 v[24:27], v[170:173], v[210:213], v[24:27]
	v_mfma_f32_16x16x32_bf16 v[20:23], v[162:165], v[222:225], v[20:23]
	v_mfma_f32_16x16x32_bf16 v[12:15], v[170:173], v[222:225], v[12:15]
	v_mfma_f32_16x16x32_bf16 v[48:51], v[178:181], v[194:197], v[48:51]
	v_mfma_f32_16x16x32_bf16 v[40:43], v[186:189], v[194:197], v[40:43]
	v_mfma_f32_16x16x32_bf16 v[36:39], v[178:181], v[202:205], v[36:39]
	v_mfma_f32_16x16x32_bf16 v[28:31], v[186:189], v[202:205], v[28:31]
	v_mfma_f32_16x16x32_bf16 v[16:19], v[178:181], v[210:213], v[16:19]
	v_mfma_f32_16x16x32_bf16 v[8:11], v[186:189], v[210:213], v[8:11]
	v_mfma_f32_16x16x32_bf16 v[4:7], v[178:181], v[222:225], v[4:7]
	v_mfma_f32_16x16x32_bf16 v[0:3], v[186:189], v[222:225], v[0:3]
	v_mfma_f32_16x16x32_bf16 v[52:55], v[166:169], v[206:209], v[52:55]
	v_mfma_f32_16x16x32_bf16 v[44:47], v[174:177], v[206:209], v[44:47]
	v_mfma_f32_16x16x32_bf16 v[32:35], v[166:169], v[214:217], v[32:35]
	v_mfma_f32_16x16x32_bf16 v[24:27], v[174:177], v[214:217], v[24:27]
	v_mfma_f32_16x16x32_bf16 v[20:23], v[166:169], v[226:229], v[20:23]
	v_mfma_f32_16x16x32_bf16 v[12:15], v[174:177], v[226:229], v[12:15]
	v_mfma_f32_16x16x32_bf16 v[48:51], v[182:185], v[198:201], v[48:51]
	v_mfma_f32_16x16x32_bf16 v[40:43], v[190:193], v[198:201], v[40:43]
	v_mfma_f32_16x16x32_bf16 v[36:39], v[182:185], v[206:209], v[36:39]
	v_mfma_f32_16x16x32_bf16 v[28:31], v[190:193], v[206:209], v[28:31]
	v_mfma_f32_16x16x32_bf16 v[16:19], v[182:185], v[214:217], v[16:19]
	v_mfma_f32_16x16x32_bf16 v[8:11], v[190:193], v[214:217], v[8:11]
	v_mfma_f32_16x16x32_bf16 v[4:7], v[182:185], v[226:229], v[4:7]
	v_mfma_f32_16x16x32_bf16 v[0:3], v[190:193], v[226:229], v[0:3]
	s_setprio 0
	s_barrier
	v_add_u32_e32 v174, s3, v159
	v_add_u32_e32 v190, s58, v159
	ds_read_b128 v[162:165], v174
	ds_read_b128 v[166:169], v174 offset:1024
	ds_read_b128 v[170:173], v174 offset:2048
	ds_read_b128 v[174:177], v174 offset:3072
	ds_read_b128 v[178:181], v190
	ds_read_b128 v[182:185], v190 offset:1024
	ds_read_b128 v[186:189], v190 offset:2048
	ds_read_b128 v[190:193], v190 offset:3072
	s_add_u32 s38, s38, 0x80000
	s_addc_u32 s39, s39, 0
	s_mov_b32 m0, s19
	ds_read_b128 v[194:197], v161 offset:32768
	ds_read_b128 v[198:201], v161 offset:33792
	ds_read_b128 v[202:205], v161 offset:34816
	ds_read_b128 v[206:209], v161 offset:35840
	ds_read_b128 v[210:213], v161 offset:36864
	ds_read_b128 v[214:217], v161 offset:37888
	ds_read_b128 v[222:225], v161 offset:38912
	ds_read_b128 v[226:229], v161 offset:39936
	global_load_lds_dwordx4 v128, s[38:39]
	s_mov_b32 m0, s40
	s_nop 0
	global_load_lds_dwordx4 v132, s[38:39]
	s_waitcnt vmcnt(8)
	s_waitcnt lgkmcnt(0)
	s_setprio 1
	s_waitcnt lgkmcnt(0)
	v_mfma_f32_16x16x32_bf16 v[124:127], v[162:165], v[194:197], v[124:127]
	v_mfma_f32_16x16x32_bf16 v[120:123], v[170:173], v[194:197], v[120:123]
	v_mfma_f32_16x16x32_bf16 v[124:127], v[166:169], v[198:201], v[124:127]
	v_mfma_f32_16x16x32_bf16 v[120:123], v[174:177], v[198:201], v[120:123]
	s_barrier
	v_mfma_f32_16x16x32_bf16 v[116:119], v[162:165], v[202:205], v[116:119]
	v_mfma_f32_16x16x32_bf16 v[104:107], v[170:173], v[202:205], v[104:107]
	v_mfma_f32_16x16x32_bf16 v[92:95], v[162:165], v[210:213], v[92:95]
	v_mfma_f32_16x16x32_bf16 v[88:91], v[170:173], v[210:213], v[88:91]
	v_mfma_f32_16x16x32_bf16 v[84:87], v[162:165], v[222:225], v[84:87]
	v_mfma_f32_16x16x32_bf16 v[72:75], v[170:173], v[222:225], v[72:75]
	v_mfma_f32_16x16x32_bf16 v[112:115], v[178:181], v[194:197], v[112:115]
	v_mfma_f32_16x16x32_bf16 v[108:111], v[186:189], v[194:197], v[108:111]
	v_mfma_f32_16x16x32_bf16 v[100:103], v[178:181], v[202:205], v[100:103]
	v_mfma_f32_16x16x32_bf16 v[96:99], v[186:189], v[202:205], v[96:99]
	v_mfma_f32_16x16x32_bf16 v[80:83], v[178:181], v[210:213], v[80:83]
	v_mfma_f32_16x16x32_bf16 v[76:79], v[186:189], v[210:213], v[76:79]
	v_mfma_f32_16x16x32_bf16 v[68:71], v[178:181], v[222:225], v[68:71]
	v_mfma_f32_16x16x32_bf16 v[64:67], v[186:189], v[222:225], v[64:67]
	v_mfma_f32_16x16x32_bf16 v[116:119], v[166:169], v[206:209], v[116:119]
	v_mfma_f32_16x16x32_bf16 v[104:107], v[174:177], v[206:209], v[104:107]
	v_mfma_f32_16x16x32_bf16 v[92:95], v[166:169], v[214:217], v[92:95]
	v_mfma_f32_16x16x32_bf16 v[88:91], v[174:177], v[214:217], v[88:91]
	v_mfma_f32_16x16x32_bf16 v[84:87], v[166:169], v[226:229], v[84:87]
	v_mfma_f32_16x16x32_bf16 v[72:75], v[174:177], v[226:229], v[72:75]
	v_mfma_f32_16x16x32_bf16 v[112:115], v[182:185], v[198:201], v[112:115]
	v_mfma_f32_16x16x32_bf16 v[108:111], v[190:193], v[198:201], v[108:111]
	v_mfma_f32_16x16x32_bf16 v[100:103], v[182:185], v[206:209], v[100:103]
	v_mfma_f32_16x16x32_bf16 v[96:99], v[190:193], v[206:209], v[96:99]
	v_mfma_f32_16x16x32_bf16 v[80:83], v[182:185], v[214:217], v[80:83]
	v_mfma_f32_16x16x32_bf16 v[76:79], v[190:193], v[214:217], v[76:79]
	v_mfma_f32_16x16x32_bf16 v[68:71], v[182:185], v[226:229], v[68:71]
	v_mfma_f32_16x16x32_bf16 v[64:67], v[190:193], v[226:229], v[64:67]
	s_setprio 0
	s_barrier
	s_add_i32 s38, s3, s6
	v_lshl_add_u64 v[156:157], v[156:157], 0, s[12:13]
	s_mov_b32 m0, s38
	ds_read_b128 v[194:197], v161 offset:49152
	ds_read_b128 v[198:201], v161 offset:50176
	ds_read_b128 v[202:205], v161 offset:51200
	ds_read_b128 v[206:209], v161 offset:52224
	ds_read_b128 v[210:213], v161 offset:53248
	ds_read_b128 v[214:217], v161 offset:54272
	ds_read_b128 v[222:225], v161 offset:55296
	ds_read_b128 v[226:229], v161 offset:56320
	global_load_lds_dwordx4 v[156:157], off
	s_add_i32 m0, s38, 0x2000
	s_add_u32 s36, s36, 0x80080
	v_lshl_add_u64 v[156:157], v[218:219], 0, s[12:13]
	s_addc_u32 s37, s37, 0
	s_add_i32 s38, s58, s6
	global_load_lds_dwordx4 v[156:157], off
	s_mov_b32 m0, s38
	s_nop 0
	global_load_lds_dwordx4 v130, s[36:37]
	s_add_i32 m0, s38, 0x2000
	s_nop 0
	global_load_lds_dwordx4 v134, s[36:37]
	v_lshl_add_u64 v[156:157], v[230:231], 0, s[12:13]
	s_mov_b32 m0, s42
	s_nop 0
	global_load_lds_dwordx4 v[156:157], off
	v_lshl_add_u64 v[156:157], v[232:233], 0, s[12:13]
	s_mov_b32 m0, s43
	s_nop 0
	global_load_lds_dwordx4 v[156:157], off
	s_waitcnt vmcnt(8)
	s_waitcnt lgkmcnt(0)
	s_setprio 1
	s_waitcnt lgkmcnt(0)
	v_mfma_f32_16x16x32_bf16 v[60:63], v[162:165], v[194:197], v[60:63]
	v_mfma_f32_16x16x32_bf16 v[56:59], v[170:173], v[194:197], v[56:59]
	v_mfma_f32_16x16x32_bf16 v[60:63], v[166:169], v[198:201], v[60:63]
	v_mfma_f32_16x16x32_bf16 v[56:59], v[174:177], v[198:201], v[56:59]
	s_barrier
	v_mfma_f32_16x16x32_bf16 v[52:55], v[162:165], v[202:205], v[52:55]
	v_mfma_f32_16x16x32_bf16 v[44:47], v[170:173], v[202:205], v[44:47]
	v_mfma_f32_16x16x32_bf16 v[32:35], v[162:165], v[210:213], v[32:35]
	v_mfma_f32_16x16x32_bf16 v[24:27], v[170:173], v[210:213], v[24:27]
	v_mfma_f32_16x16x32_bf16 v[20:23], v[162:165], v[222:225], v[20:23]
	v_mfma_f32_16x16x32_bf16 v[12:15], v[170:173], v[222:225], v[12:15]
	v_mfma_f32_16x16x32_bf16 v[48:51], v[178:181], v[194:197], v[48:51]
	v_mfma_f32_16x16x32_bf16 v[40:43], v[186:189], v[194:197], v[40:43]
	v_mfma_f32_16x16x32_bf16 v[36:39], v[178:181], v[202:205], v[36:39]
	v_mfma_f32_16x16x32_bf16 v[28:31], v[186:189], v[202:205], v[28:31]
	v_mfma_f32_16x16x32_bf16 v[16:19], v[178:181], v[210:213], v[16:19]
	v_mfma_f32_16x16x32_bf16 v[8:11], v[186:189], v[210:213], v[8:11]
	v_mfma_f32_16x16x32_bf16 v[4:7], v[178:181], v[222:225], v[4:7]
	v_mfma_f32_16x16x32_bf16 v[0:3], v[186:189], v[222:225], v[0:3]
	v_mfma_f32_16x16x32_bf16 v[52:55], v[166:169], v[206:209], v[52:55]
	v_mfma_f32_16x16x32_bf16 v[44:47], v[174:177], v[206:209], v[44:47]
	v_mfma_f32_16x16x32_bf16 v[32:35], v[166:169], v[214:217], v[32:35]
	v_mfma_f32_16x16x32_bf16 v[24:27], v[174:177], v[214:217], v[24:27]
	v_mfma_f32_16x16x32_bf16 v[20:23], v[166:169], v[226:229], v[20:23]
	v_mfma_f32_16x16x32_bf16 v[12:15], v[174:177], v[226:229], v[12:15]
	v_mfma_f32_16x16x32_bf16 v[48:51], v[182:185], v[198:201], v[48:51]
	v_mfma_f32_16x16x32_bf16 v[40:43], v[190:193], v[198:201], v[40:43]
	v_mfma_f32_16x16x32_bf16 v[36:39], v[182:185], v[206:209], v[36:39]
	v_mfma_f32_16x16x32_bf16 v[28:31], v[190:193], v[206:209], v[28:31]
	v_mfma_f32_16x16x32_bf16 v[16:19], v[182:185], v[214:217], v[16:19]
	v_mfma_f32_16x16x32_bf16 v[8:11], v[190:193], v[214:217], v[8:11]
	v_mfma_f32_16x16x32_bf16 v[4:7], v[182:185], v[226:229], v[4:7]
	v_mfma_f32_16x16x32_bf16 v[0:3], v[190:193], v[226:229], v[0:3]
	s_setprio 0
	s_barrier
	s_add_i32 s57, s57, 2
	s_add_u32 s34, s34, 0x100
	s_addc_u32 s35, s35, 0
	s_add_u32 s55, s55, 0x100
	s_addc_u32 s56, s56, 0
	s_cmp_gt_u32 s57, 29
	s_cbranch_scc1 .LBB0_1389

.LBB0_1404:
	v_add_u32_e32 v153, s95, v161
	ds_read_b128 v[156:159], v153
	ds_read_b128 v[164:167], v153 offset:1024
	ds_read_b128 v[168:171], v153 offset:2048
	ds_read_b128 v[172:175], v153 offset:3072
	v_add_u32_e32 v153, s33, v161
	ds_read_b128 v[176:179], v153
	ds_read_b128 v[180:183], v153 offset:1024
	ds_read_b128 v[184:187], v153 offset:2048
	ds_read_b128 v[188:191], v153 offset:3072
	s_add_u32 s36, s30, 0xfff80080
	s_addc_u32 s37, s31, -1
	s_and_b64 s[34:35], s[34:35], exec
	s_cselect_b32 s37, s25, s37
	s_cselect_b32 s36, s49, s36
	s_cselect_b32 s35, s23, s53
	s_cselect_b32 s34, s50, s51
	s_add_i32 m0, s21, 0xc000
	ds_read_b128 v[192:195], v163
	ds_read_b128 v[196:199], v163 offset:1024
	ds_read_b128 v[200:203], v163 offset:2048
	ds_read_b128 v[204:207], v163 offset:3072
	ds_read_b128 v[208:211], v163 offset:4096
	ds_read_b128 v[212:215], v163 offset:5120
	ds_read_b128 v[216:219], v163 offset:6144
	ds_read_b128 v[222:225], v163 offset:7168
	global_load_lds_dwordx4 v136, s[30:31]
	s_add_i32 m0, s21, 0xe000
	s_nop 0
	global_load_lds_dwordx4 v138, s[30:31]
	s_waitcnt vmcnt(8)
	s_waitcnt lgkmcnt(0)
	s_setprio 1
	s_waitcnt lgkmcnt(0)
	v_mfma_f32_16x16x32_bf16 v[124:127], v[156:159], v[192:195], v[124:127]
	v_mfma_f32_16x16x32_bf16 v[120:123], v[168:171], v[192:195], v[120:123]
	v_mfma_f32_16x16x32_bf16 v[124:127], v[164:167], v[196:199], v[124:127]
	v_mfma_f32_16x16x32_bf16 v[120:123], v[172:175], v[196:199], v[120:123]
	s_barrier
	v_mfma_f32_16x16x32_bf16 v[108:111], v[156:159], v[200:203], v[108:111]
	v_mfma_f32_16x16x32_bf16 v[104:107], v[168:171], v[200:203], v[104:107]
	v_mfma_f32_16x16x32_bf16 v[92:95], v[156:159], v[208:211], v[92:95]
	v_mfma_f32_16x16x32_bf16 v[88:91], v[168:171], v[208:211], v[88:91]
	v_mfma_f32_16x16x32_bf16 v[76:79], v[156:159], v[216:219], v[76:79]
	v_mfma_f32_16x16x32_bf16 v[72:75], v[168:171], v[216:219], v[72:75]
	v_mfma_f32_16x16x32_bf16 v[116:119], v[176:179], v[192:195], v[116:119]
	v_mfma_f32_16x16x32_bf16 v[112:115], v[184:187], v[192:195], v[112:115]
	v_mfma_f32_16x16x32_bf16 v[100:103], v[176:179], v[200:203], v[100:103]
	v_mfma_f32_16x16x32_bf16 v[96:99], v[184:187], v[200:203], v[96:99]
	v_mfma_f32_16x16x32_bf16 v[84:87], v[176:179], v[208:211], v[84:87]
	v_mfma_f32_16x16x32_bf16 v[80:83], v[184:187], v[208:211], v[80:83]
	v_mfma_f32_16x16x32_bf16 v[68:71], v[176:179], v[216:219], v[68:71]
	v_mfma_f32_16x16x32_bf16 v[64:67], v[184:187], v[216:219], v[64:67]
	v_mfma_f32_16x16x32_bf16 v[108:111], v[164:167], v[204:207], v[108:111]
	v_mfma_f32_16x16x32_bf16 v[104:107], v[172:175], v[204:207], v[104:107]
	v_mfma_f32_16x16x32_bf16 v[92:95], v[164:167], v[212:215], v[92:95]
	v_mfma_f32_16x16x32_bf16 v[88:91], v[172:175], v[212:215], v[88:91]
	v_mfma_f32_16x16x32_bf16 v[76:79], v[164:167], v[222:225], v[76:79]
	v_mfma_f32_16x16x32_bf16 v[72:75], v[172:175], v[222:225], v[72:75]
	v_mfma_f32_16x16x32_bf16 v[116:119], v[180:183], v[196:199], v[116:119]
	v_mfma_f32_16x16x32_bf16 v[112:115], v[188:191], v[196:199], v[112:115]
	v_mfma_f32_16x16x32_bf16 v[100:103], v[180:183], v[204:207], v[100:103]
	v_mfma_f32_16x16x32_bf16 v[96:99], v[188:191], v[204:207], v[96:99]
	v_mfma_f32_16x16x32_bf16 v[84:87], v[180:183], v[212:215], v[84:87]
	v_mfma_f32_16x16x32_bf16 v[80:83], v[188:191], v[212:215], v[80:83]
	v_mfma_f32_16x16x32_bf16 v[68:71], v[180:183], v[222:225], v[68:71]
	v_mfma_f32_16x16x32_bf16 v[64:67], v[188:191], v[222:225], v[64:67]
	s_setprio 0
	s_barrier
	s_add_i32 s55, s95, s7
	v_lshl_add_u64 v[226:227], s[34:35], 0, v[132:133]
	s_mov_b32 m0, s55
	ds_read_b128 v[192:195], v163 offset:16384
	ds_read_b128 v[196:199], v163 offset:17408
	ds_read_b128 v[200:203], v163 offset:18432
	ds_read_b128 v[204:207], v163 offset:19456
	ds_read_b128 v[208:211], v163 offset:20480
	ds_read_b128 v[212:215], v163 offset:21504
	ds_read_b128 v[216:219], v163 offset:22528
	ds_read_b128 v[222:225], v163 offset:23552
	global_load_lds_dwordx4 v[226:227], off
	s_add_i32 m0, s55, 0x2000
	s_add_u32 s56, s34, 0x80000
	v_lshl_add_u64 v[228:229], s[34:35], 0, v[128:129]
	s_addc_u32 s57, s35, 0
	s_add_i32 s55, s33, s7
	global_load_lds_dwordx4 v[228:229], off
	s_mov_b32 m0, s55
	v_lshl_add_u64 v[232:233], s[36:37], 0, v[130:131]
	global_load_lds_dwordx4 v132, s[56:57]
	s_add_i32 m0, s55, 0x2000
	s_nop 0
	global_load_lds_dwordx4 v128, s[56:57]
	v_lshl_add_u64 v[230:231], s[36:37], 0, v[134:135]
	s_mov_b32 m0, s21
	s_nop 0
	global_load_lds_dwordx4 v[230:231], off
	s_mov_b32 m0, s38
	s_nop 0
	global_load_lds_dwordx4 v[232:233], off
	s_waitcnt vmcnt(8)
	s_waitcnt lgkmcnt(0)
	s_setprio 1
	s_waitcnt lgkmcnt(0)
	v_mfma_f32_16x16x32_bf16 v[60:63], v[156:159], v[192:195], v[60:63]
	v_mfma_f32_16x16x32_bf16 v[56:59], v[168:171], v[192:195], v[56:59]
	v_mfma_f32_16x16x32_bf16 v[60:63], v[164:167], v[196:199], v[60:63]
	v_mfma_f32_16x16x32_bf16 v[56:59], v[172:175], v[196:199], v[56:59]
	s_barrier
	v_mfma_f32_16x16x32_bf16 v[44:47], v[156:159], v[200:203], v[44:47]
	v_mfma_f32_16x16x32_bf16 v[40:43], v[168:171], v[200:203], v[40:43]
	v_mfma_f32_16x16x32_bf16 v[28:31], v[156:159], v[208:211], v[28:31]
	v_mfma_f32_16x16x32_bf16 v[24:27], v[168:171], v[208:211], v[24:27]
	v_mfma_f32_16x16x32_bf16 v[12:15], v[156:159], v[216:219], v[12:15]
	v_mfma_f32_16x16x32_bf16 v[8:11], v[168:171], v[216:219], v[8:11]
	v_mfma_f32_16x16x32_bf16 v[52:55], v[176:179], v[192:195], v[52:55]
	v_mfma_f32_16x16x32_bf16 v[48:51], v[184:187], v[192:195], v[48:51]
	v_mfma_f32_16x16x32_bf16 v[36:39], v[176:179], v[200:203], v[36:39]
	v_mfma_f32_16x16x32_bf16 v[32:35], v[184:187], v[200:203], v[32:35]
	v_mfma_f32_16x16x32_bf16 v[20:23], v[176:179], v[208:211], v[20:23]
	v_mfma_f32_16x16x32_bf16 v[16:19], v[184:187], v[208:211], v[16:19]
	v_mfma_f32_16x16x32_bf16 v[4:7], v[176:179], v[216:219], v[4:7]
	v_mfma_f32_16x16x32_bf16 v[0:3], v[184:187], v[216:219], v[0:3]
	v_mfma_f32_16x16x32_bf16 v[44:47], v[164:167], v[204:207], v[44:47]
	v_mfma_f32_16x16x32_bf16 v[40:43], v[172:175], v[204:207], v[40:43]
	v_mfma_f32_16x16x32_bf16 v[28:31], v[164:167], v[212:215], v[28:31]
	v_mfma_f32_16x16x32_bf16 v[24:27], v[172:175], v[212:215], v[24:27]
	v_mfma_f32_16x16x32_bf16 v[12:15], v[164:167], v[222:225], v[12:15]
	v_mfma_f32_16x16x32_bf16 v[8:11], v[172:175], v[222:225], v[8:11]
	v_mfma_f32_16x16x32_bf16 v[52:55], v[180:183], v[196:199], v[52:55]
	v_mfma_f32_16x16x32_bf16 v[48:51], v[188:191], v[196:199], v[48:51]
	v_mfma_f32_16x16x32_bf16 v[36:39], v[180:183], v[204:207], v[36:39]
	v_mfma_f32_16x16x32_bf16 v[32:35], v[188:191], v[204:207], v[32:35]
	v_mfma_f32_16x16x32_bf16 v[20:23], v[180:183], v[212:215], v[20:23]
	v_mfma_f32_16x16x32_bf16 v[16:19], v[188:191], v[212:215], v[16:19]
	v_mfma_f32_16x16x32_bf16 v[4:7], v[180:183], v[222:225], v[4:7]
	v_mfma_f32_16x16x32_bf16 v[0:3], v[188:191], v[222:225], v[0:3]
	s_setprio 0
	s_barrier
	v_add_u32_e32 v153, s3, v161
	ds_read_b128 v[156:159], v153
	ds_read_b128 v[164:167], v153 offset:1024
	ds_read_b128 v[168:171], v153 offset:2048
	ds_read_b128 v[172:175], v153 offset:3072
	v_add_u32_e32 v153, s58, v161
	ds_read_b128 v[176:179], v153
	ds_read_b128 v[180:183], v153 offset:1024
	ds_read_b128 v[184:187], v153 offset:2048
	ds_read_b128 v[188:191], v153 offset:3072
	s_add_u32 s36, s36, 0x80000
	s_addc_u32 s37, s37, 0
	s_mov_b32 m0, s39
	ds_read_b128 v[192:195], v163 offset:32768
	ds_read_b128 v[196:199], v163 offset:33792
	ds_read_b128 v[200:203], v163 offset:34816
	ds_read_b128 v[204:207], v163 offset:35840
	ds_read_b128 v[208:211], v163 offset:36864
	ds_read_b128 v[212:215], v163 offset:37888
	ds_read_b128 v[216:219], v163 offset:38912
	ds_read_b128 v[222:225], v163 offset:39936
	global_load_lds_dwordx4 v134, s[36:37]
	s_mov_b32 m0, s40
	s_nop 0
	global_load_lds_dwordx4 v130, s[36:37]
	s_waitcnt vmcnt(8)
	s_waitcnt lgkmcnt(0)
	s_setprio 1
	s_waitcnt lgkmcnt(0)
	v_mfma_f32_16x16x32_bf16 v[124:127], v[156:159], v[192:195], v[124:127]
	v_mfma_f32_16x16x32_bf16 v[120:123], v[168:171], v[192:195], v[120:123]
	v_mfma_f32_16x16x32_bf16 v[124:127], v[164:167], v[196:199], v[124:127]
	v_mfma_f32_16x16x32_bf16 v[120:123], v[172:175], v[196:199], v[120:123]
	s_barrier
	v_mfma_f32_16x16x32_bf16 v[108:111], v[156:159], v[200:203], v[108:111]
	v_mfma_f32_16x16x32_bf16 v[104:107], v[168:171], v[200:203], v[104:107]
	v_mfma_f32_16x16x32_bf16 v[92:95], v[156:159], v[208:211], v[92:95]
	v_mfma_f32_16x16x32_bf16 v[88:91], v[168:171], v[208:211], v[88:91]
	v_mfma_f32_16x16x32_bf16 v[76:79], v[156:159], v[216:219], v[76:79]
	v_mfma_f32_16x16x32_bf16 v[72:75], v[168:171], v[216:219], v[72:75]
	v_mfma_f32_16x16x32_bf16 v[116:119], v[176:179], v[192:195], v[116:119]
	v_mfma_f32_16x16x32_bf16 v[112:115], v[184:187], v[192:195], v[112:115]
	v_mfma_f32_16x16x32_bf16 v[100:103], v[176:179], v[200:203], v[100:103]
	v_mfma_f32_16x16x32_bf16 v[96:99], v[184:187], v[200:203], v[96:99]
	v_mfma_f32_16x16x32_bf16 v[84:87], v[176:179], v[208:211], v[84:87]
	v_mfma_f32_16x16x32_bf16 v[80:83], v[184:187], v[208:211], v[80:83]
	v_mfma_f32_16x16x32_bf16 v[68:71], v[176:179], v[216:219], v[68:71]
	v_mfma_f32_16x16x32_bf16 v[64:67], v[184:187], v[216:219], v[64:67]
	v_mfma_f32_16x16x32_bf16 v[108:111], v[164:167], v[204:207], v[108:111]
	v_mfma_f32_16x16x32_bf16 v[104:107], v[172:175], v[204:207], v[104:107]
	v_mfma_f32_16x16x32_bf16 v[92:95], v[164:167], v[212:215], v[92:95]
	v_mfma_f32_16x16x32_bf16 v[88:91], v[172:175], v[212:215], v[88:91]
	v_mfma_f32_16x16x32_bf16 v[76:79], v[164:167], v[222:225], v[76:79]
	v_mfma_f32_16x16x32_bf16 v[72:75], v[172:175], v[222:225], v[72:75]
	v_mfma_f32_16x16x32_bf16 v[116:119], v[180:183], v[196:199], v[116:119]
	v_mfma_f32_16x16x32_bf16 v[112:115], v[188:191], v[196:199], v[112:115]
	v_mfma_f32_16x16x32_bf16 v[100:103], v[180:183], v[204:207], v[100:103]
	v_mfma_f32_16x16x32_bf16 v[96:99], v[188:191], v[204:207], v[96:99]
	v_mfma_f32_16x16x32_bf16 v[84:87], v[180:183], v[212:215], v[84:87]
	v_mfma_f32_16x16x32_bf16 v[80:83], v[188:191], v[212:215], v[80:83]
	v_mfma_f32_16x16x32_bf16 v[68:71], v[180:183], v[222:225], v[68:71]
	v_mfma_f32_16x16x32_bf16 v[64:67], v[188:191], v[222:225], v[64:67]
	s_setprio 0
	s_barrier
	s_add_i32 s36, s3, s7
	v_lshl_add_u64 v[226:227], v[226:227], 0, s[12:13]
	s_mov_b32 m0, s36
	ds_read_b128 v[192:195], v163 offset:49152
	ds_read_b128 v[196:199], v163 offset:50176
	ds_read_b128 v[200:203], v163 offset:51200
	ds_read_b128 v[204:207], v163 offset:52224
	ds_read_b128 v[208:211], v163 offset:53248
	ds_read_b128 v[212:215], v163 offset:54272
	ds_read_b128 v[216:219], v163 offset:55296
	ds_read_b128 v[222:225], v163 offset:56320
	global_load_lds_dwordx4 v[226:227], off
	s_add_i32 m0, s36, 0x2000
	s_add_u32 s34, s34, 0x80080
	v_lshl_add_u64 v[226:227], v[228:229], 0, s[12:13]
	s_addc_u32 s35, s35, 0
	s_add_i32 s36, s58, s7
	global_load_lds_dwordx4 v[226:227], off
	s_mov_b32 m0, s36
	s_nop 0
	global_load_lds_dwordx4 v132, s[34:35]
	s_add_i32 m0, s36, 0x2000
	s_nop 0
	global_load_lds_dwordx4 v128, s[34:35]
	v_lshl_add_u64 v[226:227], v[230:231], 0, s[12:13]
	s_mov_b32 m0, s42
	s_nop 0
	global_load_lds_dwordx4 v[226:227], off
	v_lshl_add_u64 v[226:227], v[232:233], 0, s[12:13]
	s_mov_b32 m0, s43
	s_nop 0
	global_load_lds_dwordx4 v[226:227], off
	s_waitcnt vmcnt(8)
	s_waitcnt lgkmcnt(0)
	s_setprio 1
	s_waitcnt lgkmcnt(0)
	v_mfma_f32_16x16x32_bf16 v[60:63], v[156:159], v[192:195], v[60:63]
	v_mfma_f32_16x16x32_bf16 v[56:59], v[168:171], v[192:195], v[56:59]
	v_mfma_f32_16x16x32_bf16 v[60:63], v[164:167], v[196:199], v[60:63]
	v_mfma_f32_16x16x32_bf16 v[56:59], v[172:175], v[196:199], v[56:59]
	s_barrier
	v_mfma_f32_16x16x32_bf16 v[44:47], v[156:159], v[200:203], v[44:47]
	v_mfma_f32_16x16x32_bf16 v[40:43], v[168:171], v[200:203], v[40:43]
	v_mfma_f32_16x16x32_bf16 v[28:31], v[156:159], v[208:211], v[28:31]
	v_mfma_f32_16x16x32_bf16 v[24:27], v[168:171], v[208:211], v[24:27]
	v_mfma_f32_16x16x32_bf16 v[12:15], v[156:159], v[216:219], v[12:15]
	v_mfma_f32_16x16x32_bf16 v[8:11], v[168:171], v[216:219], v[8:11]
	v_mfma_f32_16x16x32_bf16 v[52:55], v[176:179], v[192:195], v[52:55]
	v_mfma_f32_16x16x32_bf16 v[48:51], v[184:187], v[192:195], v[48:51]
	v_mfma_f32_16x16x32_bf16 v[36:39], v[176:179], v[200:203], v[36:39]
	v_mfma_f32_16x16x32_bf16 v[32:35], v[184:187], v[200:203], v[32:35]
	v_mfma_f32_16x16x32_bf16 v[20:23], v[176:179], v[208:211], v[20:23]
	v_mfma_f32_16x16x32_bf16 v[16:19], v[184:187], v[208:211], v[16:19]
	v_mfma_f32_16x16x32_bf16 v[4:7], v[176:179], v[216:219], v[4:7]
	v_mfma_f32_16x16x32_bf16 v[0:3], v[184:187], v[216:219], v[0:3]
	v_mfma_f32_16x16x32_bf16 v[44:47], v[164:167], v[204:207], v[44:47]
	v_mfma_f32_16x16x32_bf16 v[40:43], v[172:175], v[204:207], v[40:43]
	v_mfma_f32_16x16x32_bf16 v[28:31], v[164:167], v[212:215], v[28:31]
	v_mfma_f32_16x16x32_bf16 v[24:27], v[172:175], v[212:215], v[24:27]
	v_mfma_f32_16x16x32_bf16 v[12:15], v[164:167], v[222:225], v[12:15]
	v_mfma_f32_16x16x32_bf16 v[8:11], v[172:175], v[222:225], v[8:11]
	v_mfma_f32_16x16x32_bf16 v[52:55], v[180:183], v[196:199], v[52:55]
	v_mfma_f32_16x16x32_bf16 v[48:51], v[188:191], v[196:199], v[48:51]
	v_mfma_f32_16x16x32_bf16 v[36:39], v[180:183], v[204:207], v[36:39]
	v_mfma_f32_16x16x32_bf16 v[32:35], v[188:191], v[204:207], v[32:35]
	v_mfma_f32_16x16x32_bf16 v[20:23], v[180:183], v[212:215], v[20:23]
	v_mfma_f32_16x16x32_bf16 v[16:19], v[188:191], v[212:215], v[16:19]
	v_mfma_f32_16x16x32_bf16 v[4:7], v[180:183], v[222:225], v[4:7]
	v_mfma_f32_16x16x32_bf16 v[0:3], v[188:191], v[222:225], v[0:3]
	s_setprio 0
	s_barrier
	s_add_i32 s54, s54, 2
	s_add_u32 s30, s30, 0x100
	s_addc_u32 s31, s31, 0
	s_add_u32 s51, s51, 0x100
	s_addc_u32 s53, s53, 0
	s_cmp_gt_u32 s54, 29
	s_cbranch_scc1 .LBB0_1407

.LBB0_1555:
	ds_read_b128 v[144:147], v151
	ds_read_b128 v[156:159], v151 offset:1024
	ds_read_b128 v[160:163], v151 offset:2048
	ds_read_b128 v[164:167], v151 offset:3072
	ds_read_b128 v[168:171], v152
	ds_read_b128 v[172:175], v152 offset:1024
	ds_read_b128 v[176:179], v152 offset:2048
	ds_read_b128 v[180:183], v152 offset:3072
	s_add_u32 s22, s20, 0x100
	s_addc_u32 s23, s21, 0
	s_cmpk_eq_i32 s48, 0x54
	s_cselect_b32 s27, s1, s23
	s_cselect_b32 s26, s0, s22
	s_cselect_b32 s25, s19, s47
	s_cselect_b32 s24, s18, s46
	v_lshl_add_u64 v[216:217], s[20:21], 0, v[136:137]
	s_add_i32 m0, s28, 0xc000
	ds_read_b128 v[184:187], v153
	ds_read_b128 v[188:191], v153 offset:1024
	ds_read_b128 v[192:195], v153 offset:2048
	ds_read_b128 v[196:199], v153 offset:3072
	ds_read_b128 v[200:203], v153 offset:4096
	ds_read_b128 v[204:207], v153 offset:5120
	ds_read_b128 v[208:211], v153 offset:6144
	ds_read_b128 v[212:215], v153 offset:7168
	global_load_lds_dwordx4 v[216:217], off
	v_lshl_add_u64 v[216:217], s[20:21], 0, v[138:139]
	s_add_i32 m0, s28, 0xe000
	s_nop 0
	global_load_lds_dwordx4 v[216:217], off
	s_waitcnt vmcnt(8)
	s_waitcnt lgkmcnt(0)
	s_setprio 1
	s_waitcnt lgkmcnt(0)
	v_mfma_f32_16x16x32_bf16 v[124:127], v[144:147], v[184:187], v[124:127]
	v_mfma_f32_16x16x32_bf16 v[120:123], v[160:163], v[184:187], v[120:123]
	v_mfma_f32_16x16x32_bf16 v[124:127], v[156:159], v[188:191], v[124:127]
	v_mfma_f32_16x16x32_bf16 v[120:123], v[164:167], v[188:191], v[120:123]
	s_barrier
	v_mfma_f32_16x16x32_bf16 v[108:111], v[144:147], v[192:195], v[108:111]
	v_mfma_f32_16x16x32_bf16 v[104:107], v[160:163], v[192:195], v[104:107]
	v_mfma_f32_16x16x32_bf16 v[92:95], v[144:147], v[200:203], v[92:95]
	v_mfma_f32_16x16x32_bf16 v[88:91], v[160:163], v[200:203], v[88:91]
	v_mfma_f32_16x16x32_bf16 v[76:79], v[144:147], v[208:211], v[76:79]
	v_mfma_f32_16x16x32_bf16 v[72:75], v[160:163], v[208:211], v[72:75]
	v_mfma_f32_16x16x32_bf16 v[116:119], v[168:171], v[184:187], v[116:119]
	v_mfma_f32_16x16x32_bf16 v[112:115], v[176:179], v[184:187], v[112:115]
	v_mfma_f32_16x16x32_bf16 v[100:103], v[168:171], v[192:195], v[100:103]
	v_mfma_f32_16x16x32_bf16 v[96:99], v[176:179], v[192:195], v[96:99]
	v_mfma_f32_16x16x32_bf16 v[84:87], v[168:171], v[200:203], v[84:87]
	v_mfma_f32_16x16x32_bf16 v[80:83], v[176:179], v[200:203], v[80:83]
	v_mfma_f32_16x16x32_bf16 v[68:71], v[168:171], v[208:211], v[68:71]
	v_mfma_f32_16x16x32_bf16 v[64:67], v[176:179], v[208:211], v[64:67]
	v_mfma_f32_16x16x32_bf16 v[108:111], v[156:159], v[196:199], v[108:111]
	v_mfma_f32_16x16x32_bf16 v[104:107], v[164:167], v[196:199], v[104:107]
	v_mfma_f32_16x16x32_bf16 v[92:95], v[156:159], v[204:207], v[92:95]
	v_mfma_f32_16x16x32_bf16 v[88:91], v[164:167], v[204:207], v[88:91]
	v_mfma_f32_16x16x32_bf16 v[76:79], v[156:159], v[212:215], v[76:79]
	v_mfma_f32_16x16x32_bf16 v[72:75], v[164:167], v[212:215], v[72:75]
	v_mfma_f32_16x16x32_bf16 v[116:119], v[172:175], v[188:191], v[116:119]
	v_mfma_f32_16x16x32_bf16 v[112:115], v[180:183], v[188:191], v[112:115]
	v_mfma_f32_16x16x32_bf16 v[100:103], v[172:175], v[196:199], v[100:103]
	v_mfma_f32_16x16x32_bf16 v[96:99], v[180:183], v[196:199], v[96:99]
	v_mfma_f32_16x16x32_bf16 v[84:87], v[172:175], v[204:207], v[84:87]
	v_mfma_f32_16x16x32_bf16 v[80:83], v[180:183], v[204:207], v[80:83]
	v_mfma_f32_16x16x32_bf16 v[68:71], v[172:175], v[212:215], v[68:71]
	v_mfma_f32_16x16x32_bf16 v[64:67], v[180:183], v[212:215], v[64:67]
	s_setprio 0
	s_barrier
	s_add_i32 s20, s95, s7
	v_lshl_add_u64 v[216:217], s[24:25], 0, v[130:131]
	s_mov_b32 m0, s20
	ds_read_b128 v[184:187], v153 offset:16384
	ds_read_b128 v[188:191], v153 offset:17408
	ds_read_b128 v[192:195], v153 offset:18432
	ds_read_b128 v[196:199], v153 offset:19456
	ds_read_b128 v[200:203], v153 offset:20480
	ds_read_b128 v[204:207], v153 offset:21504
	ds_read_b128 v[208:211], v153 offset:22528
	ds_read_b128 v[212:215], v153 offset:23552
	global_load_lds_dwordx4 v[216:217], off
	s_add_i32 m0, s20, 0x2000
	s_add_u32 s20, s24, 0x160000
	v_lshl_add_u64 v[218:219], s[24:25], 0, v[134:135]
	s_addc_u32 s21, s25, 0
	s_add_i32 s49, s33, s7
	global_load_lds_dwordx4 v[218:219], off
	s_mov_b32 m0, s49
	v_lshl_add_u64 v[224:225], s[26:27], 0, v[132:133]
	global_load_lds_dwordx4 v130, s[20:21]
	s_add_i32 m0, s49, 0x2000
	s_nop 0
	global_load_lds_dwordx4 v134, s[20:21]
	v_lshl_add_u64 v[222:223], s[26:27], 0, v[128:129]
	s_mov_b32 m0, s28
	s_nop 0
	global_load_lds_dwordx4 v[222:223], off
	s_mov_b32 m0, s29
	s_nop 0
	global_load_lds_dwordx4 v[224:225], off
	s_waitcnt vmcnt(8)
	s_waitcnt lgkmcnt(0)
	s_setprio 1
	s_waitcnt lgkmcnt(0)
	v_mfma_f32_16x16x32_bf16 v[60:63], v[144:147], v[184:187], v[60:63]
	v_mfma_f32_16x16x32_bf16 v[56:59], v[160:163], v[184:187], v[56:59]
	v_mfma_f32_16x16x32_bf16 v[60:63], v[156:159], v[188:191], v[60:63]
	v_mfma_f32_16x16x32_bf16 v[56:59], v[164:167], v[188:191], v[56:59]
	s_barrier
	v_mfma_f32_16x16x32_bf16 v[44:47], v[144:147], v[192:195], v[44:47]
	v_mfma_f32_16x16x32_bf16 v[40:43], v[160:163], v[192:195], v[40:43]
	v_mfma_f32_16x16x32_bf16 v[28:31], v[144:147], v[200:203], v[28:31]
	v_mfma_f32_16x16x32_bf16 v[24:27], v[160:163], v[200:203], v[24:27]
	v_mfma_f32_16x16x32_bf16 v[12:15], v[144:147], v[208:211], v[12:15]
	v_mfma_f32_16x16x32_bf16 v[8:11], v[160:163], v[208:211], v[8:11]
	v_mfma_f32_16x16x32_bf16 v[52:55], v[168:171], v[184:187], v[52:55]
	v_mfma_f32_16x16x32_bf16 v[48:51], v[176:179], v[184:187], v[48:51]
	v_mfma_f32_16x16x32_bf16 v[36:39], v[168:171], v[192:195], v[36:39]
	v_mfma_f32_16x16x32_bf16 v[32:35], v[176:179], v[192:195], v[32:35]
	v_mfma_f32_16x16x32_bf16 v[20:23], v[168:171], v[200:203], v[20:23]
	v_mfma_f32_16x16x32_bf16 v[16:19], v[176:179], v[200:203], v[16:19]
	v_mfma_f32_16x16x32_bf16 v[4:7], v[168:171], v[208:211], v[4:7]
	v_mfma_f32_16x16x32_bf16 v[0:3], v[176:179], v[208:211], v[0:3]
	v_mfma_f32_16x16x32_bf16 v[44:47], v[156:159], v[196:199], v[44:47]
	v_mfma_f32_16x16x32_bf16 v[40:43], v[164:167], v[196:199], v[40:43]
	v_mfma_f32_16x16x32_bf16 v[28:31], v[156:159], v[204:207], v[28:31]
	v_mfma_f32_16x16x32_bf16 v[24:27], v[164:167], v[204:207], v[24:27]
	v_mfma_f32_16x16x32_bf16 v[12:15], v[156:159], v[212:215], v[12:15]
	v_mfma_f32_16x16x32_bf16 v[8:11], v[164:167], v[212:215], v[8:11]
	v_mfma_f32_16x16x32_bf16 v[52:55], v[172:175], v[188:191], v[52:55]
	v_mfma_f32_16x16x32_bf16 v[48:51], v[180:183], v[188:191], v[48:51]
	v_mfma_f32_16x16x32_bf16 v[36:39], v[172:175], v[196:199], v[36:39]
	v_mfma_f32_16x16x32_bf16 v[32:35], v[180:183], v[196:199], v[32:35]
	v_mfma_f32_16x16x32_bf16 v[20:23], v[172:175], v[204:207], v[20:23]
	v_mfma_f32_16x16x32_bf16 v[16:19], v[180:183], v[204:207], v[16:19]
	v_mfma_f32_16x16x32_bf16 v[4:7], v[172:175], v[212:215], v[4:7]
	v_mfma_f32_16x16x32_bf16 v[0:3], v[180:183], v[212:215], v[0:3]
	s_setprio 0
	s_barrier
	v_add_u32_e32 v155, s3, v149
	ds_read_b128 v[144:147], v155
	ds_read_b128 v[156:159], v155 offset:1024
	ds_read_b128 v[160:163], v155 offset:2048
	ds_read_b128 v[164:167], v155 offset:3072
	v_add_u32_e32 v155, s58, v149
	ds_read_b128 v[168:171], v155
	ds_read_b128 v[172:175], v155 offset:1024
	ds_read_b128 v[176:179], v155 offset:2048
	ds_read_b128 v[180:183], v155 offset:3072
	s_add_u32 s20, s26, 0x160000
	s_addc_u32 s21, s27, 0
	s_mov_b32 m0, s30
	ds_read_b128 v[184:187], v153 offset:32768
	ds_read_b128 v[188:191], v153 offset:33792
	ds_read_b128 v[192:195], v153 offset:34816
	ds_read_b128 v[196:199], v153 offset:35840
	ds_read_b128 v[200:203], v153 offset:36864
	ds_read_b128 v[204:207], v153 offset:37888
	ds_read_b128 v[208:211], v153 offset:38912
	ds_read_b128 v[212:215], v153 offset:39936
	global_load_lds_dwordx4 v128, s[20:21]
	s_mov_b32 m0, s31
	s_nop 0
	global_load_lds_dwordx4 v132, s[20:21]
	s_waitcnt vmcnt(8)
	s_waitcnt lgkmcnt(0)
	s_setprio 1
	s_waitcnt lgkmcnt(0)
	v_mfma_f32_16x16x32_bf16 v[124:127], v[144:147], v[184:187], v[124:127]
	v_mfma_f32_16x16x32_bf16 v[120:123], v[160:163], v[184:187], v[120:123]
	v_mfma_f32_16x16x32_bf16 v[124:127], v[156:159], v[188:191], v[124:127]
	v_mfma_f32_16x16x32_bf16 v[120:123], v[164:167], v[188:191], v[120:123]
	s_barrier
	v_mfma_f32_16x16x32_bf16 v[108:111], v[144:147], v[192:195], v[108:111]
	v_mfma_f32_16x16x32_bf16 v[104:107], v[160:163], v[192:195], v[104:107]
	v_mfma_f32_16x16x32_bf16 v[92:95], v[144:147], v[200:203], v[92:95]
	v_mfma_f32_16x16x32_bf16 v[88:91], v[160:163], v[200:203], v[88:91]
	v_mfma_f32_16x16x32_bf16 v[76:79], v[144:147], v[208:211], v[76:79]
	v_mfma_f32_16x16x32_bf16 v[72:75], v[160:163], v[208:211], v[72:75]
	v_mfma_f32_16x16x32_bf16 v[116:119], v[168:171], v[184:187], v[116:119]
	v_mfma_f32_16x16x32_bf16 v[112:115], v[176:179], v[184:187], v[112:115]
	v_mfma_f32_16x16x32_bf16 v[100:103], v[168:171], v[192:195], v[100:103]
	v_mfma_f32_16x16x32_bf16 v[96:99], v[176:179], v[192:195], v[96:99]
	v_mfma_f32_16x16x32_bf16 v[84:87], v[168:171], v[200:203], v[84:87]
	v_mfma_f32_16x16x32_bf16 v[80:83], v[176:179], v[200:203], v[80:83]
	v_mfma_f32_16x16x32_bf16 v[68:71], v[168:171], v[208:211], v[68:71]
	v_mfma_f32_16x16x32_bf16 v[64:67], v[176:179], v[208:211], v[64:67]
	v_mfma_f32_16x16x32_bf16 v[108:111], v[156:159], v[196:199], v[108:111]
	v_mfma_f32_16x16x32_bf16 v[104:107], v[164:167], v[196:199], v[104:107]
	v_mfma_f32_16x16x32_bf16 v[92:95], v[156:159], v[204:207], v[92:95]
	v_mfma_f32_16x16x32_bf16 v[88:91], v[164:167], v[204:207], v[88:91]
	v_mfma_f32_16x16x32_bf16 v[76:79], v[156:159], v[212:215], v[76:79]
	v_mfma_f32_16x16x32_bf16 v[72:75], v[164:167], v[212:215], v[72:75]
	v_mfma_f32_16x16x32_bf16 v[116:119], v[172:175], v[188:191], v[116:119]
	v_mfma_f32_16x16x32_bf16 v[112:115], v[180:183], v[188:191], v[112:115]
	v_mfma_f32_16x16x32_bf16 v[100:103], v[172:175], v[196:199], v[100:103]
	v_mfma_f32_16x16x32_bf16 v[96:99], v[180:183], v[196:199], v[96:99]
	v_mfma_f32_16x16x32_bf16 v[84:87], v[172:175], v[204:207], v[84:87]
	v_mfma_f32_16x16x32_bf16 v[80:83], v[180:183], v[204:207], v[80:83]
	v_mfma_f32_16x16x32_bf16 v[68:71], v[172:175], v[212:215], v[68:71]
	v_mfma_f32_16x16x32_bf16 v[64:67], v[180:183], v[212:215], v[64:67]
	s_setprio 0
	s_barrier
	s_add_i32 s20, s3, s7
	v_lshl_add_u64 v[216:217], v[216:217], 0, s[14:15]
	s_mov_b32 m0, s20
	ds_read_b128 v[184:187], v153 offset:49152
	ds_read_b128 v[188:191], v153 offset:50176
	ds_read_b128 v[192:195], v153 offset:51200
	ds_read_b128 v[196:199], v153 offset:52224
	ds_read_b128 v[200:203], v153 offset:53248
	ds_read_b128 v[204:207], v153 offset:54272
	ds_read_b128 v[208:211], v153 offset:55296
	ds_read_b128 v[212:215], v153 offset:56320
	global_load_lds_dwordx4 v[216:217], off
	s_add_i32 m0, s20, 0x2000
	s_add_u32 s20, s24, 0x160080
	v_lshl_add_u64 v[216:217], v[218:219], 0, s[14:15]
	s_addc_u32 s21, s25, 0
	s_add_i32 s24, s58, s7
	global_load_lds_dwordx4 v[216:217], off
	s_mov_b32 m0, s24
	s_nop 0
	global_load_lds_dwordx4 v130, s[20:21]
	s_add_i32 m0, s24, 0x2000
	s_nop 0
	global_load_lds_dwordx4 v134, s[20:21]
	v_lshl_add_u64 v[216:217], v[222:223], 0, s[14:15]
	s_mov_b32 m0, s35
	s_nop 0
	global_load_lds_dwordx4 v[216:217], off
	v_lshl_add_u64 v[216:217], v[224:225], 0, s[14:15]
	s_mov_b32 m0, s38
	s_nop 0
	global_load_lds_dwordx4 v[216:217], off
	s_waitcnt vmcnt(8)
	s_waitcnt lgkmcnt(0)
	s_setprio 1
	s_waitcnt lgkmcnt(0)
	v_mfma_f32_16x16x32_bf16 v[60:63], v[144:147], v[184:187], v[60:63]
	v_mfma_f32_16x16x32_bf16 v[56:59], v[160:163], v[184:187], v[56:59]
	v_mfma_f32_16x16x32_bf16 v[60:63], v[156:159], v[188:191], v[60:63]
	v_mfma_f32_16x16x32_bf16 v[56:59], v[164:167], v[188:191], v[56:59]
	s_barrier
	v_mfma_f32_16x16x32_bf16 v[44:47], v[144:147], v[192:195], v[44:47]
	v_mfma_f32_16x16x32_bf16 v[40:43], v[160:163], v[192:195], v[40:43]
	v_mfma_f32_16x16x32_bf16 v[28:31], v[144:147], v[200:203], v[28:31]
	v_mfma_f32_16x16x32_bf16 v[24:27], v[160:163], v[200:203], v[24:27]
	v_mfma_f32_16x16x32_bf16 v[12:15], v[144:147], v[208:211], v[12:15]
	v_mfma_f32_16x16x32_bf16 v[8:11], v[160:163], v[208:211], v[8:11]
	v_mfma_f32_16x16x32_bf16 v[52:55], v[168:171], v[184:187], v[52:55]
	v_mfma_f32_16x16x32_bf16 v[48:51], v[176:179], v[184:187], v[48:51]
	v_mfma_f32_16x16x32_bf16 v[36:39], v[168:171], v[192:195], v[36:39]
	v_mfma_f32_16x16x32_bf16 v[32:35], v[176:179], v[192:195], v[32:35]
	v_mfma_f32_16x16x32_bf16 v[20:23], v[168:171], v[200:203], v[20:23]
	v_mfma_f32_16x16x32_bf16 v[16:19], v[176:179], v[200:203], v[16:19]
	v_mfma_f32_16x16x32_bf16 v[4:7], v[168:171], v[208:211], v[4:7]
	v_mfma_f32_16x16x32_bf16 v[0:3], v[176:179], v[208:211], v[0:3]
	v_mfma_f32_16x16x32_bf16 v[44:47], v[156:159], v[196:199], v[44:47]
	v_mfma_f32_16x16x32_bf16 v[40:43], v[164:167], v[196:199], v[40:43]
	v_mfma_f32_16x16x32_bf16 v[28:31], v[156:159], v[204:207], v[28:31]
	v_mfma_f32_16x16x32_bf16 v[24:27], v[164:167], v[204:207], v[24:27]
	v_mfma_f32_16x16x32_bf16 v[12:15], v[156:159], v[212:215], v[12:15]
	v_mfma_f32_16x16x32_bf16 v[8:11], v[164:167], v[212:215], v[8:11]
	v_mfma_f32_16x16x32_bf16 v[52:55], v[172:175], v[188:191], v[52:55]
	v_mfma_f32_16x16x32_bf16 v[48:51], v[180:183], v[188:191], v[48:51]
	v_mfma_f32_16x16x32_bf16 v[36:39], v[172:175], v[196:199], v[36:39]
	v_mfma_f32_16x16x32_bf16 v[32:35], v[180:183], v[196:199], v[32:35]
	v_mfma_f32_16x16x32_bf16 v[20:23], v[172:175], v[204:207], v[20:23]
	v_mfma_f32_16x16x32_bf16 v[16:19], v[180:183], v[204:207], v[16:19]
	v_mfma_f32_16x16x32_bf16 v[4:7], v[172:175], v[212:215], v[4:7]
	v_mfma_f32_16x16x32_bf16 v[0:3], v[180:183], v[212:215], v[0:3]
	s_setprio 0
	s_barrier
	s_add_i32 s48, s48, 2
	s_add_u32 s46, s46, 0x100
	s_addc_u32 s47, s47, 0
	s_cmpk_gt_u32 s48, 0x55
	s_mov_b64 s[20:21], s[22:23]
	s_cbranch_scc0 .LBB0_1555
	s_and_b64 vcc, exec, s[16:17]
	s_cbranch_vccz .LBB0_1558
	s_barrier

.LBB0_1647:
	v_add_u32_e32 v156, s95, v159
	ds_read_b128 v[162:165], v156
	ds_read_b128 v[166:169], v156 offset:1024
	ds_read_b128 v[170:173], v156 offset:2048
	ds_read_b128 v[174:177], v156 offset:3072
	v_add_u32_e32 v156, s33, v159
	ds_read_b128 v[178:181], v156
	ds_read_b128 v[182:185], v156 offset:1024
	ds_read_b128 v[186:189], v156 offset:2048
	ds_read_b128 v[190:193], v156 offset:3072
	s_add_u32 s44, s40, 0xfff80080
	s_addc_u32 s45, s41, -1
	s_and_b64 s[42:43], s[42:43], exec
	s_cselect_b32 s45, s29, s45
	s_cselect_b32 s44, s63, s44
	s_cselect_b32 s43, s27, s66
	s_cselect_b32 s42, s64, s65
	s_add_i32 m0, s17, 0xc000
	ds_read_b128 v[194:197], v161
	ds_read_b128 v[198:201], v161 offset:1024
	ds_read_b128 v[202:205], v161 offset:2048
	ds_read_b128 v[206:209], v161 offset:3072
	ds_read_b128 v[210:213], v161 offset:4096
	ds_read_b128 v[214:217], v161 offset:5120
	ds_read_b128 v[222:225], v161 offset:6144
	ds_read_b128 v[226:229], v161 offset:7168
	global_load_lds_dwordx4 v136, s[40:41]
	s_add_i32 m0, s17, 0xe000
	s_nop 0
	global_load_lds_dwordx4 v138, s[40:41]
	s_waitcnt vmcnt(8)
	s_waitcnt lgkmcnt(0)
	s_setprio 1
	s_waitcnt lgkmcnt(0)
	v_mfma_f32_16x16x32_bf16 v[124:127], v[162:165], v[194:197], v[124:127]
	v_mfma_f32_16x16x32_bf16 v[120:123], v[170:173], v[194:197], v[120:123]
	v_mfma_f32_16x16x32_bf16 v[124:127], v[166:169], v[198:201], v[124:127]
	v_mfma_f32_16x16x32_bf16 v[120:123], v[174:177], v[198:201], v[120:123]
	s_barrier
	v_mfma_f32_16x16x32_bf16 v[116:119], v[162:165], v[202:205], v[116:119]
	v_mfma_f32_16x16x32_bf16 v[104:107], v[170:173], v[202:205], v[104:107]
	v_mfma_f32_16x16x32_bf16 v[92:95], v[162:165], v[210:213], v[92:95]
	v_mfma_f32_16x16x32_bf16 v[88:91], v[170:173], v[210:213], v[88:91]
	v_mfma_f32_16x16x32_bf16 v[84:87], v[162:165], v[222:225], v[84:87]
	v_mfma_f32_16x16x32_bf16 v[72:75], v[170:173], v[222:225], v[72:75]
	v_mfma_f32_16x16x32_bf16 v[112:115], v[178:181], v[194:197], v[112:115]
	v_mfma_f32_16x16x32_bf16 v[108:111], v[186:189], v[194:197], v[108:111]
	v_mfma_f32_16x16x32_bf16 v[100:103], v[178:181], v[202:205], v[100:103]
	v_mfma_f32_16x16x32_bf16 v[96:99], v[186:189], v[202:205], v[96:99]
	v_mfma_f32_16x16x32_bf16 v[80:83], v[178:181], v[210:213], v[80:83]
	v_mfma_f32_16x16x32_bf16 v[76:79], v[186:189], v[210:213], v[76:79]
	v_mfma_f32_16x16x32_bf16 v[68:71], v[178:181], v[222:225], v[68:71]
	v_mfma_f32_16x16x32_bf16 v[64:67], v[186:189], v[222:225], v[64:67]
	v_mfma_f32_16x16x32_bf16 v[116:119], v[166:169], v[206:209], v[116:119]
	v_mfma_f32_16x16x32_bf16 v[104:107], v[174:177], v[206:209], v[104:107]
	v_mfma_f32_16x16x32_bf16 v[92:95], v[166:169], v[214:217], v[92:95]
	v_mfma_f32_16x16x32_bf16 v[88:91], v[174:177], v[214:217], v[88:91]
	v_mfma_f32_16x16x32_bf16 v[84:87], v[166:169], v[226:229], v[84:87]
	v_mfma_f32_16x16x32_bf16 v[72:75], v[174:177], v[226:229], v[72:75]
	v_mfma_f32_16x16x32_bf16 v[112:115], v[182:185], v[198:201], v[112:115]
	v_mfma_f32_16x16x32_bf16 v[108:111], v[190:193], v[198:201], v[108:111]
	v_mfma_f32_16x16x32_bf16 v[100:103], v[182:185], v[206:209], v[100:103]
	v_mfma_f32_16x16x32_bf16 v[96:99], v[190:193], v[206:209], v[96:99]
	v_mfma_f32_16x16x32_bf16 v[80:83], v[182:185], v[214:217], v[80:83]
	v_mfma_f32_16x16x32_bf16 v[76:79], v[190:193], v[214:217], v[76:79]
	v_mfma_f32_16x16x32_bf16 v[68:71], v[182:185], v[226:229], v[68:71]
	v_mfma_f32_16x16x32_bf16 v[64:67], v[190:193], v[226:229], v[64:67]
	s_setprio 0
	s_barrier
	s_add_i32 s68, s95, s6
	v_lshl_add_u64 v[156:157], s[42:43], 0, v[130:131]
	s_mov_b32 m0, s68
	ds_read_b128 v[194:197], v161 offset:16384
	ds_read_b128 v[198:201], v161 offset:17408
	ds_read_b128 v[202:205], v161 offset:18432
	ds_read_b128 v[206:209], v161 offset:19456
	ds_read_b128 v[210:213], v161 offset:20480
	ds_read_b128 v[214:217], v161 offset:21504
	ds_read_b128 v[222:225], v161 offset:22528
	ds_read_b128 v[226:229], v161 offset:23552
	global_load_lds_dwordx4 v[156:157], off
	s_add_i32 m0, s68, 0x2000
	s_add_u32 s68, s42, 0x80000
	v_lshl_add_u64 v[218:219], s[42:43], 0, v[134:135]
	s_addc_u32 s69, s43, 0
	s_add_i32 s70, s33, s6
	global_load_lds_dwordx4 v[218:219], off
	s_mov_b32 m0, s70
	v_lshl_add_u64 v[232:233], s[44:45], 0, v[132:133]
	global_load_lds_dwordx4 v130, s[68:69]
	s_add_i32 m0, s70, 0x2000
	s_nop 0
	global_load_lds_dwordx4 v134, s[68:69]
	v_lshl_add_u64 v[230:231], s[44:45], 0, v[128:129]
	s_mov_b32 m0, s17
	s_nop 0
	global_load_lds_dwordx4 v[230:231], off
	s_mov_b32 m0, s19
	s_nop 0
	global_load_lds_dwordx4 v[232:233], off
	s_waitcnt vmcnt(8)
	s_waitcnt lgkmcnt(0)
	s_setprio 1
	s_waitcnt lgkmcnt(0)
	v_mfma_f32_16x16x32_bf16 v[60:63], v[162:165], v[194:197], v[60:63]
	v_mfma_f32_16x16x32_bf16 v[56:59], v[170:173], v[194:197], v[56:59]
	v_mfma_f32_16x16x32_bf16 v[60:63], v[166:169], v[198:201], v[60:63]
	v_mfma_f32_16x16x32_bf16 v[56:59], v[174:177], v[198:201], v[56:59]
	s_barrier
	v_mfma_f32_16x16x32_bf16 v[52:55], v[162:165], v[202:205], v[52:55]
	v_mfma_f32_16x16x32_bf16 v[44:47], v[170:173], v[202:205], v[44:47]
	v_mfma_f32_16x16x32_bf16 v[32:35], v[162:165], v[210:213], v[32:35]
	v_mfma_f32_16x16x32_bf16 v[24:27], v[170:173], v[210:213], v[24:27]
	v_mfma_f32_16x16x32_bf16 v[20:23], v[162:165], v[222:225], v[20:23]
	v_mfma_f32_16x16x32_bf16 v[12:15], v[170:173], v[222:225], v[12:15]
	v_mfma_f32_16x16x32_bf16 v[48:51], v[178:181], v[194:197], v[48:51]
	v_mfma_f32_16x16x32_bf16 v[40:43], v[186:189], v[194:197], v[40:43]
	v_mfma_f32_16x16x32_bf16 v[36:39], v[178:181], v[202:205], v[36:39]
	v_mfma_f32_16x16x32_bf16 v[28:31], v[186:189], v[202:205], v[28:31]
	v_mfma_f32_16x16x32_bf16 v[16:19], v[178:181], v[210:213], v[16:19]
	v_mfma_f32_16x16x32_bf16 v[8:11], v[186:189], v[210:213], v[8:11]
	v_mfma_f32_16x16x32_bf16 v[4:7], v[178:181], v[222:225], v[4:7]
	v_mfma_f32_16x16x32_bf16 v[0:3], v[186:189], v[222:225], v[0:3]
	v_mfma_f32_16x16x32_bf16 v[52:55], v[166:169], v[206:209], v[52:55]
	v_mfma_f32_16x16x32_bf16 v[44:47], v[174:177], v[206:209], v[44:47]
	v_mfma_f32_16x16x32_bf16 v[32:35], v[166:169], v[214:217], v[32:35]
	v_mfma_f32_16x16x32_bf16 v[24:27], v[174:177], v[214:217], v[24:27]
	v_mfma_f32_16x16x32_bf16 v[20:23], v[166:169], v[226:229], v[20:23]
	v_mfma_f32_16x16x32_bf16 v[12:15], v[174:177], v[226:229], v[12:15]
	v_mfma_f32_16x16x32_bf16 v[48:51], v[182:185], v[198:201], v[48:51]
	v_mfma_f32_16x16x32_bf16 v[40:43], v[190:193], v[198:201], v[40:43]
	v_mfma_f32_16x16x32_bf16 v[36:39], v[182:185], v[206:209], v[36:39]
	v_mfma_f32_16x16x32_bf16 v[28:31], v[190:193], v[206:209], v[28:31]
	v_mfma_f32_16x16x32_bf16 v[16:19], v[182:185], v[214:217], v[16:19]
	v_mfma_f32_16x16x32_bf16 v[8:11], v[190:193], v[214:217], v[8:11]
	v_mfma_f32_16x16x32_bf16 v[4:7], v[182:185], v[226:229], v[4:7]
	v_mfma_f32_16x16x32_bf16 v[0:3], v[190:193], v[226:229], v[0:3]
	s_setprio 0
	s_barrier
	v_add_u32_e32 v174, s3, v159
	v_add_u32_e32 v190, s58, v159
	ds_read_b128 v[162:165], v174
	ds_read_b128 v[166:169], v174 offset:1024
	ds_read_b128 v[170:173], v174 offset:2048
	ds_read_b128 v[174:177], v174 offset:3072
	ds_read_b128 v[178:181], v190
	ds_read_b128 v[182:185], v190 offset:1024
	ds_read_b128 v[186:189], v190 offset:2048
	ds_read_b128 v[190:193], v190 offset:3072
	s_add_u32 s44, s44, 0x80000
	s_addc_u32 s45, s45, 0
	s_mov_b32 m0, s46
	ds_read_b128 v[194:197], v161 offset:32768
	ds_read_b128 v[198:201], v161 offset:33792
	ds_read_b128 v[202:205], v161 offset:34816
	ds_read_b128 v[206:209], v161 offset:35840
	ds_read_b128 v[210:213], v161 offset:36864
	ds_read_b128 v[214:217], v161 offset:37888
	ds_read_b128 v[222:225], v161 offset:38912
	ds_read_b128 v[226:229], v161 offset:39936
	global_load_lds_dwordx4 v128, s[44:45]
	s_mov_b32 m0, s47
	s_nop 0
	global_load_lds_dwordx4 v132, s[44:45]
	s_waitcnt vmcnt(8)
	s_waitcnt lgkmcnt(0)
	s_setprio 1
	s_waitcnt lgkmcnt(0)
	v_mfma_f32_16x16x32_bf16 v[124:127], v[162:165], v[194:197], v[124:127]
	v_mfma_f32_16x16x32_bf16 v[120:123], v[170:173], v[194:197], v[120:123]
	v_mfma_f32_16x16x32_bf16 v[124:127], v[166:169], v[198:201], v[124:127]
	v_mfma_f32_16x16x32_bf16 v[120:123], v[174:177], v[198:201], v[120:123]
	s_barrier
	v_mfma_f32_16x16x32_bf16 v[116:119], v[162:165], v[202:205], v[116:119]
	v_mfma_f32_16x16x32_bf16 v[104:107], v[170:173], v[202:205], v[104:107]
	v_mfma_f32_16x16x32_bf16 v[92:95], v[162:165], v[210:213], v[92:95]
	v_mfma_f32_16x16x32_bf16 v[88:91], v[170:173], v[210:213], v[88:91]
	v_mfma_f32_16x16x32_bf16 v[84:87], v[162:165], v[222:225], v[84:87]
	v_mfma_f32_16x16x32_bf16 v[72:75], v[170:173], v[222:225], v[72:75]
	v_mfma_f32_16x16x32_bf16 v[112:115], v[178:181], v[194:197], v[112:115]
	v_mfma_f32_16x16x32_bf16 v[108:111], v[186:189], v[194:197], v[108:111]
	v_mfma_f32_16x16x32_bf16 v[100:103], v[178:181], v[202:205], v[100:103]
	v_mfma_f32_16x16x32_bf16 v[96:99], v[186:189], v[202:205], v[96:99]
	v_mfma_f32_16x16x32_bf16 v[80:83], v[178:181], v[210:213], v[80:83]
	v_mfma_f32_16x16x32_bf16 v[76:79], v[186:189], v[210:213], v[76:79]
	v_mfma_f32_16x16x32_bf16 v[68:71], v[178:181], v[222:225], v[68:71]
	v_mfma_f32_16x16x32_bf16 v[64:67], v[186:189], v[222:225], v[64:67]
	v_mfma_f32_16x16x32_bf16 v[116:119], v[166:169], v[206:209], v[116:119]
	v_mfma_f32_16x16x32_bf16 v[104:107], v[174:177], v[206:209], v[104:107]
	v_mfma_f32_16x16x32_bf16 v[92:95], v[166:169], v[214:217], v[92:95]
	v_mfma_f32_16x16x32_bf16 v[88:91], v[174:177], v[214:217], v[88:91]
	v_mfma_f32_16x16x32_bf16 v[84:87], v[166:169], v[226:229], v[84:87]
	v_mfma_f32_16x16x32_bf16 v[72:75], v[174:177], v[226:229], v[72:75]
	v_mfma_f32_16x16x32_bf16 v[112:115], v[182:185], v[198:201], v[112:115]
	v_mfma_f32_16x16x32_bf16 v[108:111], v[190:193], v[198:201], v[108:111]
	v_mfma_f32_16x16x32_bf16 v[100:103], v[182:185], v[206:209], v[100:103]
	v_mfma_f32_16x16x32_bf16 v[96:99], v[190:193], v[206:209], v[96:99]
	v_mfma_f32_16x16x32_bf16 v[80:83], v[182:185], v[214:217], v[80:83]
	v_mfma_f32_16x16x32_bf16 v[76:79], v[190:193], v[214:217], v[76:79]
	v_mfma_f32_16x16x32_bf16 v[68:71], v[182:185], v[226:229], v[68:71]
	v_mfma_f32_16x16x32_bf16 v[64:67], v[190:193], v[226:229], v[64:67]
	s_setprio 0
	s_barrier
	s_add_i32 s44, s3, s6
	v_lshl_add_u64 v[156:157], v[156:157], 0, s[8:9]
	s_mov_b32 m0, s44
	ds_read_b128 v[194:197], v161 offset:49152
	ds_read_b128 v[198:201], v161 offset:50176
	ds_read_b128 v[202:205], v161 offset:51200
	ds_read_b128 v[206:209], v161 offset:52224
	ds_read_b128 v[210:213], v161 offset:53248
	ds_read_b128 v[214:217], v161 offset:54272
	ds_read_b128 v[222:225], v161 offset:55296
	ds_read_b128 v[226:229], v161 offset:56320
	global_load_lds_dwordx4 v[156:157], off
	s_add_i32 m0, s44, 0x2000
	s_add_u32 s42, s42, 0x80080
	v_lshl_add_u64 v[156:157], v[218:219], 0, s[8:9]
	s_addc_u32 s43, s43, 0
	s_add_i32 s44, s58, s6
	global_load_lds_dwordx4 v[156:157], off
	s_mov_b32 m0, s44
	s_nop 0
	global_load_lds_dwordx4 v130, s[42:43]
	s_add_i32 m0, s44, 0x2000
	s_nop 0
	global_load_lds_dwordx4 v134, s[42:43]
	v_lshl_add_u64 v[156:157], v[230:231], 0, s[8:9]
	s_mov_b32 m0, s49
	s_nop 0
	global_load_lds_dwordx4 v[156:157], off
	v_lshl_add_u64 v[156:157], v[232:233], 0, s[8:9]
	s_mov_b32 m0, s50
	s_nop 0
	global_load_lds_dwordx4 v[156:157], off
	s_waitcnt vmcnt(8)
	s_waitcnt lgkmcnt(0)
	s_setprio 1
	s_waitcnt lgkmcnt(0)
	v_mfma_f32_16x16x32_bf16 v[60:63], v[162:165], v[194:197], v[60:63]
	v_mfma_f32_16x16x32_bf16 v[56:59], v[170:173], v[194:197], v[56:59]
	v_mfma_f32_16x16x32_bf16 v[60:63], v[166:169], v[198:201], v[60:63]
	v_mfma_f32_16x16x32_bf16 v[56:59], v[174:177], v[198:201], v[56:59]
	s_barrier
	v_mfma_f32_16x16x32_bf16 v[52:55], v[162:165], v[202:205], v[52:55]
	v_mfma_f32_16x16x32_bf16 v[44:47], v[170:173], v[202:205], v[44:47]
	v_mfma_f32_16x16x32_bf16 v[32:35], v[162:165], v[210:213], v[32:35]
	v_mfma_f32_16x16x32_bf16 v[24:27], v[170:173], v[210:213], v[24:27]
	v_mfma_f32_16x16x32_bf16 v[20:23], v[162:165], v[222:225], v[20:23]
	v_mfma_f32_16x16x32_bf16 v[12:15], v[170:173], v[222:225], v[12:15]
	v_mfma_f32_16x16x32_bf16 v[48:51], v[178:181], v[194:197], v[48:51]
	v_mfma_f32_16x16x32_bf16 v[40:43], v[186:189], v[194:197], v[40:43]
	v_mfma_f32_16x16x32_bf16 v[36:39], v[178:181], v[202:205], v[36:39]
	v_mfma_f32_16x16x32_bf16 v[28:31], v[186:189], v[202:205], v[28:31]
	v_mfma_f32_16x16x32_bf16 v[16:19], v[178:181], v[210:213], v[16:19]
	v_mfma_f32_16x16x32_bf16 v[8:11], v[186:189], v[210:213], v[8:11]
	v_mfma_f32_16x16x32_bf16 v[4:7], v[178:181], v[222:225], v[4:7]
	v_mfma_f32_16x16x32_bf16 v[0:3], v[186:189], v[222:225], v[0:3]
	v_mfma_f32_16x16x32_bf16 v[52:55], v[166:169], v[206:209], v[52:55]
	v_mfma_f32_16x16x32_bf16 v[44:47], v[174:177], v[206:209], v[44:47]
	v_mfma_f32_16x16x32_bf16 v[32:35], v[166:169], v[214:217], v[32:35]
	v_mfma_f32_16x16x32_bf16 v[24:27], v[174:177], v[214:217], v[24:27]
	v_mfma_f32_16x16x32_bf16 v[20:23], v[166:169], v[226:229], v[20:23]
	v_mfma_f32_16x16x32_bf16 v[12:15], v[174:177], v[226:229], v[12:15]
	v_mfma_f32_16x16x32_bf16 v[48:51], v[182:185], v[198:201], v[48:51]
	v_mfma_f32_16x16x32_bf16 v[40:43], v[190:193], v[198:201], v[40:43]
	v_mfma_f32_16x16x32_bf16 v[36:39], v[182:185], v[206:209], v[36:39]
	v_mfma_f32_16x16x32_bf16 v[28:31], v[190:193], v[206:209], v[28:31]
	v_mfma_f32_16x16x32_bf16 v[16:19], v[182:185], v[214:217], v[16:19]
	v_mfma_f32_16x16x32_bf16 v[8:11], v[190:193], v[214:217], v[8:11]
	v_mfma_f32_16x16x32_bf16 v[4:7], v[182:185], v[226:229], v[4:7]
	v_mfma_f32_16x16x32_bf16 v[0:3], v[190:193], v[226:229], v[0:3]
	s_setprio 0
	s_barrier
	s_add_i32 s67, s67, 2
	s_add_u32 s40, s40, 0x100
	s_addc_u32 s41, s41, 0
	s_add_u32 s65, s65, 0x100
	s_addc_u32 s66, s66, 0
	s_cmp_gt_u32 s67, 29
	s_cbranch_scc1 .LBB0_1650

.LBB0_1865:
	ds_read_b128 v[144:147], v151
	ds_read_b128 v[156:159], v151 offset:1024
	ds_read_b128 v[160:163], v151 offset:2048
	ds_read_b128 v[164:167], v151 offset:3072
	ds_read_b128 v[168:171], v152
	ds_read_b128 v[172:175], v152 offset:1024
	ds_read_b128 v[176:179], v152 offset:2048
	ds_read_b128 v[180:183], v152 offset:3072
	s_add_u32 s30, s28, 0xfff80080
	s_addc_u32 s31, s29, -1
	s_cmp_eq_u32 s50, 28
	s_cselect_b32 s35, s19, s31
	s_cselect_b32 s34, s25, s30
	s_cselect_b32 s31, s17, s49
	s_cselect_b32 s30, s47, s48
	s_add_i32 m0, s27, 0xc000
	ds_read_b128 v[184:187], v153
	ds_read_b128 v[188:191], v153 offset:1024
	ds_read_b128 v[192:195], v153 offset:2048
	ds_read_b128 v[196:199], v153 offset:3072
	ds_read_b128 v[200:203], v153 offset:4096
	ds_read_b128 v[204:207], v153 offset:5120
	ds_read_b128 v[208:211], v153 offset:6144
	ds_read_b128 v[212:215], v153 offset:7168
	global_load_lds_dwordx4 v136, s[28:29]
	s_add_i32 m0, s27, 0xe000
	s_nop 0
	global_load_lds_dwordx4 v138, s[28:29]
	s_waitcnt vmcnt(8)
	s_waitcnt lgkmcnt(0)
	s_setprio 1
	s_waitcnt lgkmcnt(0)
	v_mfma_f32_16x16x32_bf16 v[124:127], v[144:147], v[184:187], v[124:127]
	v_mfma_f32_16x16x32_bf16 v[120:123], v[160:163], v[184:187], v[120:123]
	v_mfma_f32_16x16x32_bf16 v[124:127], v[156:159], v[188:191], v[124:127]
	v_mfma_f32_16x16x32_bf16 v[120:123], v[164:167], v[188:191], v[120:123]
	s_barrier
	v_mfma_f32_16x16x32_bf16 v[108:111], v[144:147], v[192:195], v[108:111]
	v_mfma_f32_16x16x32_bf16 v[104:107], v[160:163], v[192:195], v[104:107]
	v_mfma_f32_16x16x32_bf16 v[92:95], v[144:147], v[200:203], v[92:95]
	v_mfma_f32_16x16x32_bf16 v[88:91], v[160:163], v[200:203], v[88:91]
	v_mfma_f32_16x16x32_bf16 v[76:79], v[144:147], v[208:211], v[76:79]
	v_mfma_f32_16x16x32_bf16 v[72:75], v[160:163], v[208:211], v[72:75]
	v_mfma_f32_16x16x32_bf16 v[116:119], v[168:171], v[184:187], v[116:119]
	v_mfma_f32_16x16x32_bf16 v[112:115], v[176:179], v[184:187], v[112:115]
	v_mfma_f32_16x16x32_bf16 v[100:103], v[168:171], v[192:195], v[100:103]
	v_mfma_f32_16x16x32_bf16 v[96:99], v[176:179], v[192:195], v[96:99]
	v_mfma_f32_16x16x32_bf16 v[84:87], v[168:171], v[200:203], v[84:87]
	v_mfma_f32_16x16x32_bf16 v[80:83], v[176:179], v[200:203], v[80:83]
	v_mfma_f32_16x16x32_bf16 v[68:71], v[168:171], v[208:211], v[68:71]
	v_mfma_f32_16x16x32_bf16 v[64:67], v[176:179], v[208:211], v[64:67]
	v_mfma_f32_16x16x32_bf16 v[108:111], v[156:159], v[196:199], v[108:111]
	v_mfma_f32_16x16x32_bf16 v[104:107], v[164:167], v[196:199], v[104:107]
	v_mfma_f32_16x16x32_bf16 v[92:95], v[156:159], v[204:207], v[92:95]
	v_mfma_f32_16x16x32_bf16 v[88:91], v[164:167], v[204:207], v[88:91]
	v_mfma_f32_16x16x32_bf16 v[76:79], v[156:159], v[212:215], v[76:79]
	v_mfma_f32_16x16x32_bf16 v[72:75], v[164:167], v[212:215], v[72:75]
	v_mfma_f32_16x16x32_bf16 v[116:119], v[172:175], v[188:191], v[116:119]
	v_mfma_f32_16x16x32_bf16 v[112:115], v[180:183], v[188:191], v[112:115]
	v_mfma_f32_16x16x32_bf16 v[100:103], v[172:175], v[196:199], v[100:103]
	v_mfma_f32_16x16x32_bf16 v[96:99], v[180:183], v[196:199], v[96:99]
	v_mfma_f32_16x16x32_bf16 v[84:87], v[172:175], v[204:207], v[84:87]
	v_mfma_f32_16x16x32_bf16 v[80:83], v[180:183], v[204:207], v[80:83]
	v_mfma_f32_16x16x32_bf16 v[68:71], v[172:175], v[212:215], v[68:71]
	v_mfma_f32_16x16x32_bf16 v[64:67], v[180:183], v[212:215], v[64:67]
	s_setprio 0
	s_barrier
	s_add_i32 s51, s95, s7
	v_lshl_add_u64 v[216:217], s[30:31], 0, v[130:131]
	s_mov_b32 m0, s51
	ds_read_b128 v[184:187], v153 offset:16384
	ds_read_b128 v[188:191], v153 offset:17408
	ds_read_b128 v[192:195], v153 offset:18432
	ds_read_b128 v[196:199], v153 offset:19456
	ds_read_b128 v[200:203], v153 offset:20480
	ds_read_b128 v[204:207], v153 offset:21504
	ds_read_b128 v[208:211], v153 offset:22528
	ds_read_b128 v[212:215], v153 offset:23552
	global_load_lds_dwordx4 v[216:217], off
	s_add_i32 m0, s51, 0x2000
	s_add_u32 s54, s30, 0x80000
	v_lshl_add_u64 v[218:219], s[30:31], 0, v[134:135]
	s_addc_u32 s55, s31, 0
	s_add_i32 s51, s33, s7
	global_load_lds_dwordx4 v[218:219], off
	s_mov_b32 m0, s51
	v_lshl_add_u64 v[224:225], s[34:35], 0, v[132:133]
	global_load_lds_dwordx4 v130, s[54:55]
	s_add_i32 m0, s51, 0x2000
	s_nop 0
	global_load_lds_dwordx4 v134, s[54:55]
	v_lshl_add_u64 v[222:223], s[34:35], 0, v[128:129]
	s_mov_b32 m0, s27
	s_nop 0
	global_load_lds_dwordx4 v[222:223], off
	s_mov_b32 m0, s38
	s_nop 0
	global_load_lds_dwordx4 v[224:225], off
	s_waitcnt vmcnt(8)
	s_waitcnt lgkmcnt(0)
	s_setprio 1
	s_waitcnt lgkmcnt(0)
	v_mfma_f32_16x16x32_bf16 v[60:63], v[144:147], v[184:187], v[60:63]
	v_mfma_f32_16x16x32_bf16 v[56:59], v[160:163], v[184:187], v[56:59]
	v_mfma_f32_16x16x32_bf16 v[60:63], v[156:159], v[188:191], v[60:63]
	v_mfma_f32_16x16x32_bf16 v[56:59], v[164:167], v[188:191], v[56:59]
	s_barrier
	v_mfma_f32_16x16x32_bf16 v[44:47], v[144:147], v[192:195], v[44:47]
	v_mfma_f32_16x16x32_bf16 v[40:43], v[160:163], v[192:195], v[40:43]
	v_mfma_f32_16x16x32_bf16 v[28:31], v[144:147], v[200:203], v[28:31]
	v_mfma_f32_16x16x32_bf16 v[24:27], v[160:163], v[200:203], v[24:27]
	v_mfma_f32_16x16x32_bf16 v[12:15], v[144:147], v[208:211], v[12:15]
	v_mfma_f32_16x16x32_bf16 v[8:11], v[160:163], v[208:211], v[8:11]
	v_mfma_f32_16x16x32_bf16 v[52:55], v[168:171], v[184:187], v[52:55]
	v_mfma_f32_16x16x32_bf16 v[48:51], v[176:179], v[184:187], v[48:51]
	v_mfma_f32_16x16x32_bf16 v[36:39], v[168:171], v[192:195], v[36:39]
	v_mfma_f32_16x16x32_bf16 v[32:35], v[176:179], v[192:195], v[32:35]
	v_mfma_f32_16x16x32_bf16 v[20:23], v[168:171], v[200:203], v[20:23]
	v_mfma_f32_16x16x32_bf16 v[16:19], v[176:179], v[200:203], v[16:19]
	v_mfma_f32_16x16x32_bf16 v[4:7], v[168:171], v[208:211], v[4:7]
	v_mfma_f32_16x16x32_bf16 v[0:3], v[176:179], v[208:211], v[0:3]
	v_mfma_f32_16x16x32_bf16 v[44:47], v[156:159], v[196:199], v[44:47]
	v_mfma_f32_16x16x32_bf16 v[40:43], v[164:167], v[196:199], v[40:43]
	v_mfma_f32_16x16x32_bf16 v[28:31], v[156:159], v[204:207], v[28:31]
	v_mfma_f32_16x16x32_bf16 v[24:27], v[164:167], v[204:207], v[24:27]
	v_mfma_f32_16x16x32_bf16 v[12:15], v[156:159], v[212:215], v[12:15]
	v_mfma_f32_16x16x32_bf16 v[8:11], v[164:167], v[212:215], v[8:11]
	v_mfma_f32_16x16x32_bf16 v[52:55], v[172:175], v[188:191], v[52:55]
	v_mfma_f32_16x16x32_bf16 v[48:51], v[180:183], v[188:191], v[48:51]
	v_mfma_f32_16x16x32_bf16 v[36:39], v[172:175], v[196:199], v[36:39]
	v_mfma_f32_16x16x32_bf16 v[32:35], v[180:183], v[196:199], v[32:35]
	v_mfma_f32_16x16x32_bf16 v[20:23], v[172:175], v[204:207], v[20:23]
	v_mfma_f32_16x16x32_bf16 v[16:19], v[180:183], v[204:207], v[16:19]
	v_mfma_f32_16x16x32_bf16 v[4:7], v[172:175], v[212:215], v[4:7]
	v_mfma_f32_16x16x32_bf16 v[0:3], v[180:183], v[212:215], v[0:3]
	s_setprio 0
	s_barrier
	v_add_u32_e32 v155, s3, v149
	ds_read_b128 v[144:147], v155
	ds_read_b128 v[156:159], v155 offset:1024
	ds_read_b128 v[160:163], v155 offset:2048
	ds_read_b128 v[164:167], v155 offset:3072
	v_add_u32_e32 v155, s58, v149
	ds_read_b128 v[168:171], v155
	ds_read_b128 v[172:175], v155 offset:1024
	ds_read_b128 v[176:179], v155 offset:2048
	ds_read_b128 v[180:183], v155 offset:3072
	s_add_u32 s34, s34, 0x80000
	s_addc_u32 s35, s35, 0
	s_mov_b32 m0, s39
	ds_read_b128 v[184:187], v153 offset:32768
	ds_read_b128 v[188:191], v153 offset:33792
	ds_read_b128 v[192:195], v153 offset:34816
	ds_read_b128 v[196:199], v153 offset:35840
	ds_read_b128 v[200:203], v153 offset:36864
	ds_read_b128 v[204:207], v153 offset:37888
	ds_read_b128 v[208:211], v153 offset:38912
	ds_read_b128 v[212:215], v153 offset:39936
	global_load_lds_dwordx4 v128, s[34:35]
	s_mov_b32 m0, s40
	s_nop 0
	global_load_lds_dwordx4 v132, s[34:35]
	s_waitcnt vmcnt(8)
	s_waitcnt lgkmcnt(0)
	s_setprio 1
	s_waitcnt lgkmcnt(0)
	v_mfma_f32_16x16x32_bf16 v[124:127], v[144:147], v[184:187], v[124:127]
	v_mfma_f32_16x16x32_bf16 v[120:123], v[160:163], v[184:187], v[120:123]
	v_mfma_f32_16x16x32_bf16 v[124:127], v[156:159], v[188:191], v[124:127]
	v_mfma_f32_16x16x32_bf16 v[120:123], v[164:167], v[188:191], v[120:123]
	s_barrier
	v_mfma_f32_16x16x32_bf16 v[108:111], v[144:147], v[192:195], v[108:111]
	v_mfma_f32_16x16x32_bf16 v[104:107], v[160:163], v[192:195], v[104:107]
	v_mfma_f32_16x16x32_bf16 v[92:95], v[144:147], v[200:203], v[92:95]
	v_mfma_f32_16x16x32_bf16 v[88:91], v[160:163], v[200:203], v[88:91]
	v_mfma_f32_16x16x32_bf16 v[76:79], v[144:147], v[208:211], v[76:79]
	v_mfma_f32_16x16x32_bf16 v[72:75], v[160:163], v[208:211], v[72:75]
	v_mfma_f32_16x16x32_bf16 v[116:119], v[168:171], v[184:187], v[116:119]
	v_mfma_f32_16x16x32_bf16 v[112:115], v[176:179], v[184:187], v[112:115]
	v_mfma_f32_16x16x32_bf16 v[100:103], v[168:171], v[192:195], v[100:103]
	v_mfma_f32_16x16x32_bf16 v[96:99], v[176:179], v[192:195], v[96:99]
	v_mfma_f32_16x16x32_bf16 v[84:87], v[168:171], v[200:203], v[84:87]
	v_mfma_f32_16x16x32_bf16 v[80:83], v[176:179], v[200:203], v[80:83]
	v_mfma_f32_16x16x32_bf16 v[68:71], v[168:171], v[208:211], v[68:71]
	v_mfma_f32_16x16x32_bf16 v[64:67], v[176:179], v[208:211], v[64:67]
	v_mfma_f32_16x16x32_bf16 v[108:111], v[156:159], v[196:199], v[108:111]
	v_mfma_f32_16x16x32_bf16 v[104:107], v[164:167], v[196:199], v[104:107]
	v_mfma_f32_16x16x32_bf16 v[92:95], v[156:159], v[204:207], v[92:95]
	v_mfma_f32_16x16x32_bf16 v[88:91], v[164:167], v[204:207], v[88:91]
	v_mfma_f32_16x16x32_bf16 v[76:79], v[156:159], v[212:215], v[76:79]
	v_mfma_f32_16x16x32_bf16 v[72:75], v[164:167], v[212:215], v[72:75]
	v_mfma_f32_16x16x32_bf16 v[116:119], v[172:175], v[188:191], v[116:119]
	v_mfma_f32_16x16x32_bf16 v[112:115], v[180:183], v[188:191], v[112:115]
	v_mfma_f32_16x16x32_bf16 v[100:103], v[172:175], v[196:199], v[100:103]
	v_mfma_f32_16x16x32_bf16 v[96:99], v[180:183], v[196:199], v[96:99]
	v_mfma_f32_16x16x32_bf16 v[84:87], v[172:175], v[204:207], v[84:87]
	v_mfma_f32_16x16x32_bf16 v[80:83], v[180:183], v[204:207], v[80:83]
	v_mfma_f32_16x16x32_bf16 v[68:71], v[172:175], v[212:215], v[68:71]
	v_mfma_f32_16x16x32_bf16 v[64:67], v[180:183], v[212:215], v[64:67]
	s_setprio 0
	s_barrier
	s_add_i32 s34, s3, s7
	v_lshl_add_u64 v[216:217], v[216:217], 0, s[12:13]
	s_mov_b32 m0, s34
	ds_read_b128 v[184:187], v153 offset:49152
	ds_read_b128 v[188:191], v153 offset:50176
	ds_read_b128 v[192:195], v153 offset:51200
	ds_read_b128 v[196:199], v153 offset:52224
	ds_read_b128 v[200:203], v153 offset:53248
	ds_read_b128 v[204:207], v153 offset:54272
	ds_read_b128 v[208:211], v153 offset:55296
	ds_read_b128 v[212:215], v153 offset:56320
	global_load_lds_dwordx4 v[216:217], off
	s_add_i32 m0, s34, 0x2000
	s_add_u32 s30, s30, 0x80080
	v_lshl_add_u64 v[216:217], v[218:219], 0, s[12:13]
	s_addc_u32 s31, s31, 0
	s_add_i32 s34, s58, s7
	global_load_lds_dwordx4 v[216:217], off
	s_mov_b32 m0, s34
	s_nop 0
	global_load_lds_dwordx4 v130, s[30:31]
	s_add_i32 m0, s34, 0x2000
	s_nop 0
	global_load_lds_dwordx4 v134, s[30:31]
	v_lshl_add_u64 v[216:217], v[222:223], 0, s[12:13]
	s_mov_b32 m0, s42
	s_nop 0
	global_load_lds_dwordx4 v[216:217], off
	v_lshl_add_u64 v[216:217], v[224:225], 0, s[12:13]
	s_mov_b32 m0, s43
	s_nop 0
	global_load_lds_dwordx4 v[216:217], off
	s_waitcnt vmcnt(8)
	s_waitcnt lgkmcnt(0)
	s_setprio 1
	s_waitcnt lgkmcnt(0)
	v_mfma_f32_16x16x32_bf16 v[60:63], v[144:147], v[184:187], v[60:63]
	v_mfma_f32_16x16x32_bf16 v[56:59], v[160:163], v[184:187], v[56:59]
	v_mfma_f32_16x16x32_bf16 v[60:63], v[156:159], v[188:191], v[60:63]
	v_mfma_f32_16x16x32_bf16 v[56:59], v[164:167], v[188:191], v[56:59]
	s_barrier
	v_mfma_f32_16x16x32_bf16 v[44:47], v[144:147], v[192:195], v[44:47]
	v_mfma_f32_16x16x32_bf16 v[40:43], v[160:163], v[192:195], v[40:43]
	v_mfma_f32_16x16x32_bf16 v[28:31], v[144:147], v[200:203], v[28:31]
	v_mfma_f32_16x16x32_bf16 v[24:27], v[160:163], v[200:203], v[24:27]
	v_mfma_f32_16x16x32_bf16 v[12:15], v[144:147], v[208:211], v[12:15]
	v_mfma_f32_16x16x32_bf16 v[8:11], v[160:163], v[208:211], v[8:11]
	v_mfma_f32_16x16x32_bf16 v[52:55], v[168:171], v[184:187], v[52:55]
	v_mfma_f32_16x16x32_bf16 v[48:51], v[176:179], v[184:187], v[48:51]
	v_mfma_f32_16x16x32_bf16 v[36:39], v[168:171], v[192:195], v[36:39]
	v_mfma_f32_16x16x32_bf16 v[32:35], v[176:179], v[192:195], v[32:35]
	v_mfma_f32_16x16x32_bf16 v[20:23], v[168:171], v[200:203], v[20:23]
	v_mfma_f32_16x16x32_bf16 v[16:19], v[176:179], v[200:203], v[16:19]
	v_mfma_f32_16x16x32_bf16 v[4:7], v[168:171], v[208:211], v[4:7]
	v_mfma_f32_16x16x32_bf16 v[0:3], v[176:179], v[208:211], v[0:3]
	v_mfma_f32_16x16x32_bf16 v[44:47], v[156:159], v[196:199], v[44:47]
	v_mfma_f32_16x16x32_bf16 v[40:43], v[164:167], v[196:199], v[40:43]
	v_mfma_f32_16x16x32_bf16 v[28:31], v[156:159], v[204:207], v[28:31]
	v_mfma_f32_16x16x32_bf16 v[24:27], v[164:167], v[204:207], v[24:27]
	v_mfma_f32_16x16x32_bf16 v[12:15], v[156:159], v[212:215], v[12:15]
	v_mfma_f32_16x16x32_bf16 v[8:11], v[164:167], v[212:215], v[8:11]
	v_mfma_f32_16x16x32_bf16 v[52:55], v[172:175], v[188:191], v[52:55]
	v_mfma_f32_16x16x32_bf16 v[48:51], v[180:183], v[188:191], v[48:51]
	v_mfma_f32_16x16x32_bf16 v[36:39], v[172:175], v[196:199], v[36:39]
	v_mfma_f32_16x16x32_bf16 v[32:35], v[180:183], v[196:199], v[32:35]
	v_mfma_f32_16x16x32_bf16 v[20:23], v[172:175], v[204:207], v[20:23]
	v_mfma_f32_16x16x32_bf16 v[16:19], v[180:183], v[204:207], v[16:19]
	v_mfma_f32_16x16x32_bf16 v[4:7], v[172:175], v[212:215], v[4:7]
	v_mfma_f32_16x16x32_bf16 v[0:3], v[180:183], v[212:215], v[0:3]
	s_setprio 0
	s_barrier
	s_add_i32 s50, s50, 2
	s_add_u32 s28, s28, 0x100
	s_addc_u32 s29, s29, 0
	s_add_u32 s48, s48, 0x100
	s_addc_u32 s49, s49, 0
	s_cmp_gt_u32 s50, 29
	s_cbranch_scc0 .LBB0_1865
	s_and_b64 vcc, exec, s[14:15]
	s_cbranch_vccz .LBB0_1868
	s_barrier

.LBB0_1949:
	v_add_u32_e32 v153, s95, v161
	ds_read_b128 v[156:159], v153
	ds_read_b128 v[164:167], v153 offset:1024
	ds_read_b128 v[168:171], v153 offset:2048
	ds_read_b128 v[172:175], v153 offset:3072
	v_add_u32_e32 v153, s33, v161
	ds_read_b128 v[176:179], v153
	ds_read_b128 v[180:183], v153 offset:1024
	ds_read_b128 v[184:187], v153 offset:2048
	ds_read_b128 v[188:191], v153 offset:3072
	s_add_u32 s30, s26, 0xfff80080
	s_addc_u32 s31, s27, -1
	s_and_b64 s[28:29], s[28:29], exec
	s_cselect_b32 s31, s21, s31
	s_cselect_b32 s30, s47, s30
	s_cselect_b32 s29, s19, s50
	s_cselect_b32 s28, s48, s49
	s_add_i32 m0, s35, 0xc000
	ds_read_b128 v[192:195], v163
	ds_read_b128 v[196:199], v163 offset:1024
	ds_read_b128 v[200:203], v163 offset:2048
	ds_read_b128 v[204:207], v163 offset:3072
	ds_read_b128 v[208:211], v163 offset:4096
	ds_read_b128 v[212:215], v163 offset:5120
	ds_read_b128 v[216:219], v163 offset:6144
	ds_read_b128 v[222:225], v163 offset:7168
	global_load_lds_dwordx4 v136, s[26:27]
	s_add_i32 m0, s35, 0xe000
	s_nop 0
	global_load_lds_dwordx4 v138, s[26:27]
	s_waitcnt vmcnt(8)
	s_waitcnt lgkmcnt(0)
	s_setprio 1
	s_waitcnt lgkmcnt(0)
	v_mfma_f32_16x16x32_bf16 v[124:127], v[156:159], v[192:195], v[124:127]
	v_mfma_f32_16x16x32_bf16 v[120:123], v[168:171], v[192:195], v[120:123]
	v_mfma_f32_16x16x32_bf16 v[124:127], v[164:167], v[196:199], v[124:127]
	v_mfma_f32_16x16x32_bf16 v[120:123], v[172:175], v[196:199], v[120:123]
	s_barrier
	v_mfma_f32_16x16x32_bf16 v[108:111], v[156:159], v[200:203], v[108:111]
	v_mfma_f32_16x16x32_bf16 v[104:107], v[168:171], v[200:203], v[104:107]
	v_mfma_f32_16x16x32_bf16 v[92:95], v[156:159], v[208:211], v[92:95]
	v_mfma_f32_16x16x32_bf16 v[88:91], v[168:171], v[208:211], v[88:91]
	v_mfma_f32_16x16x32_bf16 v[76:79], v[156:159], v[216:219], v[76:79]
	v_mfma_f32_16x16x32_bf16 v[72:75], v[168:171], v[216:219], v[72:75]
	v_mfma_f32_16x16x32_bf16 v[116:119], v[176:179], v[192:195], v[116:119]
	v_mfma_f32_16x16x32_bf16 v[112:115], v[184:187], v[192:195], v[112:115]
	v_mfma_f32_16x16x32_bf16 v[100:103], v[176:179], v[200:203], v[100:103]
	v_mfma_f32_16x16x32_bf16 v[96:99], v[184:187], v[200:203], v[96:99]
	v_mfma_f32_16x16x32_bf16 v[84:87], v[176:179], v[208:211], v[84:87]
	v_mfma_f32_16x16x32_bf16 v[80:83], v[184:187], v[208:211], v[80:83]
	v_mfma_f32_16x16x32_bf16 v[68:71], v[176:179], v[216:219], v[68:71]
	v_mfma_f32_16x16x32_bf16 v[64:67], v[184:187], v[216:219], v[64:67]
	v_mfma_f32_16x16x32_bf16 v[108:111], v[164:167], v[204:207], v[108:111]
	v_mfma_f32_16x16x32_bf16 v[104:107], v[172:175], v[204:207], v[104:107]
	v_mfma_f32_16x16x32_bf16 v[92:95], v[164:167], v[212:215], v[92:95]
	v_mfma_f32_16x16x32_bf16 v[88:91], v[172:175], v[212:215], v[88:91]
	v_mfma_f32_16x16x32_bf16 v[76:79], v[164:167], v[222:225], v[76:79]
	v_mfma_f32_16x16x32_bf16 v[72:75], v[172:175], v[222:225], v[72:75]
	v_mfma_f32_16x16x32_bf16 v[116:119], v[180:183], v[196:199], v[116:119]
	v_mfma_f32_16x16x32_bf16 v[112:115], v[188:191], v[196:199], v[112:115]
	v_mfma_f32_16x16x32_bf16 v[100:103], v[180:183], v[204:207], v[100:103]
	v_mfma_f32_16x16x32_bf16 v[96:99], v[188:191], v[204:207], v[96:99]
	v_mfma_f32_16x16x32_bf16 v[84:87], v[180:183], v[212:215], v[84:87]
	v_mfma_f32_16x16x32_bf16 v[80:83], v[188:191], v[212:215], v[80:83]
	v_mfma_f32_16x16x32_bf16 v[68:71], v[180:183], v[222:225], v[68:71]
	v_mfma_f32_16x16x32_bf16 v[64:67], v[188:191], v[222:225], v[64:67]
	s_setprio 0
	s_barrier
	s_add_i32 s53, s95, s15
	v_lshl_add_u64 v[226:227], s[28:29], 0, v[132:133]
	s_mov_b32 m0, s53
	ds_read_b128 v[192:195], v163 offset:16384
	ds_read_b128 v[196:199], v163 offset:17408
	ds_read_b128 v[200:203], v163 offset:18432
	ds_read_b128 v[204:207], v163 offset:19456
	ds_read_b128 v[208:211], v163 offset:20480
	ds_read_b128 v[212:215], v163 offset:21504
	ds_read_b128 v[216:219], v163 offset:22528
	ds_read_b128 v[222:225], v163 offset:23552
	global_load_lds_dwordx4 v[226:227], off
	s_add_i32 m0, s53, 0x2000
	s_add_u32 s54, s28, 0x80000
	v_lshl_add_u64 v[228:229], s[28:29], 0, v[128:129]
	s_addc_u32 s55, s29, 0
	s_add_i32 s53, s33, s15
	global_load_lds_dwordx4 v[228:229], off
	s_mov_b32 m0, s53
	v_lshl_add_u64 v[232:233], s[30:31], 0, v[130:131]
	global_load_lds_dwordx4 v132, s[54:55]
	s_add_i32 m0, s53, 0x2000
	s_nop 0
	global_load_lds_dwordx4 v128, s[54:55]
	v_lshl_add_u64 v[230:231], s[30:31], 0, v[134:135]
	s_mov_b32 m0, s35
	s_nop 0
	global_load_lds_dwordx4 v[230:231], off
	s_mov_b32 m0, s36
	s_nop 0
	global_load_lds_dwordx4 v[232:233], off
	s_waitcnt vmcnt(8)
	s_waitcnt lgkmcnt(0)
	s_setprio 1
	s_waitcnt lgkmcnt(0)
	v_mfma_f32_16x16x32_bf16 v[60:63], v[156:159], v[192:195], v[60:63]
	v_mfma_f32_16x16x32_bf16 v[56:59], v[168:171], v[192:195], v[56:59]
	v_mfma_f32_16x16x32_bf16 v[60:63], v[164:167], v[196:199], v[60:63]
	v_mfma_f32_16x16x32_bf16 v[56:59], v[172:175], v[196:199], v[56:59]
	s_barrier
	v_mfma_f32_16x16x32_bf16 v[44:47], v[156:159], v[200:203], v[44:47]
	v_mfma_f32_16x16x32_bf16 v[40:43], v[168:171], v[200:203], v[40:43]
	v_mfma_f32_16x16x32_bf16 v[28:31], v[156:159], v[208:211], v[28:31]
	v_mfma_f32_16x16x32_bf16 v[24:27], v[168:171], v[208:211], v[24:27]
	v_mfma_f32_16x16x32_bf16 v[12:15], v[156:159], v[216:219], v[12:15]
	v_mfma_f32_16x16x32_bf16 v[8:11], v[168:171], v[216:219], v[8:11]
	v_mfma_f32_16x16x32_bf16 v[52:55], v[176:179], v[192:195], v[52:55]
	v_mfma_f32_16x16x32_bf16 v[48:51], v[184:187], v[192:195], v[48:51]
	v_mfma_f32_16x16x32_bf16 v[36:39], v[176:179], v[200:203], v[36:39]
	v_mfma_f32_16x16x32_bf16 v[32:35], v[184:187], v[200:203], v[32:35]
	v_mfma_f32_16x16x32_bf16 v[20:23], v[176:179], v[208:211], v[20:23]
	v_mfma_f32_16x16x32_bf16 v[16:19], v[184:187], v[208:211], v[16:19]
	v_mfma_f32_16x16x32_bf16 v[4:7], v[176:179], v[216:219], v[4:7]
	v_mfma_f32_16x16x32_bf16 v[0:3], v[184:187], v[216:219], v[0:3]
	v_mfma_f32_16x16x32_bf16 v[44:47], v[164:167], v[204:207], v[44:47]
	v_mfma_f32_16x16x32_bf16 v[40:43], v[172:175], v[204:207], v[40:43]
	v_mfma_f32_16x16x32_bf16 v[28:31], v[164:167], v[212:215], v[28:31]
	v_mfma_f32_16x16x32_bf16 v[24:27], v[172:175], v[212:215], v[24:27]
	v_mfma_f32_16x16x32_bf16 v[12:15], v[164:167], v[222:225], v[12:15]
	v_mfma_f32_16x16x32_bf16 v[8:11], v[172:175], v[222:225], v[8:11]
	v_mfma_f32_16x16x32_bf16 v[52:55], v[180:183], v[196:199], v[52:55]
	v_mfma_f32_16x16x32_bf16 v[48:51], v[188:191], v[196:199], v[48:51]
	v_mfma_f32_16x16x32_bf16 v[36:39], v[180:183], v[204:207], v[36:39]
	v_mfma_f32_16x16x32_bf16 v[32:35], v[188:191], v[204:207], v[32:35]
	v_mfma_f32_16x16x32_bf16 v[20:23], v[180:183], v[212:215], v[20:23]
	v_mfma_f32_16x16x32_bf16 v[16:19], v[188:191], v[212:215], v[16:19]
	v_mfma_f32_16x16x32_bf16 v[4:7], v[180:183], v[222:225], v[4:7]
	v_mfma_f32_16x16x32_bf16 v[0:3], v[188:191], v[222:225], v[0:3]
	s_setprio 0
	s_barrier
	v_add_u32_e32 v153, s3, v161
	ds_read_b128 v[156:159], v153
	ds_read_b128 v[164:167], v153 offset:1024
	ds_read_b128 v[168:171], v153 offset:2048
	ds_read_b128 v[172:175], v153 offset:3072
	v_add_u32_e32 v153, s58, v161
	ds_read_b128 v[176:179], v153
	ds_read_b128 v[180:183], v153 offset:1024
	ds_read_b128 v[184:187], v153 offset:2048
	ds_read_b128 v[188:191], v153 offset:3072
	s_add_u32 s30, s30, 0x80000
	s_addc_u32 s31, s31, 0
	s_mov_b32 m0, s37
	ds_read_b128 v[192:195], v163 offset:32768
	ds_read_b128 v[196:199], v163 offset:33792
	ds_read_b128 v[200:203], v163 offset:34816
	ds_read_b128 v[204:207], v163 offset:35840
	ds_read_b128 v[208:211], v163 offset:36864
	ds_read_b128 v[212:215], v163 offset:37888
	ds_read_b128 v[216:219], v163 offset:38912
	ds_read_b128 v[222:225], v163 offset:39936
	global_load_lds_dwordx4 v134, s[30:31]
	s_mov_b32 m0, s38
	s_nop 0
	global_load_lds_dwordx4 v130, s[30:31]
	s_waitcnt vmcnt(8)
	s_waitcnt lgkmcnt(0)
	s_setprio 1
	s_waitcnt lgkmcnt(0)
	v_mfma_f32_16x16x32_bf16 v[124:127], v[156:159], v[192:195], v[124:127]
	v_mfma_f32_16x16x32_bf16 v[120:123], v[168:171], v[192:195], v[120:123]
	v_mfma_f32_16x16x32_bf16 v[124:127], v[164:167], v[196:199], v[124:127]
	v_mfma_f32_16x16x32_bf16 v[120:123], v[172:175], v[196:199], v[120:123]
	s_barrier
	v_mfma_f32_16x16x32_bf16 v[108:111], v[156:159], v[200:203], v[108:111]
	v_mfma_f32_16x16x32_bf16 v[104:107], v[168:171], v[200:203], v[104:107]
	v_mfma_f32_16x16x32_bf16 v[92:95], v[156:159], v[208:211], v[92:95]
	v_mfma_f32_16x16x32_bf16 v[88:91], v[168:171], v[208:211], v[88:91]
	v_mfma_f32_16x16x32_bf16 v[76:79], v[156:159], v[216:219], v[76:79]
	v_mfma_f32_16x16x32_bf16 v[72:75], v[168:171], v[216:219], v[72:75]
	v_mfma_f32_16x16x32_bf16 v[116:119], v[176:179], v[192:195], v[116:119]
	v_mfma_f32_16x16x32_bf16 v[112:115], v[184:187], v[192:195], v[112:115]
	v_mfma_f32_16x16x32_bf16 v[100:103], v[176:179], v[200:203], v[100:103]
	v_mfma_f32_16x16x32_bf16 v[96:99], v[184:187], v[200:203], v[96:99]
	v_mfma_f32_16x16x32_bf16 v[84:87], v[176:179], v[208:211], v[84:87]
	v_mfma_f32_16x16x32_bf16 v[80:83], v[184:187], v[208:211], v[80:83]
	v_mfma_f32_16x16x32_bf16 v[68:71], v[176:179], v[216:219], v[68:71]
	v_mfma_f32_16x16x32_bf16 v[64:67], v[184:187], v[216:219], v[64:67]
	v_mfma_f32_16x16x32_bf16 v[108:111], v[164:167], v[204:207], v[108:111]
	v_mfma_f32_16x16x32_bf16 v[104:107], v[172:175], v[204:207], v[104:107]
	v_mfma_f32_16x16x32_bf16 v[92:95], v[164:167], v[212:215], v[92:95]
	v_mfma_f32_16x16x32_bf16 v[88:91], v[172:175], v[212:215], v[88:91]
	v_mfma_f32_16x16x32_bf16 v[76:79], v[164:167], v[222:225], v[76:79]
	v_mfma_f32_16x16x32_bf16 v[72:75], v[172:175], v[222:225], v[72:75]
	v_mfma_f32_16x16x32_bf16 v[116:119], v[180:183], v[196:199], v[116:119]
	v_mfma_f32_16x16x32_bf16 v[112:115], v[188:191], v[196:199], v[112:115]
	v_mfma_f32_16x16x32_bf16 v[100:103], v[180:183], v[204:207], v[100:103]
	v_mfma_f32_16x16x32_bf16 v[96:99], v[188:191], v[204:207], v[96:99]
	v_mfma_f32_16x16x32_bf16 v[84:87], v[180:183], v[212:215], v[84:87]
	v_mfma_f32_16x16x32_bf16 v[80:83], v[188:191], v[212:215], v[80:83]
	v_mfma_f32_16x16x32_bf16 v[68:71], v[180:183], v[222:225], v[68:71]
	v_mfma_f32_16x16x32_bf16 v[64:67], v[188:191], v[222:225], v[64:67]
	s_setprio 0
	s_barrier
	s_add_i32 s30, s3, s15
	v_lshl_add_u64 v[226:227], v[226:227], 0, s[8:9]
	s_mov_b32 m0, s30
	ds_read_b128 v[192:195], v163 offset:49152
	ds_read_b128 v[196:199], v163 offset:50176
	ds_read_b128 v[200:203], v163 offset:51200
	ds_read_b128 v[204:207], v163 offset:52224
	ds_read_b128 v[208:211], v163 offset:53248
	ds_read_b128 v[212:215], v163 offset:54272
	ds_read_b128 v[216:219], v163 offset:55296
	ds_read_b128 v[222:225], v163 offset:56320
	global_load_lds_dwordx4 v[226:227], off
	s_add_i32 m0, s30, 0x2000
	s_add_u32 s28, s28, 0x80080
	v_lshl_add_u64 v[226:227], v[228:229], 0, s[8:9]
	s_addc_u32 s29, s29, 0
	s_add_i32 s30, s58, s15
	global_load_lds_dwordx4 v[226:227], off
	s_mov_b32 m0, s30
	s_nop 0
	global_load_lds_dwordx4 v132, s[28:29]
	s_add_i32 m0, s30, 0x2000
	s_nop 0
	global_load_lds_dwordx4 v128, s[28:29]
	v_lshl_add_u64 v[226:227], v[230:231], 0, s[8:9]
	s_mov_b32 m0, s40
	s_nop 0
	global_load_lds_dwordx4 v[226:227], off
	v_lshl_add_u64 v[226:227], v[232:233], 0, s[8:9]
	s_mov_b32 m0, s41
	s_nop 0
	global_load_lds_dwordx4 v[226:227], off
	s_waitcnt vmcnt(8)
	s_waitcnt lgkmcnt(0)
	s_setprio 1
	s_waitcnt lgkmcnt(0)
	v_mfma_f32_16x16x32_bf16 v[60:63], v[156:159], v[192:195], v[60:63]
	v_mfma_f32_16x16x32_bf16 v[56:59], v[168:171], v[192:195], v[56:59]
	v_mfma_f32_16x16x32_bf16 v[60:63], v[164:167], v[196:199], v[60:63]
	v_mfma_f32_16x16x32_bf16 v[56:59], v[172:175], v[196:199], v[56:59]
	s_barrier
	v_mfma_f32_16x16x32_bf16 v[44:47], v[156:159], v[200:203], v[44:47]
	v_mfma_f32_16x16x32_bf16 v[40:43], v[168:171], v[200:203], v[40:43]
	v_mfma_f32_16x16x32_bf16 v[28:31], v[156:159], v[208:211], v[28:31]
	v_mfma_f32_16x16x32_bf16 v[24:27], v[168:171], v[208:211], v[24:27]
	v_mfma_f32_16x16x32_bf16 v[12:15], v[156:159], v[216:219], v[12:15]
	v_mfma_f32_16x16x32_bf16 v[8:11], v[168:171], v[216:219], v[8:11]
	v_mfma_f32_16x16x32_bf16 v[52:55], v[176:179], v[192:195], v[52:55]
	v_mfma_f32_16x16x32_bf16 v[48:51], v[184:187], v[192:195], v[48:51]
	v_mfma_f32_16x16x32_bf16 v[36:39], v[176:179], v[200:203], v[36:39]
	v_mfma_f32_16x16x32_bf16 v[32:35], v[184:187], v[200:203], v[32:35]
	v_mfma_f32_16x16x32_bf16 v[20:23], v[176:179], v[208:211], v[20:23]
	v_mfma_f32_16x16x32_bf16 v[16:19], v[184:187], v[208:211], v[16:19]
	v_mfma_f32_16x16x32_bf16 v[4:7], v[176:179], v[216:219], v[4:7]
	v_mfma_f32_16x16x32_bf16 v[0:3], v[184:187], v[216:219], v[0:3]
	v_mfma_f32_16x16x32_bf16 v[44:47], v[164:167], v[204:207], v[44:47]
	v_mfma_f32_16x16x32_bf16 v[40:43], v[172:175], v[204:207], v[40:43]
	v_mfma_f32_16x16x32_bf16 v[28:31], v[164:167], v[212:215], v[28:31]
	v_mfma_f32_16x16x32_bf16 v[24:27], v[172:175], v[212:215], v[24:27]
	v_mfma_f32_16x16x32_bf16 v[12:15], v[164:167], v[222:225], v[12:15]
	v_mfma_f32_16x16x32_bf16 v[8:11], v[172:175], v[222:225], v[8:11]
	v_mfma_f32_16x16x32_bf16 v[52:55], v[180:183], v[196:199], v[52:55]
	v_mfma_f32_16x16x32_bf16 v[48:51], v[188:191], v[196:199], v[48:51]
	v_mfma_f32_16x16x32_bf16 v[36:39], v[180:183], v[204:207], v[36:39]
	v_mfma_f32_16x16x32_bf16 v[32:35], v[188:191], v[204:207], v[32:35]
	v_mfma_f32_16x16x32_bf16 v[20:23], v[180:183], v[212:215], v[20:23]
	v_mfma_f32_16x16x32_bf16 v[16:19], v[188:191], v[212:215], v[16:19]
	v_mfma_f32_16x16x32_bf16 v[4:7], v[180:183], v[222:225], v[4:7]
	v_mfma_f32_16x16x32_bf16 v[0:3], v[188:191], v[222:225], v[0:3]
	s_setprio 0
	s_barrier
	s_add_i32 s51, s51, 2
	s_add_u32 s26, s26, 0x100
	s_addc_u32 s27, s27, 0
	s_add_u32 s49, s49, 0x100
	s_addc_u32 s50, s50, 0
	s_cmp_gt_u32 s51, 29
	s_cbranch_scc1 .LBB0_1952

.LBB0_2044:
	ds_read_b128 v[144:147], v157
	ds_read_b128 v[148:151], v157 offset:1024
	ds_read_b128 v[162:165], v157 offset:2048
	ds_read_b128 v[166:169], v157 offset:3072
	ds_read_b128 v[170:173], v158
	ds_read_b128 v[174:177], v158 offset:1024
	ds_read_b128 v[178:181], v158 offset:2048
	ds_read_b128 v[182:185], v158 offset:3072
	s_add_u32 s4, s6, 0x100
	s_addc_u32 s5, s7, 0
	s_cmpk_eq_i32 s56, 0x54
	s_cselect_b32 s37, s29, s5
	s_cselect_b32 s36, s28, s4
	s_cselect_b32 s35, s31, s55
	s_cselect_b32 s34, s30, s54
	v_lshl_add_u64 v[152:153], s[6:7], 0, v[136:137]
	s_add_i32 m0, s40, 0xc000
	ds_read_b128 v[186:189], v159
	ds_read_b128 v[190:193], v159 offset:1024
	ds_read_b128 v[194:197], v159 offset:2048
	ds_read_b128 v[198:201], v159 offset:3072
	ds_read_b128 v[202:205], v159 offset:4096
	ds_read_b128 v[206:209], v159 offset:5120
	ds_read_b128 v[210:213], v159 offset:6144
	ds_read_b128 v[214:217], v159 offset:7168
	global_load_lds_dwordx4 v[152:153], off
	v_lshl_add_u64 v[152:153], s[6:7], 0, v[138:139]
	s_add_i32 m0, s40, 0xe000
	s_nop 0
	global_load_lds_dwordx4 v[152:153], off
	s_waitcnt vmcnt(8)
	s_waitcnt lgkmcnt(0)
	s_setprio 1
	s_waitcnt lgkmcnt(0)
	v_mfma_f32_16x16x32_bf16 v[124:127], v[144:147], v[186:189], v[124:127]
	v_mfma_f32_16x16x32_bf16 v[120:123], v[162:165], v[186:189], v[120:123]
	v_mfma_f32_16x16x32_bf16 v[124:127], v[148:151], v[190:193], v[124:127]
	v_mfma_f32_16x16x32_bf16 v[120:123], v[166:169], v[190:193], v[120:123]
	s_barrier
	v_mfma_f32_16x16x32_bf16 v[108:111], v[144:147], v[194:197], v[108:111]
	v_mfma_f32_16x16x32_bf16 v[104:107], v[162:165], v[194:197], v[104:107]
	v_mfma_f32_16x16x32_bf16 v[92:95], v[144:147], v[202:205], v[92:95]
	v_mfma_f32_16x16x32_bf16 v[88:91], v[162:165], v[202:205], v[88:91]
	v_mfma_f32_16x16x32_bf16 v[76:79], v[144:147], v[210:213], v[76:79]
	v_mfma_f32_16x16x32_bf16 v[72:75], v[162:165], v[210:213], v[72:75]
	v_mfma_f32_16x16x32_bf16 v[116:119], v[170:173], v[186:189], v[116:119]
	v_mfma_f32_16x16x32_bf16 v[112:115], v[178:181], v[186:189], v[112:115]
	v_mfma_f32_16x16x32_bf16 v[100:103], v[170:173], v[194:197], v[100:103]
	v_mfma_f32_16x16x32_bf16 v[96:99], v[178:181], v[194:197], v[96:99]
	v_mfma_f32_16x16x32_bf16 v[84:87], v[170:173], v[202:205], v[84:87]
	v_mfma_f32_16x16x32_bf16 v[80:83], v[178:181], v[202:205], v[80:83]
	v_mfma_f32_16x16x32_bf16 v[68:71], v[170:173], v[210:213], v[68:71]
	v_mfma_f32_16x16x32_bf16 v[64:67], v[178:181], v[210:213], v[64:67]
	v_mfma_f32_16x16x32_bf16 v[108:111], v[148:151], v[198:201], v[108:111]
	v_mfma_f32_16x16x32_bf16 v[104:107], v[166:169], v[198:201], v[104:107]
	v_mfma_f32_16x16x32_bf16 v[92:95], v[148:151], v[206:209], v[92:95]
	v_mfma_f32_16x16x32_bf16 v[88:91], v[166:169], v[206:209], v[88:91]
	v_mfma_f32_16x16x32_bf16 v[76:79], v[148:151], v[214:217], v[76:79]
	v_mfma_f32_16x16x32_bf16 v[72:75], v[166:169], v[214:217], v[72:75]
	v_mfma_f32_16x16x32_bf16 v[116:119], v[174:177], v[190:193], v[116:119]
	v_mfma_f32_16x16x32_bf16 v[112:115], v[182:185], v[190:193], v[112:115]
	v_mfma_f32_16x16x32_bf16 v[100:103], v[174:177], v[198:201], v[100:103]
	v_mfma_f32_16x16x32_bf16 v[96:99], v[182:185], v[198:201], v[96:99]
	v_mfma_f32_16x16x32_bf16 v[84:87], v[174:177], v[206:209], v[84:87]
	v_mfma_f32_16x16x32_bf16 v[80:83], v[182:185], v[206:209], v[80:83]
	v_mfma_f32_16x16x32_bf16 v[68:71], v[174:177], v[214:217], v[68:71]
	v_mfma_f32_16x16x32_bf16 v[64:67], v[182:185], v[214:217], v[64:67]
	s_setprio 0
	s_barrier
	s_add_i32 s6, s95, s39
	v_lshl_add_u64 v[152:153], s[34:35], 0, v[130:131]
	s_mov_b32 m0, s6
	ds_read_b128 v[186:189], v159 offset:16384
	ds_read_b128 v[190:193], v159 offset:17408
	ds_read_b128 v[194:197], v159 offset:18432
	ds_read_b128 v[198:201], v159 offset:19456
	ds_read_b128 v[202:205], v159 offset:20480
	ds_read_b128 v[206:209], v159 offset:21504
	ds_read_b128 v[210:213], v159 offset:22528
	ds_read_b128 v[214:217], v159 offset:23552
	global_load_lds_dwordx4 v[152:153], off
	s_add_i32 m0, s6, 0x2000
	s_add_u32 s6, s34, 0x160000
	v_lshl_add_u64 v[218:219], s[34:35], 0, v[134:135]
	s_addc_u32 s7, s35, 0
	s_add_i32 s57, s33, s39
	global_load_lds_dwordx4 v[218:219], off
	s_mov_b32 m0, s57
	v_lshl_add_u64 v[222:223], s[36:37], 0, v[132:133]
	global_load_lds_dwordx4 v130, s[6:7]
	s_add_i32 m0, s57, 0x2000
	s_nop 0
	global_load_lds_dwordx4 v134, s[6:7]
	v_lshl_add_u64 v[220:221], s[36:37], 0, v[128:129]
	s_mov_b32 m0, s40
	s_nop 0
	global_load_lds_dwordx4 v[220:221], off
	s_mov_b32 m0, s41
	s_nop 0
	global_load_lds_dwordx4 v[222:223], off
	s_waitcnt vmcnt(8)
	s_waitcnt lgkmcnt(0)
	s_setprio 1
	s_waitcnt lgkmcnt(0)
	v_mfma_f32_16x16x32_bf16 v[60:63], v[144:147], v[186:189], v[60:63]
	v_mfma_f32_16x16x32_bf16 v[56:59], v[162:165], v[186:189], v[56:59]
	v_mfma_f32_16x16x32_bf16 v[60:63], v[148:151], v[190:193], v[60:63]
	v_mfma_f32_16x16x32_bf16 v[56:59], v[166:169], v[190:193], v[56:59]
	s_barrier
	v_mfma_f32_16x16x32_bf16 v[44:47], v[144:147], v[194:197], v[44:47]
	v_mfma_f32_16x16x32_bf16 v[40:43], v[162:165], v[194:197], v[40:43]
	v_mfma_f32_16x16x32_bf16 v[28:31], v[144:147], v[202:205], v[28:31]
	v_mfma_f32_16x16x32_bf16 v[24:27], v[162:165], v[202:205], v[24:27]
	v_mfma_f32_16x16x32_bf16 v[12:15], v[144:147], v[210:213], v[12:15]
	v_mfma_f32_16x16x32_bf16 v[8:11], v[162:165], v[210:213], v[8:11]
	v_mfma_f32_16x16x32_bf16 v[52:55], v[170:173], v[186:189], v[52:55]
	v_mfma_f32_16x16x32_bf16 v[48:51], v[178:181], v[186:189], v[48:51]
	v_mfma_f32_16x16x32_bf16 v[36:39], v[170:173], v[194:197], v[36:39]
	v_mfma_f32_16x16x32_bf16 v[32:35], v[178:181], v[194:197], v[32:35]
	v_mfma_f32_16x16x32_bf16 v[20:23], v[170:173], v[202:205], v[20:23]
	v_mfma_f32_16x16x32_bf16 v[16:19], v[178:181], v[202:205], v[16:19]
	v_mfma_f32_16x16x32_bf16 v[4:7], v[170:173], v[210:213], v[4:7]
	v_mfma_f32_16x16x32_bf16 v[0:3], v[178:181], v[210:213], v[0:3]
	v_mfma_f32_16x16x32_bf16 v[44:47], v[148:151], v[198:201], v[44:47]
	v_mfma_f32_16x16x32_bf16 v[40:43], v[166:169], v[198:201], v[40:43]
	v_mfma_f32_16x16x32_bf16 v[28:31], v[148:151], v[206:209], v[28:31]
	v_mfma_f32_16x16x32_bf16 v[24:27], v[166:169], v[206:209], v[24:27]
	v_mfma_f32_16x16x32_bf16 v[12:15], v[148:151], v[214:217], v[12:15]
	v_mfma_f32_16x16x32_bf16 v[8:11], v[166:169], v[214:217], v[8:11]
	v_mfma_f32_16x16x32_bf16 v[52:55], v[174:177], v[190:193], v[52:55]
	v_mfma_f32_16x16x32_bf16 v[48:51], v[182:185], v[190:193], v[48:51]
	v_mfma_f32_16x16x32_bf16 v[36:39], v[174:177], v[198:201], v[36:39]
	v_mfma_f32_16x16x32_bf16 v[32:35], v[182:185], v[198:201], v[32:35]
	v_mfma_f32_16x16x32_bf16 v[20:23], v[174:177], v[206:209], v[20:23]
	v_mfma_f32_16x16x32_bf16 v[16:19], v[182:185], v[206:209], v[16:19]
	v_mfma_f32_16x16x32_bf16 v[4:7], v[174:177], v[214:217], v[4:7]
	v_mfma_f32_16x16x32_bf16 v[0:3], v[182:185], v[214:217], v[0:3]
	s_setprio 0
	s_barrier
	v_add_u32_e32 v161, s3, v155
	ds_read_b128 v[144:147], v161
	ds_read_b128 v[148:151], v161 offset:1024
	ds_read_b128 v[162:165], v161 offset:2048
	ds_read_b128 v[166:169], v161 offset:3072
	v_add_u32_e32 v161, s58, v155
	ds_read_b128 v[170:173], v161
	ds_read_b128 v[174:177], v161 offset:1024
	ds_read_b128 v[178:181], v161 offset:2048
	ds_read_b128 v[182:185], v161 offset:3072
	s_add_u32 s6, s36, 0x160000
	s_addc_u32 s7, s37, 0
	s_mov_b32 m0, s42
	ds_read_b128 v[186:189], v159 offset:32768
	ds_read_b128 v[190:193], v159 offset:33792
	ds_read_b128 v[194:197], v159 offset:34816
	ds_read_b128 v[198:201], v159 offset:35840
	ds_read_b128 v[202:205], v159 offset:36864
	ds_read_b128 v[206:209], v159 offset:37888
	ds_read_b128 v[210:213], v159 offset:38912
	ds_read_b128 v[214:217], v159 offset:39936
	global_load_lds_dwordx4 v128, s[6:7]
	s_mov_b32 m0, s43
	s_nop 0
	global_load_lds_dwordx4 v132, s[6:7]
	s_waitcnt vmcnt(8)
	s_waitcnt lgkmcnt(0)
	s_setprio 1
	s_waitcnt lgkmcnt(0)
	v_mfma_f32_16x16x32_bf16 v[124:127], v[144:147], v[186:189], v[124:127]
	v_mfma_f32_16x16x32_bf16 v[120:123], v[162:165], v[186:189], v[120:123]
	v_mfma_f32_16x16x32_bf16 v[124:127], v[148:151], v[190:193], v[124:127]
	v_mfma_f32_16x16x32_bf16 v[120:123], v[166:169], v[190:193], v[120:123]
	s_barrier
	v_mfma_f32_16x16x32_bf16 v[108:111], v[144:147], v[194:197], v[108:111]
	v_mfma_f32_16x16x32_bf16 v[104:107], v[162:165], v[194:197], v[104:107]
	v_mfma_f32_16x16x32_bf16 v[92:95], v[144:147], v[202:205], v[92:95]
	v_mfma_f32_16x16x32_bf16 v[88:91], v[162:165], v[202:205], v[88:91]
	v_mfma_f32_16x16x32_bf16 v[76:79], v[144:147], v[210:213], v[76:79]
	v_mfma_f32_16x16x32_bf16 v[72:75], v[162:165], v[210:213], v[72:75]
	v_mfma_f32_16x16x32_bf16 v[116:119], v[170:173], v[186:189], v[116:119]
	v_mfma_f32_16x16x32_bf16 v[112:115], v[178:181], v[186:189], v[112:115]
	v_mfma_f32_16x16x32_bf16 v[100:103], v[170:173], v[194:197], v[100:103]
	v_mfma_f32_16x16x32_bf16 v[96:99], v[178:181], v[194:197], v[96:99]
	v_mfma_f32_16x16x32_bf16 v[84:87], v[170:173], v[202:205], v[84:87]
	v_mfma_f32_16x16x32_bf16 v[80:83], v[178:181], v[202:205], v[80:83]
	v_mfma_f32_16x16x32_bf16 v[68:71], v[170:173], v[210:213], v[68:71]
	v_mfma_f32_16x16x32_bf16 v[64:67], v[178:181], v[210:213], v[64:67]
	v_mfma_f32_16x16x32_bf16 v[108:111], v[148:151], v[198:201], v[108:111]
	v_mfma_f32_16x16x32_bf16 v[104:107], v[166:169], v[198:201], v[104:107]
	v_mfma_f32_16x16x32_bf16 v[92:95], v[148:151], v[206:209], v[92:95]
	v_mfma_f32_16x16x32_bf16 v[88:91], v[166:169], v[206:209], v[88:91]
	v_mfma_f32_16x16x32_bf16 v[76:79], v[148:151], v[214:217], v[76:79]
	v_mfma_f32_16x16x32_bf16 v[72:75], v[166:169], v[214:217], v[72:75]
	v_mfma_f32_16x16x32_bf16 v[116:119], v[174:177], v[190:193], v[116:119]
	v_mfma_f32_16x16x32_bf16 v[112:115], v[182:185], v[190:193], v[112:115]
	v_mfma_f32_16x16x32_bf16 v[100:103], v[174:177], v[198:201], v[100:103]
	v_mfma_f32_16x16x32_bf16 v[96:99], v[182:185], v[198:201], v[96:99]
	v_mfma_f32_16x16x32_bf16 v[84:87], v[174:177], v[206:209], v[84:87]
	v_mfma_f32_16x16x32_bf16 v[80:83], v[182:185], v[206:209], v[80:83]
	v_mfma_f32_16x16x32_bf16 v[68:71], v[174:177], v[214:217], v[68:71]
	v_mfma_f32_16x16x32_bf16 v[64:67], v[182:185], v[214:217], v[64:67]
	s_setprio 0
	s_barrier
	s_add_i32 s6, s3, s39
	v_lshl_add_u64 v[152:153], v[152:153], 0, s[12:13]
	s_mov_b32 m0, s6
	ds_read_b128 v[186:189], v159 offset:49152
	ds_read_b128 v[190:193], v159 offset:50176
	ds_read_b128 v[194:197], v159 offset:51200
	ds_read_b128 v[198:201], v159 offset:52224
	ds_read_b128 v[202:205], v159 offset:53248
	ds_read_b128 v[206:209], v159 offset:54272
	ds_read_b128 v[210:213], v159 offset:55296
	ds_read_b128 v[214:217], v159 offset:56320
	global_load_lds_dwordx4 v[152:153], off
	s_add_i32 m0, s6, 0x2000
	s_add_u32 s6, s34, 0x160080
	v_lshl_add_u64 v[152:153], v[218:219], 0, s[12:13]
	s_addc_u32 s7, s35, 0
	s_add_i32 s34, s58, s39
	global_load_lds_dwordx4 v[152:153], off
	s_mov_b32 m0, s34
	s_nop 0
	global_load_lds_dwordx4 v130, s[6:7]
	s_add_i32 m0, s34, 0x2000
	s_nop 0
	global_load_lds_dwordx4 v134, s[6:7]
	v_lshl_add_u64 v[152:153], v[220:221], 0, s[12:13]
	s_mov_b32 m0, s45
	s_nop 0
	global_load_lds_dwordx4 v[152:153], off
	v_lshl_add_u64 v[152:153], v[222:223], 0, s[12:13]
	s_mov_b32 m0, s46
	s_nop 0
	global_load_lds_dwordx4 v[152:153], off
	s_waitcnt vmcnt(8)
	s_waitcnt lgkmcnt(0)
	s_setprio 1
	s_waitcnt lgkmcnt(0)
	v_mfma_f32_16x16x32_bf16 v[60:63], v[144:147], v[186:189], v[60:63]
	v_mfma_f32_16x16x32_bf16 v[56:59], v[162:165], v[186:189], v[56:59]
	v_mfma_f32_16x16x32_bf16 v[60:63], v[148:151], v[190:193], v[60:63]
	v_mfma_f32_16x16x32_bf16 v[56:59], v[166:169], v[190:193], v[56:59]
	s_barrier
	v_mfma_f32_16x16x32_bf16 v[44:47], v[144:147], v[194:197], v[44:47]
	v_mfma_f32_16x16x32_bf16 v[40:43], v[162:165], v[194:197], v[40:43]
	v_mfma_f32_16x16x32_bf16 v[28:31], v[144:147], v[202:205], v[28:31]
	v_mfma_f32_16x16x32_bf16 v[24:27], v[162:165], v[202:205], v[24:27]
	v_mfma_f32_16x16x32_bf16 v[12:15], v[144:147], v[210:213], v[12:15]
	v_mfma_f32_16x16x32_bf16 v[8:11], v[162:165], v[210:213], v[8:11]
	v_mfma_f32_16x16x32_bf16 v[52:55], v[170:173], v[186:189], v[52:55]
	v_mfma_f32_16x16x32_bf16 v[48:51], v[178:181], v[186:189], v[48:51]
	v_mfma_f32_16x16x32_bf16 v[36:39], v[170:173], v[194:197], v[36:39]
	v_mfma_f32_16x16x32_bf16 v[32:35], v[178:181], v[194:197], v[32:35]
	v_mfma_f32_16x16x32_bf16 v[20:23], v[170:173], v[202:205], v[20:23]
	v_mfma_f32_16x16x32_bf16 v[16:19], v[178:181], v[202:205], v[16:19]
	v_mfma_f32_16x16x32_bf16 v[4:7], v[170:173], v[210:213], v[4:7]
	v_mfma_f32_16x16x32_bf16 v[0:3], v[178:181], v[210:213], v[0:3]
	v_mfma_f32_16x16x32_bf16 v[44:47], v[148:151], v[198:201], v[44:47]
	v_mfma_f32_16x16x32_bf16 v[40:43], v[166:169], v[198:201], v[40:43]
	v_mfma_f32_16x16x32_bf16 v[28:31], v[148:151], v[206:209], v[28:31]
	v_mfma_f32_16x16x32_bf16 v[24:27], v[166:169], v[206:209], v[24:27]
	v_mfma_f32_16x16x32_bf16 v[12:15], v[148:151], v[214:217], v[12:15]
	v_mfma_f32_16x16x32_bf16 v[8:11], v[166:169], v[214:217], v[8:11]
	v_mfma_f32_16x16x32_bf16 v[52:55], v[174:177], v[190:193], v[52:55]
	v_mfma_f32_16x16x32_bf16 v[48:51], v[182:185], v[190:193], v[48:51]
	v_mfma_f32_16x16x32_bf16 v[36:39], v[174:177], v[198:201], v[36:39]
	v_mfma_f32_16x16x32_bf16 v[32:35], v[182:185], v[198:201], v[32:35]
	v_mfma_f32_16x16x32_bf16 v[20:23], v[174:177], v[206:209], v[20:23]
	v_mfma_f32_16x16x32_bf16 v[16:19], v[182:185], v[206:209], v[16:19]
	v_mfma_f32_16x16x32_bf16 v[4:7], v[174:177], v[214:217], v[4:7]
	v_mfma_f32_16x16x32_bf16 v[0:3], v[182:185], v[214:217], v[0:3]
	s_setprio 0
	s_barrier
	s_add_i32 s56, s56, 2
	s_add_u32 s54, s54, 0x100
	s_addc_u32 s55, s55, 0
	s_cmpk_gt_u32 s56, 0x55
	s_mov_b64 s[6:7], s[4:5]
	s_cbranch_scc0 .LBB0_2044
	s_and_b64 vcc, exec, s[14:15]
	s_cbranch_vccz .LBB0_2047
	s_barrier
